# attention M head compare + K address adds moved above the barrier; GEMM mid-segment setprio 0/1 pairs removed
# speedup vs baseline: 1.0019x; 1.0019x over previous
; #define PG8_LDA(dst, b, h) do { _Pragma("unroll") for (int m = 0; m < 4; ++m) _Pragma("unroll") for (int k = 0; k < 2; ++k) dst[m][k] = *(const LAS bf16x8*)(lds + PG8_SA(b, h) + aoff + m * 2048 + k * 1024); } while (0)
; #define PG8_LDB(dst, b, h) do { _Pragma("unroll") for (int n = 0; n < 2; ++n) _Pragma("unroll") for (int k = 0; k < 2; ++k) dst[n][k] = *(const LAS bf16x8*)(lds + PG8_SB(b, h) + boff + n * 2048 + k * 1024); } while (0)
; #define PG8_WAIT_V(n) asm volatile("s_waitcnt vmcnt(" #n ")" ::: "memory")
; #define PG8_WAIT_L(n) asm volatile("s_waitcnt lgkmcnt(" #n ")" ::: "memory")
; #define PG8_BAR __builtin_amdgcn_s_barrier()
; #define PG8_SCHED __builtin_amdgcn_sched_barrier(0)
; template <class Epi, class Addr, bool ALIGN_EPI = true, class Order = StaticOrder>
; __device__ __forceinline__ void gemm_phase(LAS unsigned char* lds, const Gemm g, const Order& S, const Epi& E, const int wid) {
;     ...
;         for (int t = 0; t < nt; t += 2) {
;             const bool last = (t == nt - 2);
;             const char* a1 = cA + (size_t)(t + 1) * kstep;
;             const char* a2 = last ? nA : cA + (size_t)(t + 2) * kstep; const char* b2 = last ? nB : cB + (size_t)(t + 2) * kstep;
;             const char* a3 = a2 + kstep; const char* b3 = b2 + kstep;
;             PG8_LDB(B0, 0, 0); PG8_LDB(B1, 0, 1); PG8_SCHED; PG8_LDA(At, 0, 0); PG8_STAGE(PG8_SA(1, 1), a1 + hstepA, voffA);
;             PG8_WAIT_V(8); PG8_WAIT_L(0); PG8_BAR; PG8_MMA(0, 0, At, B0); PG8_MMA(0, 1, At, B1); PG8_BAR; PG8_SCHED;
;             PG8_LDA(At, 0, 1); PG8_STAGE(PG8_SB(0, 0), b2, voffB); PG8_STAGE(PG8_SB(0, 1), b2 + hstepB, voffB); PG8_STAGE(PG8_SA(0, 0), a2, voffA);
;             PG8_WAIT_V(8); PG8_WAIT_L(0); PG8_BAR; PG8_MMA(1, 0, At, B0); PG8_MMA(1, 1, At, B1); PG8_BAR; PG8_SCHED;
;             PG8_LDB(B0, 1, 0); PG8_LDB(B1, 1, 1); PG8_SCHED; PG8_LDA(At, 1, 0); PG8_STAGE(PG8_SA(0, 1), a2 + hstepA, voffA);
;             PG8_WAIT_V(8); PG8_WAIT_L(0); PG8_BAR; PG8_MMA(0, 0, At, B0); PG8_MMA(0, 1, At, B1); PG8_BAR; PG8_SCHED;
;             PG8_LDA(At, 1, 1); PG8_STAGE(PG8_SB(1, 0), b3, voffB); PG8_STAGE(PG8_SB(1, 1), b3 + hstepB, voffB); PG8_STAGE(PG8_SA(1, 0), a3, voffA);
;             PG8_WAIT_V(8); PG8_WAIT_L(0); PG8_BAR; PG8_MMA(1, 0, At, B0); PG8_MMA(1, 1, At, B1); PG8_BAR; PG8_SCHED;
.LBB0_123:
	ds_read_b128 v[128:131], v169
	ds_read_b128 v[132:135], v169 offset:1024
	ds_read_b128 v[152:155], v169 offset:2048
	ds_read_b128 v[156:159], v169 offset:3072
	ds_read_b128 v[160:163], v170
	ds_read_b128 v[176:179], v170 offset:1024
	ds_read_b128 v[180:183], v170 offset:2048
	ds_read_b128 v[184:187], v170 offset:3072
	s_add_u32 s46, s8, 0x100
	s_addc_u32 s47, s9, 0
	s_cmp_eq_u32 s80, 60
	s_cselect_b32 s52, s27, s46
	s_cselect_b32 s53, s21, s47
	s_cselect_b32 s50, s39, s78
	s_cselect_b32 s51, s17, s79
	s_add_u32 s48, s52, 0x80
	s_addc_u32 s49, s53, 0
	ds_read_b128 v[188:191], v171
	ds_read_b128 v[192:195], v171 offset:1024
	ds_read_b128 v[196:199], v171 offset:2048
	ds_read_b128 v[200:203], v171 offset:3072
	ds_read_b128 v[204:207], v171 offset:4096
	ds_read_b128 v[208:211], v171 offset:5120
	ds_read_b128 v[212:215], v171 offset:6144
	ds_read_b128 v[216:219], v171 offset:7168
	s_add_u32 s8, s8, 0x100080
	s_addc_u32 s9, s9, 0
	s_mov_b32 s18, m0
	s_mov_b32 m0, s66
	s_nop 0
	global_load_lds_dwordx4 v164, s[8:9]
	s_mov_b32 m0, s67
	s_nop 0
	global_load_lds_dwordx4 v166, s[8:9]
	s_mov_b32 m0, s18
	s_waitcnt vmcnt(8)
	s_waitcnt lgkmcnt(0)
	s_barrier
	s_setprio 1
	s_waitcnt lgkmcnt(7)
	v_mfma_f32_16x16x32_bf16 v[124:127], v[128:131], v[188:191], v[124:127]
	v_mfma_f32_16x16x32_bf16 v[120:123], v[152:155], v[188:191], v[120:123]
	s_waitcnt lgkmcnt(5)
	v_mfma_f32_16x16x32_bf16 v[108:111], v[128:131], v[196:199], v[108:111]
	v_mfma_f32_16x16x32_bf16 v[104:107], v[152:155], v[196:199], v[104:107]
	s_waitcnt lgkmcnt(3)
	v_mfma_f32_16x16x32_bf16 v[92:95], v[128:131], v[204:207], v[92:95]
	v_mfma_f32_16x16x32_bf16 v[88:91], v[152:155], v[204:207], v[88:91]
	s_waitcnt lgkmcnt(1)
	v_mfma_f32_16x16x32_bf16 v[76:79], v[128:131], v[212:215], v[76:79]
	v_mfma_f32_16x16x32_bf16 v[72:75], v[152:155], v[212:215], v[72:75]
	v_mfma_f32_16x16x32_bf16 v[124:127], v[132:135], v[192:195], v[124:127]
	v_mfma_f32_16x16x32_bf16 v[120:123], v[156:159], v[192:195], v[120:123]
	v_mfma_f32_16x16x32_bf16 v[108:111], v[132:135], v[200:203], v[108:111]
	v_mfma_f32_16x16x32_bf16 v[104:107], v[156:159], v[200:203], v[104:107]
	v_mfma_f32_16x16x32_bf16 v[92:95], v[132:135], v[208:211], v[92:95]
	v_mfma_f32_16x16x32_bf16 v[88:91], v[156:159], v[208:211], v[88:91]
	s_waitcnt lgkmcnt(0)
	v_mfma_f32_16x16x32_bf16 v[76:79], v[132:135], v[216:219], v[76:79]
	v_mfma_f32_16x16x32_bf16 v[72:75], v[156:159], v[216:219], v[72:75]
	v_mfma_f32_16x16x32_bf16 v[116:119], v[160:163], v[188:191], v[116:119]
	v_mfma_f32_16x16x32_bf16 v[112:115], v[180:183], v[188:191], v[112:115]
	v_mfma_f32_16x16x32_bf16 v[100:103], v[160:163], v[196:199], v[100:103]
	v_mfma_f32_16x16x32_bf16 v[96:99], v[180:183], v[196:199], v[96:99]
	v_mfma_f32_16x16x32_bf16 v[84:87], v[160:163], v[204:207], v[84:87]
	v_mfma_f32_16x16x32_bf16 v[80:83], v[180:183], v[204:207], v[80:83]
	v_mfma_f32_16x16x32_bf16 v[68:71], v[160:163], v[212:215], v[68:71]
	v_mfma_f32_16x16x32_bf16 v[64:67], v[180:183], v[212:215], v[64:67]
	v_mfma_f32_16x16x32_bf16 v[116:119], v[176:179], v[192:195], v[116:119]
	v_mfma_f32_16x16x32_bf16 v[112:115], v[184:187], v[192:195], v[112:115]
	v_mfma_f32_16x16x32_bf16 v[100:103], v[176:179], v[200:203], v[100:103]
	v_mfma_f32_16x16x32_bf16 v[96:99], v[184:187], v[200:203], v[96:99]
	v_mfma_f32_16x16x32_bf16 v[84:87], v[176:179], v[208:211], v[84:87]
	v_mfma_f32_16x16x32_bf16 v[80:83], v[184:187], v[208:211], v[80:83]
	v_mfma_f32_16x16x32_bf16 v[68:71], v[176:179], v[216:219], v[68:71]
	v_mfma_f32_16x16x32_bf16 v[64:67], v[184:187], v[216:219], v[64:67]
	s_setprio 0
	s_barrier
	ds_read_b128 v[188:191], v171 offset:16384
	ds_read_b128 v[192:195], v171 offset:17408
	ds_read_b128 v[196:199], v171 offset:18432
	ds_read_b128 v[200:203], v171 offset:19456
	ds_read_b128 v[204:207], v171 offset:20480
	ds_read_b128 v[208:211], v171 offset:21504
	ds_read_b128 v[212:215], v171 offset:22528
	ds_read_b128 v[216:219], v171 offset:23552
	s_mov_b32 s8, m0
	s_mov_b32 m0, s43
	s_nop 0
	global_load_lds_dwordx4 v165, s[50:51]
	s_mov_b32 m0, s54
	s_nop 0
	global_load_lds_dwordx4 v167, s[50:51]
	s_mov_b32 m0, s8
	s_add_u32 s8, s50, 0x100000
	s_addc_u32 s9, s51, 0
	s_mov_b32 s18, m0
	s_mov_b32 m0, s55
	s_nop 0
	global_load_lds_dwordx4 v165, s[8:9]
	s_mov_b32 m0, s56
	s_nop 0
	global_load_lds_dwordx4 v167, s[8:9]
	s_mov_b32 m0, s18
	s_mov_b32 s8, m0
	s_mov_b32 m0, s41
	s_nop 0
	global_load_lds_dwordx4 v164, s[52:53]
	s_mov_b32 m0, s57
	s_nop 0
	global_load_lds_dwordx4 v166, s[52:53]
	s_mov_b32 m0, s8
	s_waitcnt vmcnt(8)
	s_waitcnt lgkmcnt(0)
	s_barrier
; #define PG8_LDA(dst, b, h) do { _Pragma("unroll") for (int m = 0; m < 4; ++m) _Pragma("unroll") for (int k = 0; k < 2; ++k) dst[m][k] = *(const LAS bf16x8*)(lds + PG8_SA(b, h) + aoff + m * 2048 + k * 1024); } while (0)
; #define PG8_LDB(dst, b, h) do { _Pragma("unroll") for (int n = 0; n < 2; ++n) _Pragma("unroll") for (int k = 0; k < 2; ++k) dst[n][k] = *(const LAS bf16x8*)(lds + PG8_SB(b, h) + boff + n * 2048 + k * 1024); } while (0)
; #define PG8_WAIT_V(n) asm volatile("s_waitcnt vmcnt(" #n ")" ::: "memory")
; #define PG8_WAIT_L(n) asm volatile("s_waitcnt lgkmcnt(" #n ")" ::: "memory")
; #define PG8_BAR __builtin_amdgcn_s_barrier()
; #define PG8_SCHED __builtin_amdgcn_sched_barrier(0)
; template <class Epi, class Addr, bool ALIGN_EPI = true, class Order = StaticOrder>
; __device__ __forceinline__ void gemm_phase(LAS unsigned char* lds, const Gemm g, const Order& S, const Epi& E, const int wid) {
;     ...
;         for (int t = 0; t < nt; t += 2) {
;             const bool last = (t == nt - 2);
;             const char* a1 = cA + (size_t)(t + 1) * kstep;
;             const char* a2 = last ? nA : cA + (size_t)(t + 2) * kstep; const char* b2 = last ? nB : cB + (size_t)(t + 2) * kstep;
;             const char* a3 = a2 + kstep; const char* b3 = b2 + kstep;
;             PG8_LDB(B0, 0, 0); PG8_LDB(B1, 0, 1); PG8_SCHED; PG8_LDA(At, 0, 0); PG8_STAGE(PG8_SA(1, 1), a1 + hstepA, voffA);
;             PG8_WAIT_V(8); PG8_WAIT_L(0); PG8_BAR; PG8_MMA(0, 0, At, B0); PG8_MMA(0, 1, At, B1); PG8_BAR; PG8_SCHED;
;             PG8_LDA(At, 0, 1); PG8_STAGE(PG8_SB(0, 0), b2, voffB); PG8_STAGE(PG8_SB(0, 1), b2 + hstepB, voffB); PG8_STAGE(PG8_SA(0, 0), a2, voffA);
;             PG8_WAIT_V(8); PG8_WAIT_L(0); PG8_BAR; PG8_MMA(1, 0, At, B0); PG8_MMA(1, 1, At, B1); PG8_BAR; PG8_SCHED;
;             PG8_LDB(B0, 1, 0); PG8_LDB(B1, 1, 1); PG8_SCHED; PG8_LDA(At, 1, 0); PG8_STAGE(PG8_SA(0, 1), a2 + hstepA, voffA);
;             PG8_WAIT_V(8); PG8_WAIT_L(0); PG8_BAR; PG8_MMA(0, 0, At, B0); PG8_MMA(0, 1, At, B1); PG8_BAR; PG8_SCHED;
;             PG8_LDA(At, 1, 1); PG8_STAGE(PG8_SB(1, 0), b3, voffB); PG8_STAGE(PG8_SB(1, 1), b3 + hstepB, voffB); PG8_STAGE(PG8_SA(1, 0), a3, voffA);
;             PG8_WAIT_V(8); PG8_WAIT_L(0); PG8_BAR; PG8_MMA(1, 0, At, B0); PG8_MMA(1, 1, At, B1); PG8_BAR; PG8_SCHED;
	s_setprio 1
	s_waitcnt lgkmcnt(7)
	v_mfma_f32_16x16x32_bf16 v[60:63], v[128:131], v[188:191], v[60:63]
	v_mfma_f32_16x16x32_bf16 v[56:59], v[152:155], v[188:191], v[56:59]
	s_waitcnt lgkmcnt(5)
	v_mfma_f32_16x16x32_bf16 v[44:47], v[128:131], v[196:199], v[44:47]
	v_mfma_f32_16x16x32_bf16 v[40:43], v[152:155], v[196:199], v[40:43]
	s_waitcnt lgkmcnt(3)
	v_mfma_f32_16x16x32_bf16 v[28:31], v[128:131], v[204:207], v[28:31]
	v_mfma_f32_16x16x32_bf16 v[24:27], v[152:155], v[204:207], v[24:27]
	s_waitcnt lgkmcnt(1)
	v_mfma_f32_16x16x32_bf16 v[12:15], v[128:131], v[212:215], v[12:15]
	v_mfma_f32_16x16x32_bf16 v[8:11], v[152:155], v[212:215], v[8:11]
	v_mfma_f32_16x16x32_bf16 v[60:63], v[132:135], v[192:195], v[60:63]
	v_mfma_f32_16x16x32_bf16 v[56:59], v[156:159], v[192:195], v[56:59]
	v_mfma_f32_16x16x32_bf16 v[44:47], v[132:135], v[200:203], v[44:47]
	v_mfma_f32_16x16x32_bf16 v[40:43], v[156:159], v[200:203], v[40:43]
	v_mfma_f32_16x16x32_bf16 v[28:31], v[132:135], v[208:211], v[28:31]
	v_mfma_f32_16x16x32_bf16 v[24:27], v[156:159], v[208:211], v[24:27]
	s_waitcnt lgkmcnt(0)
	v_mfma_f32_16x16x32_bf16 v[12:15], v[132:135], v[216:219], v[12:15]
	v_mfma_f32_16x16x32_bf16 v[8:11], v[156:159], v[216:219], v[8:11]
	v_mfma_f32_16x16x32_bf16 v[52:55], v[160:163], v[188:191], v[52:55]
	v_mfma_f32_16x16x32_bf16 v[48:51], v[180:183], v[188:191], v[48:51]
	v_mfma_f32_16x16x32_bf16 v[36:39], v[160:163], v[196:199], v[36:39]
	v_mfma_f32_16x16x32_bf16 v[32:35], v[180:183], v[196:199], v[32:35]
	v_mfma_f32_16x16x32_bf16 v[20:23], v[160:163], v[204:207], v[20:23]
	v_mfma_f32_16x16x32_bf16 v[16:19], v[180:183], v[204:207], v[16:19]
	v_mfma_f32_16x16x32_bf16 v[4:7], v[160:163], v[212:215], v[4:7]
	v_mfma_f32_16x16x32_bf16 v[0:3], v[180:183], v[212:215], v[0:3]
	v_mfma_f32_16x16x32_bf16 v[52:55], v[176:179], v[192:195], v[52:55]
	v_mfma_f32_16x16x32_bf16 v[48:51], v[184:187], v[192:195], v[48:51]
	v_mfma_f32_16x16x32_bf16 v[36:39], v[176:179], v[200:203], v[36:39]
	v_mfma_f32_16x16x32_bf16 v[32:35], v[184:187], v[200:203], v[32:35]
	v_mfma_f32_16x16x32_bf16 v[20:23], v[176:179], v[208:211], v[20:23]
	v_mfma_f32_16x16x32_bf16 v[16:19], v[184:187], v[208:211], v[16:19]
	v_mfma_f32_16x16x32_bf16 v[4:7], v[176:179], v[216:219], v[4:7]
	v_mfma_f32_16x16x32_bf16 v[0:3], v[184:187], v[216:219], v[0:3]
	s_setprio 0
	s_barrier
	ds_read_b128 v[128:131], v172
	ds_read_b128 v[132:135], v172 offset:1024
	ds_read_b128 v[152:155], v172 offset:2048
	ds_read_b128 v[156:159], v172 offset:3072
	ds_read_b128 v[160:163], v173
	ds_read_b128 v[176:179], v173 offset:1024
	ds_read_b128 v[180:183], v173 offset:2048
	ds_read_b128 v[184:187], v173 offset:3072
	ds_read_b128 v[188:191], v171 offset:32768
	ds_read_b128 v[192:195], v171 offset:33792
	ds_read_b128 v[196:199], v171 offset:34816
	ds_read_b128 v[200:203], v171 offset:35840
	ds_read_b128 v[204:207], v171 offset:36864
	ds_read_b128 v[208:211], v171 offset:37888
	ds_read_b128 v[212:215], v171 offset:38912
	ds_read_b128 v[216:219], v171 offset:39936
	s_add_u32 s8, s52, 0x100000
	s_addc_u32 s9, s53, 0
	s_mov_b32 s18, m0
	s_mov_b32 m0, s58
	s_nop 0
	global_load_lds_dwordx4 v164, s[8:9]
	s_mov_b32 m0, s59
	s_nop 0
	global_load_lds_dwordx4 v166, s[8:9]
	s_mov_b32 m0, s18
	s_waitcnt vmcnt(8)
	s_waitcnt lgkmcnt(0)
	s_barrier
	s_setprio 1
	s_waitcnt lgkmcnt(7)
	v_mfma_f32_16x16x32_bf16 v[124:127], v[128:131], v[188:191], v[124:127]
	v_mfma_f32_16x16x32_bf16 v[120:123], v[152:155], v[188:191], v[120:123]
	s_waitcnt lgkmcnt(5)
	v_mfma_f32_16x16x32_bf16 v[108:111], v[128:131], v[196:199], v[108:111]
	v_mfma_f32_16x16x32_bf16 v[104:107], v[152:155], v[196:199], v[104:107]
	s_waitcnt lgkmcnt(3)
	v_mfma_f32_16x16x32_bf16 v[92:95], v[128:131], v[204:207], v[92:95]
	v_mfma_f32_16x16x32_bf16 v[88:91], v[152:155], v[204:207], v[88:91]
	s_waitcnt lgkmcnt(1)
	v_mfma_f32_16x16x32_bf16 v[76:79], v[128:131], v[212:215], v[76:79]
	v_mfma_f32_16x16x32_bf16 v[72:75], v[152:155], v[212:215], v[72:75]
	v_mfma_f32_16x16x32_bf16 v[124:127], v[132:135], v[192:195], v[124:127]
	v_mfma_f32_16x16x32_bf16 v[120:123], v[156:159], v[192:195], v[120:123]
	v_mfma_f32_16x16x32_bf16 v[108:111], v[132:135], v[200:203], v[108:111]
	v_mfma_f32_16x16x32_bf16 v[104:107], v[156:159], v[200:203], v[104:107]
	v_mfma_f32_16x16x32_bf16 v[92:95], v[132:135], v[208:211], v[92:95]
	v_mfma_f32_16x16x32_bf16 v[88:91], v[156:159], v[208:211], v[88:91]
	s_waitcnt lgkmcnt(0)
	v_mfma_f32_16x16x32_bf16 v[76:79], v[132:135], v[216:219], v[76:79]
	v_mfma_f32_16x16x32_bf16 v[72:75], v[156:159], v[216:219], v[72:75]
	v_mfma_f32_16x16x32_bf16 v[116:119], v[160:163], v[188:191], v[116:119]
	v_mfma_f32_16x16x32_bf16 v[112:115], v[180:183], v[188:191], v[112:115]
	v_mfma_f32_16x16x32_bf16 v[100:103], v[160:163], v[196:199], v[100:103]
	v_mfma_f32_16x16x32_bf16 v[96:99], v[180:183], v[196:199], v[96:99]
	v_mfma_f32_16x16x32_bf16 v[84:87], v[160:163], v[204:207], v[84:87]
	v_mfma_f32_16x16x32_bf16 v[80:83], v[180:183], v[204:207], v[80:83]
	v_mfma_f32_16x16x32_bf16 v[68:71], v[160:163], v[212:215], v[68:71]
	v_mfma_f32_16x16x32_bf16 v[64:67], v[180:183], v[212:215], v[64:67]
	v_mfma_f32_16x16x32_bf16 v[116:119], v[176:179], v[192:195], v[116:119]
	v_mfma_f32_16x16x32_bf16 v[112:115], v[184:187], v[192:195], v[112:115]
	v_mfma_f32_16x16x32_bf16 v[100:103], v[176:179], v[200:203], v[100:103]
	v_mfma_f32_16x16x32_bf16 v[96:99], v[184:187], v[200:203], v[96:99]
	v_mfma_f32_16x16x32_bf16 v[84:87], v[176:179], v[208:211], v[84:87]
	v_mfma_f32_16x16x32_bf16 v[80:83], v[184:187], v[208:211], v[80:83]
	v_mfma_f32_16x16x32_bf16 v[68:71], v[176:179], v[216:219], v[68:71]
	v_mfma_f32_16x16x32_bf16 v[64:67], v[184:187], v[216:219], v[64:67]
	s_setprio 0
	s_barrier
; #define PG8_LDA(dst, b, h) do { _Pragma("unroll") for (int m = 0; m < 4; ++m) _Pragma("unroll") for (int k = 0; k < 2; ++k) dst[m][k] = *(const LAS bf16x8*)(lds + PG8_SA(b, h) + aoff + m * 2048 + k * 1024); } while (0)
; #define PG8_LDB(dst, b, h) do { _Pragma("unroll") for (int n = 0; n < 2; ++n) _Pragma("unroll") for (int k = 0; k < 2; ++k) dst[n][k] = *(const LAS bf16x8*)(lds + PG8_SB(b, h) + boff + n * 2048 + k * 1024); } while (0)
; #define PG8_WAIT_V(n) asm volatile("s_waitcnt vmcnt(" #n ")" ::: "memory")
; #define PG8_WAIT_L(n) asm volatile("s_waitcnt lgkmcnt(" #n ")" ::: "memory")
; #define PG8_BAR __builtin_amdgcn_s_barrier()
; #define PG8_SCHED __builtin_amdgcn_sched_barrier(0)
; template <class Epi, class Addr, bool ALIGN_EPI = true, class Order = StaticOrder>
; __device__ __forceinline__ void gemm_phase(LAS unsigned char* lds, const Gemm g, const Order& S, const Epi& E, const int wid) {
;     ...
;         for (int t = 0; t < nt; t += 2) {
;             const bool last = (t == nt - 2);
;             const char* a1 = cA + (size_t)(t + 1) * kstep;
;             const char* a2 = last ? nA : cA + (size_t)(t + 2) * kstep; const char* b2 = last ? nB : cB + (size_t)(t + 2) * kstep;
;             const char* a3 = a2 + kstep; const char* b3 = b2 + kstep;
;             PG8_LDB(B0, 0, 0); PG8_LDB(B1, 0, 1); PG8_SCHED; PG8_LDA(At, 0, 0); PG8_STAGE(PG8_SA(1, 1), a1 + hstepA, voffA);
;             PG8_WAIT_V(8); PG8_WAIT_L(0); PG8_BAR; PG8_MMA(0, 0, At, B0); PG8_MMA(0, 1, At, B1); PG8_BAR; PG8_SCHED;
;             PG8_LDA(At, 0, 1); PG8_STAGE(PG8_SB(0, 0), b2, voffB); PG8_STAGE(PG8_SB(0, 1), b2 + hstepB, voffB); PG8_STAGE(PG8_SA(0, 0), a2, voffA);
;             PG8_WAIT_V(8); PG8_WAIT_L(0); PG8_BAR; PG8_MMA(1, 0, At, B0); PG8_MMA(1, 1, At, B1); PG8_BAR; PG8_SCHED;
;             PG8_LDB(B0, 1, 0); PG8_LDB(B1, 1, 1); PG8_SCHED; PG8_LDA(At, 1, 0); PG8_STAGE(PG8_SA(0, 1), a2 + hstepA, voffA);
;             PG8_WAIT_V(8); PG8_WAIT_L(0); PG8_BAR; PG8_MMA(0, 0, At, B0); PG8_MMA(0, 1, At, B1); PG8_BAR; PG8_SCHED;
;             PG8_LDA(At, 1, 1); PG8_STAGE(PG8_SB(1, 0), b3, voffB); PG8_STAGE(PG8_SB(1, 1), b3 + hstepB, voffB); PG8_STAGE(PG8_SA(1, 0), a3, voffA);
;             PG8_WAIT_V(8); PG8_WAIT_L(0); PG8_BAR; PG8_MMA(1, 0, At, B0); PG8_MMA(1, 1, At, B1); PG8_BAR; PG8_SCHED;
;         }
;         if constexpr (ALIGN_EPI) { if (wr == 0) PG8_BAR; }
	ds_read_b128 v[188:191], v171 offset:49152
	ds_read_b128 v[192:195], v171 offset:50176
	ds_read_b128 v[196:199], v171 offset:51200
	ds_read_b128 v[200:203], v171 offset:52224
	ds_read_b128 v[204:207], v171 offset:53248
	ds_read_b128 v[208:211], v171 offset:54272
	ds_read_b128 v[212:215], v171 offset:55296
	ds_read_b128 v[216:219], v171 offset:56320
	s_add_u32 s8, s50, 0x80
	s_addc_u32 s9, s51, 0
	s_mov_b32 s18, m0
	s_mov_b32 m0, s60
	s_nop 0
	global_load_lds_dwordx4 v165, s[8:9]
	s_mov_b32 m0, s61
	s_nop 0
	global_load_lds_dwordx4 v167, s[8:9]
	s_mov_b32 m0, s18
	s_add_u32 s8, s50, 0x100080
	s_addc_u32 s9, s51, 0
	s_mov_b32 s18, m0
	s_mov_b32 m0, s64
	s_nop 0
	global_load_lds_dwordx4 v165, s[8:9]
	s_mov_b32 m0, s65
	s_nop 0
	global_load_lds_dwordx4 v167, s[8:9]
	s_mov_b32 m0, s18
	s_mov_b32 s8, m0
	s_mov_b32 m0, s62
	s_nop 0
	global_load_lds_dwordx4 v164, s[48:49]
	s_mov_b32 m0, s63
	s_nop 0
	global_load_lds_dwordx4 v166, s[48:49]
	s_mov_b32 m0, s8
	s_waitcnt vmcnt(8)
	s_waitcnt lgkmcnt(0)
	s_barrier
	s_setprio 1
	s_waitcnt lgkmcnt(7)
	v_mfma_f32_16x16x32_bf16 v[60:63], v[128:131], v[188:191], v[60:63]
	v_mfma_f32_16x16x32_bf16 v[56:59], v[152:155], v[188:191], v[56:59]
	s_waitcnt lgkmcnt(5)
	v_mfma_f32_16x16x32_bf16 v[44:47], v[128:131], v[196:199], v[44:47]
	v_mfma_f32_16x16x32_bf16 v[40:43], v[152:155], v[196:199], v[40:43]
	s_waitcnt lgkmcnt(3)
	v_mfma_f32_16x16x32_bf16 v[28:31], v[128:131], v[204:207], v[28:31]
	v_mfma_f32_16x16x32_bf16 v[24:27], v[152:155], v[204:207], v[24:27]
	s_waitcnt lgkmcnt(1)
	v_mfma_f32_16x16x32_bf16 v[12:15], v[128:131], v[212:215], v[12:15]
	v_mfma_f32_16x16x32_bf16 v[8:11], v[152:155], v[212:215], v[8:11]
	v_mfma_f32_16x16x32_bf16 v[60:63], v[132:135], v[192:195], v[60:63]
	v_mfma_f32_16x16x32_bf16 v[56:59], v[156:159], v[192:195], v[56:59]
	v_mfma_f32_16x16x32_bf16 v[44:47], v[132:135], v[200:203], v[44:47]
	v_mfma_f32_16x16x32_bf16 v[40:43], v[156:159], v[200:203], v[40:43]
	v_mfma_f32_16x16x32_bf16 v[28:31], v[132:135], v[208:211], v[28:31]
	v_mfma_f32_16x16x32_bf16 v[24:27], v[156:159], v[208:211], v[24:27]
	s_waitcnt lgkmcnt(0)
	v_mfma_f32_16x16x32_bf16 v[12:15], v[132:135], v[216:219], v[12:15]
	v_mfma_f32_16x16x32_bf16 v[8:11], v[156:159], v[216:219], v[8:11]
	v_mfma_f32_16x16x32_bf16 v[52:55], v[160:163], v[188:191], v[52:55]
	v_mfma_f32_16x16x32_bf16 v[48:51], v[180:183], v[188:191], v[48:51]
	v_mfma_f32_16x16x32_bf16 v[36:39], v[160:163], v[196:199], v[36:39]
	v_mfma_f32_16x16x32_bf16 v[32:35], v[180:183], v[196:199], v[32:35]
	v_mfma_f32_16x16x32_bf16 v[20:23], v[160:163], v[204:207], v[20:23]
	v_mfma_f32_16x16x32_bf16 v[16:19], v[180:183], v[204:207], v[16:19]
	v_mfma_f32_16x16x32_bf16 v[4:7], v[160:163], v[212:215], v[4:7]
	v_mfma_f32_16x16x32_bf16 v[0:3], v[180:183], v[212:215], v[0:3]
	v_mfma_f32_16x16x32_bf16 v[52:55], v[176:179], v[192:195], v[52:55]
	v_mfma_f32_16x16x32_bf16 v[48:51], v[184:187], v[192:195], v[48:51]
	v_mfma_f32_16x16x32_bf16 v[36:39], v[176:179], v[200:203], v[36:39]
	v_mfma_f32_16x16x32_bf16 v[32:35], v[184:187], v[200:203], v[32:35]
	v_mfma_f32_16x16x32_bf16 v[20:23], v[176:179], v[208:211], v[20:23]
	v_mfma_f32_16x16x32_bf16 v[16:19], v[184:187], v[208:211], v[16:19]
	v_mfma_f32_16x16x32_bf16 v[4:7], v[176:179], v[216:219], v[4:7]
	v_mfma_f32_16x16x32_bf16 v[0:3], v[184:187], v[216:219], v[0:3]
	s_setprio 0
	s_barrier
	s_add_i32 s80, s80, 2
	s_add_u32 s78, s78, 0x100
	s_addc_u32 s79, s79, 0
	s_cmp_gt_u32 s80, 61
	s_mov_b64 s[8:9], s[46:47]
	s_cbranch_scc0 .LBB0_123
	s_and_b64 vcc, exec, s[10:11]
	s_cbranch_vccz .LBB0_126
	s_barrier

; #define PG8_LDA(dst, b, h) do { _Pragma("unroll") for (int m = 0; m < 4; ++m) _Pragma("unroll") for (int k = 0; k < 2; ++k) dst[m][k] = *(const LAS bf16x8*)(lds + PG8_SA(b, h) + aoff + m * 2048 + k * 1024); } while (0)
; #define PG8_LDB(dst, b, h) do { _Pragma("unroll") for (int n = 0; n < 2; ++n) _Pragma("unroll") for (int k = 0; k < 2; ++k) dst[n][k] = *(const LAS bf16x8*)(lds + PG8_SB(b, h) + boff + n * 2048 + k * 1024); } while (0)
; #define PG8_WAIT_V(n) asm volatile("s_waitcnt vmcnt(" #n ")" ::: "memory")
; #define PG8_BAR __builtin_amdgcn_s_barrier()
; template <class Epi, class Addr, bool ALIGN_EPI = true, class Order = StaticOrder>
; __device__ __forceinline__ void gemm_phase(LAS unsigned char* lds, const Gemm g, const Order& S, const Epi& E, const int wid) {
;     ...
;         const bool has_next = S.next(ui + 1, nxt);
;         const char* nA = has_next ? (const char*)g.A + Addr::offA(nxt, g) : cA; const char* nB = has_next ? (const char*)g.Bt + Addr::offB(nxt, g) : cB;
;         for (int t = 0; t < nt; t += 2) {
;             const bool last = (t == nt - 2);
;             const char* a1 = cA + (size_t)(t + 1) * kstep;
;             const char* a2 = last ? nA : cA + (size_t)(t + 2) * kstep; const char* b2 = last ? nB : cB + (size_t)(t + 2) * kstep;
;             const char* a3 = a2 + kstep; const char* b3 = b2 + kstep;
;             PG8_LDB(B0, 0, 0); PG8_LDB(B1, 0, 1); PG8_SCHED; PG8_LDA(At, 0, 0); PG8_STAGE(PG8_SA(1, 1), a1 + hstepA, voffA);
;             PG8_WAIT_V(8); PG8_WAIT_L(0); PG8_BAR; PG8_MMA(0, 0, At, B0); PG8_MMA(0, 1, At, B1); PG8_BAR; PG8_SCHED;
;             PG8_LDA(At, 0, 1); PG8_STAGE(PG8_SB(0, 0), b2, voffB); PG8_STAGE(PG8_SB(0, 1), b2 + hstepB, voffB); PG8_STAGE(PG8_SA(0, 0), a2, voffA);
;             PG8_WAIT_V(8); PG8_WAIT_L(0); PG8_BAR; PG8_MMA(1, 0, At, B0); PG8_MMA(1, 1, At, B1); PG8_BAR; PG8_SCHED;
;             PG8_LDB(B0, 1, 0); PG8_LDB(B1, 1, 1); PG8_SCHED; PG8_LDA(At, 1, 0); PG8_STAGE(PG8_SA(0, 1), a2 + hstepA, voffA);
;             PG8_WAIT_V(8); PG8_WAIT_L(0); PG8_BAR; PG8_MMA(0, 0, At, B0); PG8_MMA(0, 1, At, B1); PG8_BAR; PG8_SCHED;
;             PG8_LDA(At, 1, 1); PG8_STAGE(PG8_SB(1, 0), b3, voffB); PG8_STAGE(PG8_SB(1, 1), b3 + hstepB, voffB); PG8_STAGE(PG8_SA(1, 0), a3, voffA);
;             PG8_WAIT_V(8); PG8_WAIT_L(0); PG8_BAR; PG8_MMA(1, 0, At, B0); PG8_MMA(1, 1, At, B1); PG8_BAR; PG8_SCHED;
.LBB0_191:
	ds_read_b128 v[146:149], v140
	ds_read_b128 v[150:153], v140 offset:1024
	ds_read_b128 v[154:157], v140 offset:2048
	ds_read_b128 v[158:161], v140 offset:3072
	ds_read_b128 v[162:165], v141
	ds_read_b128 v[166:169], v141 offset:1024
	ds_read_b128 v[170:173], v141 offset:2048
	ds_read_b128 v[174:177], v141 offset:3072
	s_add_u32 s24, s22, 0x100
	s_addc_u32 s25, s23, 0
	s_cmp_eq_u32 s77, 60
	s_cselect_b32 s46, s17, s24
	s_cselect_b32 s47, s9, s25
	s_cselect_b32 s44, s74, s75
	s_cselect_b32 s45, s21, s76
	s_add_u32 s26, s46, 0x80
	s_addc_u32 s27, s47, 0
	ds_read_b128 v[178:181], v142
	ds_read_b128 v[182:185], v142 offset:1024
	ds_read_b128 v[186:189], v142 offset:2048
	ds_read_b128 v[190:193], v142 offset:3072
	ds_read_b128 v[194:197], v142 offset:4096
	ds_read_b128 v[198:201], v142 offset:5120
	ds_read_b128 v[202:205], v142 offset:6144
	ds_read_b128 v[206:209], v142 offset:7168
	s_add_u32 s18, s22, 0x100080
	s_addc_u32 s19, s23, 0
	s_mov_b32 s22, m0
	s_mov_b32 m0, s66
	s_nop 0
	global_load_lds_dwordx4 v136, s[18:19]
	s_mov_b32 m0, s67
	s_nop 0
	global_load_lds_dwordx4 v138, s[18:19]
	s_mov_b32 m0, s22
	s_waitcnt vmcnt(8)
	s_waitcnt lgkmcnt(0)
	s_barrier
	s_setprio 1
	s_waitcnt lgkmcnt(7)
	v_mfma_f32_16x16x32_bf16 v[124:127], v[146:149], v[178:181], v[124:127]
	v_mfma_f32_16x16x32_bf16 v[120:123], v[154:157], v[178:181], v[120:123]
	s_waitcnt lgkmcnt(5)
	v_mfma_f32_16x16x32_bf16 v[116:119], v[146:149], v[186:189], v[116:119]
	v_mfma_f32_16x16x32_bf16 v[108:111], v[154:157], v[186:189], v[108:111]
	s_waitcnt lgkmcnt(3)
	v_mfma_f32_16x16x32_bf16 v[100:103], v[146:149], v[194:197], v[100:103]
	v_mfma_f32_16x16x32_bf16 v[92:95], v[154:157], v[194:197], v[92:95]
	s_waitcnt lgkmcnt(1)
	v_mfma_f32_16x16x32_bf16 v[84:87], v[146:149], v[202:205], v[84:87]
	v_mfma_f32_16x16x32_bf16 v[76:79], v[154:157], v[202:205], v[76:79]
	v_mfma_f32_16x16x32_bf16 v[124:127], v[150:153], v[182:185], v[124:127]
	v_mfma_f32_16x16x32_bf16 v[120:123], v[158:161], v[182:185], v[120:123]
	v_mfma_f32_16x16x32_bf16 v[116:119], v[150:153], v[190:193], v[116:119]
	v_mfma_f32_16x16x32_bf16 v[108:111], v[158:161], v[190:193], v[108:111]
	v_mfma_f32_16x16x32_bf16 v[100:103], v[150:153], v[198:201], v[100:103]
	v_mfma_f32_16x16x32_bf16 v[92:95], v[158:161], v[198:201], v[92:95]
	s_waitcnt lgkmcnt(0)
	v_mfma_f32_16x16x32_bf16 v[84:87], v[150:153], v[206:209], v[84:87]
	v_mfma_f32_16x16x32_bf16 v[76:79], v[158:161], v[206:209], v[76:79]
	v_mfma_f32_16x16x32_bf16 v[112:115], v[162:165], v[178:181], v[112:115]
	v_mfma_f32_16x16x32_bf16 v[104:107], v[170:173], v[178:181], v[104:107]
	v_mfma_f32_16x16x32_bf16 v[96:99], v[162:165], v[186:189], v[96:99]
	v_mfma_f32_16x16x32_bf16 v[88:91], v[170:173], v[186:189], v[88:91]
	v_mfma_f32_16x16x32_bf16 v[80:83], v[162:165], v[194:197], v[80:83]
	v_mfma_f32_16x16x32_bf16 v[72:75], v[170:173], v[194:197], v[72:75]
	v_mfma_f32_16x16x32_bf16 v[68:71], v[162:165], v[202:205], v[68:71]
	v_mfma_f32_16x16x32_bf16 v[64:67], v[170:173], v[202:205], v[64:67]
	v_mfma_f32_16x16x32_bf16 v[112:115], v[166:169], v[182:185], v[112:115]
	v_mfma_f32_16x16x32_bf16 v[104:107], v[174:177], v[182:185], v[104:107]
	v_mfma_f32_16x16x32_bf16 v[96:99], v[166:169], v[190:193], v[96:99]
	v_mfma_f32_16x16x32_bf16 v[88:91], v[174:177], v[190:193], v[88:91]
	v_mfma_f32_16x16x32_bf16 v[80:83], v[166:169], v[198:201], v[80:83]
	v_mfma_f32_16x16x32_bf16 v[72:75], v[174:177], v[198:201], v[72:75]
	v_mfma_f32_16x16x32_bf16 v[68:71], v[166:169], v[206:209], v[68:71]
	v_mfma_f32_16x16x32_bf16 v[64:67], v[174:177], v[206:209], v[64:67]
	s_setprio 0
	s_barrier
	ds_read_b128 v[178:181], v142 offset:16384
	ds_read_b128 v[182:185], v142 offset:17408
	ds_read_b128 v[186:189], v142 offset:18432
	ds_read_b128 v[190:193], v142 offset:19456
	ds_read_b128 v[194:197], v142 offset:20480
	ds_read_b128 v[198:201], v142 offset:21504
	ds_read_b128 v[202:205], v142 offset:22528
	ds_read_b128 v[206:209], v142 offset:23552
	s_mov_b32 s18, m0
	s_mov_b32 m0, s43
	s_nop 0
	global_load_lds_dwordx4 v137, s[44:45]
	s_mov_b32 m0, s54
	s_nop 0
	global_load_lds_dwordx4 v139, s[44:45]
	s_mov_b32 m0, s18
	s_add_u32 s18, s44, 0x2000000
	s_addc_u32 s19, s45, 0
	s_mov_b32 s22, m0
	s_mov_b32 m0, s55
	s_nop 0
	global_load_lds_dwordx4 v137, s[18:19]
	s_mov_b32 m0, s56
	s_nop 0
	global_load_lds_dwordx4 v139, s[18:19]
	s_mov_b32 m0, s22
	s_mov_b32 s18, m0
	s_mov_b32 m0, s41
	s_nop 0
	global_load_lds_dwordx4 v136, s[46:47]
	s_mov_b32 m0, s57
	s_nop 0
	global_load_lds_dwordx4 v138, s[46:47]
	s_mov_b32 m0, s18
	s_waitcnt vmcnt(8)
	s_waitcnt lgkmcnt(0)
	s_barrier
; #define PG8_LDA(dst, b, h) do { _Pragma("unroll") for (int m = 0; m < 4; ++m) _Pragma("unroll") for (int k = 0; k < 2; ++k) dst[m][k] = *(const LAS bf16x8*)(lds + PG8_SA(b, h) + aoff + m * 2048 + k * 1024); } while (0)
; #define PG8_LDB(dst, b, h) do { _Pragma("unroll") for (int n = 0; n < 2; ++n) _Pragma("unroll") for (int k = 0; k < 2; ++k) dst[n][k] = *(const LAS bf16x8*)(lds + PG8_SB(b, h) + boff + n * 2048 + k * 1024); } while (0)
; #define PG8_WAIT_V(n) asm volatile("s_waitcnt vmcnt(" #n ")" ::: "memory")
; #define PG8_WAIT_L(n) asm volatile("s_waitcnt lgkmcnt(" #n ")" ::: "memory")
; #define PG8_BAR __builtin_amdgcn_s_barrier()
; #define PG8_SCHED __builtin_amdgcn_sched_barrier(0)
; template <class Epi, class Addr, bool ALIGN_EPI = true, class Order = StaticOrder>
; __device__ __forceinline__ void gemm_phase(LAS unsigned char* lds, const Gemm g, const Order& S, const Epi& E, const int wid) {
;     ...
;         for (int t = 0; t < nt; t += 2) {
;             const bool last = (t == nt - 2);
;             const char* a1 = cA + (size_t)(t + 1) * kstep;
;             const char* a2 = last ? nA : cA + (size_t)(t + 2) * kstep; const char* b2 = last ? nB : cB + (size_t)(t + 2) * kstep;
;             const char* a3 = a2 + kstep; const char* b3 = b2 + kstep;
;             PG8_LDB(B0, 0, 0); PG8_LDB(B1, 0, 1); PG8_SCHED; PG8_LDA(At, 0, 0); PG8_STAGE(PG8_SA(1, 1), a1 + hstepA, voffA);
;             PG8_WAIT_V(8); PG8_WAIT_L(0); PG8_BAR; PG8_MMA(0, 0, At, B0); PG8_MMA(0, 1, At, B1); PG8_BAR; PG8_SCHED;
;             PG8_LDA(At, 0, 1); PG8_STAGE(PG8_SB(0, 0), b2, voffB); PG8_STAGE(PG8_SB(0, 1), b2 + hstepB, voffB); PG8_STAGE(PG8_SA(0, 0), a2, voffA);
;             PG8_WAIT_V(8); PG8_WAIT_L(0); PG8_BAR; PG8_MMA(1, 0, At, B0); PG8_MMA(1, 1, At, B1); PG8_BAR; PG8_SCHED;
;             PG8_LDB(B0, 1, 0); PG8_LDB(B1, 1, 1); PG8_SCHED; PG8_LDA(At, 1, 0); PG8_STAGE(PG8_SA(0, 1), a2 + hstepA, voffA);
;             PG8_WAIT_V(8); PG8_WAIT_L(0); PG8_BAR; PG8_MMA(0, 0, At, B0); PG8_MMA(0, 1, At, B1); PG8_BAR; PG8_SCHED;
;             PG8_LDA(At, 1, 1); PG8_STAGE(PG8_SB(1, 0), b3, voffB); PG8_STAGE(PG8_SB(1, 1), b3 + hstepB, voffB); PG8_STAGE(PG8_SA(1, 0), a3, voffA);
;             PG8_WAIT_V(8); PG8_WAIT_L(0); PG8_BAR; PG8_MMA(1, 0, At, B0); PG8_MMA(1, 1, At, B1); PG8_BAR; PG8_SCHED;
	s_setprio 1
	s_waitcnt lgkmcnt(7)
	v_mfma_f32_16x16x32_bf16 v[60:63], v[146:149], v[178:181], v[60:63]
	v_mfma_f32_16x16x32_bf16 v[56:59], v[154:157], v[178:181], v[56:59]
	s_waitcnt lgkmcnt(5)
	v_mfma_f32_16x16x32_bf16 v[52:55], v[146:149], v[186:189], v[52:55]
	v_mfma_f32_16x16x32_bf16 v[44:47], v[154:157], v[186:189], v[44:47]
	s_waitcnt lgkmcnt(3)
	v_mfma_f32_16x16x32_bf16 v[36:39], v[146:149], v[194:197], v[36:39]
	v_mfma_f32_16x16x32_bf16 v[28:31], v[154:157], v[194:197], v[28:31]
	s_waitcnt lgkmcnt(1)
	v_mfma_f32_16x16x32_bf16 v[20:23], v[146:149], v[202:205], v[20:23]
	v_mfma_f32_16x16x32_bf16 v[12:15], v[154:157], v[202:205], v[12:15]
	v_mfma_f32_16x16x32_bf16 v[60:63], v[150:153], v[182:185], v[60:63]
	v_mfma_f32_16x16x32_bf16 v[56:59], v[158:161], v[182:185], v[56:59]
	v_mfma_f32_16x16x32_bf16 v[52:55], v[150:153], v[190:193], v[52:55]
	v_mfma_f32_16x16x32_bf16 v[44:47], v[158:161], v[190:193], v[44:47]
	v_mfma_f32_16x16x32_bf16 v[36:39], v[150:153], v[198:201], v[36:39]
	v_mfma_f32_16x16x32_bf16 v[28:31], v[158:161], v[198:201], v[28:31]
	s_waitcnt lgkmcnt(0)
	v_mfma_f32_16x16x32_bf16 v[20:23], v[150:153], v[206:209], v[20:23]
	v_mfma_f32_16x16x32_bf16 v[12:15], v[158:161], v[206:209], v[12:15]
	v_mfma_f32_16x16x32_bf16 v[48:51], v[162:165], v[178:181], v[48:51]
	v_mfma_f32_16x16x32_bf16 v[40:43], v[170:173], v[178:181], v[40:43]
	v_mfma_f32_16x16x32_bf16 v[32:35], v[162:165], v[186:189], v[32:35]
	v_mfma_f32_16x16x32_bf16 v[24:27], v[170:173], v[186:189], v[24:27]
	v_mfma_f32_16x16x32_bf16 v[16:19], v[162:165], v[194:197], v[16:19]
	v_mfma_f32_16x16x32_bf16 v[8:11], v[170:173], v[194:197], v[8:11]
	v_mfma_f32_16x16x32_bf16 v[4:7], v[162:165], v[202:205], v[4:7]
	v_mfma_f32_16x16x32_bf16 v[0:3], v[170:173], v[202:205], v[0:3]
	v_mfma_f32_16x16x32_bf16 v[48:51], v[166:169], v[182:185], v[48:51]
	v_mfma_f32_16x16x32_bf16 v[40:43], v[174:177], v[182:185], v[40:43]
	v_mfma_f32_16x16x32_bf16 v[32:35], v[166:169], v[190:193], v[32:35]
	v_mfma_f32_16x16x32_bf16 v[24:27], v[174:177], v[190:193], v[24:27]
	v_mfma_f32_16x16x32_bf16 v[16:19], v[166:169], v[198:201], v[16:19]
	v_mfma_f32_16x16x32_bf16 v[8:11], v[174:177], v[198:201], v[8:11]
	v_mfma_f32_16x16x32_bf16 v[4:7], v[166:169], v[206:209], v[4:7]
	v_mfma_f32_16x16x32_bf16 v[0:3], v[174:177], v[206:209], v[0:3]
	s_setprio 0
	s_barrier
	ds_read_b128 v[146:149], v143
	ds_read_b128 v[150:153], v143 offset:1024
	ds_read_b128 v[154:157], v143 offset:2048
	ds_read_b128 v[158:161], v143 offset:3072
	ds_read_b128 v[162:165], v144
	ds_read_b128 v[166:169], v144 offset:1024
	ds_read_b128 v[170:173], v144 offset:2048
	ds_read_b128 v[174:177], v144 offset:3072
	ds_read_b128 v[178:181], v142 offset:32768
	ds_read_b128 v[182:185], v142 offset:33792
	ds_read_b128 v[186:189], v142 offset:34816
	ds_read_b128 v[190:193], v142 offset:35840
	ds_read_b128 v[194:197], v142 offset:36864
	ds_read_b128 v[198:201], v142 offset:37888
	ds_read_b128 v[202:205], v142 offset:38912
	ds_read_b128 v[206:209], v142 offset:39936
	s_add_u32 s18, s46, 0x100000
	s_addc_u32 s19, s47, 0
	s_mov_b32 s22, m0
	s_mov_b32 m0, s58
	s_nop 0
	global_load_lds_dwordx4 v136, s[18:19]
	s_mov_b32 m0, s59
	s_nop 0
	global_load_lds_dwordx4 v138, s[18:19]
	s_mov_b32 m0, s22
	s_waitcnt vmcnt(8)
	s_waitcnt lgkmcnt(0)
	s_barrier
	s_setprio 1
	s_waitcnt lgkmcnt(7)
	v_mfma_f32_16x16x32_bf16 v[124:127], v[146:149], v[178:181], v[124:127]
	v_mfma_f32_16x16x32_bf16 v[120:123], v[154:157], v[178:181], v[120:123]
	s_waitcnt lgkmcnt(5)
	v_mfma_f32_16x16x32_bf16 v[116:119], v[146:149], v[186:189], v[116:119]
	v_mfma_f32_16x16x32_bf16 v[108:111], v[154:157], v[186:189], v[108:111]
	s_waitcnt lgkmcnt(3)
	v_mfma_f32_16x16x32_bf16 v[100:103], v[146:149], v[194:197], v[100:103]
	v_mfma_f32_16x16x32_bf16 v[92:95], v[154:157], v[194:197], v[92:95]
	s_waitcnt lgkmcnt(1)
	v_mfma_f32_16x16x32_bf16 v[84:87], v[146:149], v[202:205], v[84:87]
	v_mfma_f32_16x16x32_bf16 v[76:79], v[154:157], v[202:205], v[76:79]
	v_mfma_f32_16x16x32_bf16 v[124:127], v[150:153], v[182:185], v[124:127]
	v_mfma_f32_16x16x32_bf16 v[120:123], v[158:161], v[182:185], v[120:123]
	v_mfma_f32_16x16x32_bf16 v[116:119], v[150:153], v[190:193], v[116:119]
	v_mfma_f32_16x16x32_bf16 v[108:111], v[158:161], v[190:193], v[108:111]
	v_mfma_f32_16x16x32_bf16 v[100:103], v[150:153], v[198:201], v[100:103]
	v_mfma_f32_16x16x32_bf16 v[92:95], v[158:161], v[198:201], v[92:95]
	s_waitcnt lgkmcnt(0)
	v_mfma_f32_16x16x32_bf16 v[84:87], v[150:153], v[206:209], v[84:87]
	v_mfma_f32_16x16x32_bf16 v[76:79], v[158:161], v[206:209], v[76:79]
	v_mfma_f32_16x16x32_bf16 v[112:115], v[162:165], v[178:181], v[112:115]
	v_mfma_f32_16x16x32_bf16 v[104:107], v[170:173], v[178:181], v[104:107]
	v_mfma_f32_16x16x32_bf16 v[96:99], v[162:165], v[186:189], v[96:99]
	v_mfma_f32_16x16x32_bf16 v[88:91], v[170:173], v[186:189], v[88:91]
	v_mfma_f32_16x16x32_bf16 v[80:83], v[162:165], v[194:197], v[80:83]
	v_mfma_f32_16x16x32_bf16 v[72:75], v[170:173], v[194:197], v[72:75]
	v_mfma_f32_16x16x32_bf16 v[68:71], v[162:165], v[202:205], v[68:71]
	v_mfma_f32_16x16x32_bf16 v[64:67], v[170:173], v[202:205], v[64:67]
	v_mfma_f32_16x16x32_bf16 v[112:115], v[166:169], v[182:185], v[112:115]
	v_mfma_f32_16x16x32_bf16 v[104:107], v[174:177], v[182:185], v[104:107]
	v_mfma_f32_16x16x32_bf16 v[96:99], v[166:169], v[190:193], v[96:99]
	v_mfma_f32_16x16x32_bf16 v[88:91], v[174:177], v[190:193], v[88:91]
	v_mfma_f32_16x16x32_bf16 v[80:83], v[166:169], v[198:201], v[80:83]
	v_mfma_f32_16x16x32_bf16 v[72:75], v[174:177], v[198:201], v[72:75]
	v_mfma_f32_16x16x32_bf16 v[68:71], v[166:169], v[206:209], v[68:71]
	v_mfma_f32_16x16x32_bf16 v[64:67], v[174:177], v[206:209], v[64:67]
	s_setprio 0
	s_barrier
; #define PG8_LDA(dst, b, h) do { _Pragma("unroll") for (int m = 0; m < 4; ++m) _Pragma("unroll") for (int k = 0; k < 2; ++k) dst[m][k] = *(const LAS bf16x8*)(lds + PG8_SA(b, h) + aoff + m * 2048 + k * 1024); } while (0)
; #define PG8_LDB(dst, b, h) do { _Pragma("unroll") for (int n = 0; n < 2; ++n) _Pragma("unroll") for (int k = 0; k < 2; ++k) dst[n][k] = *(const LAS bf16x8*)(lds + PG8_SB(b, h) + boff + n * 2048 + k * 1024); } while (0)
; #define PG8_WAIT_V(n) asm volatile("s_waitcnt vmcnt(" #n ")" ::: "memory")
; #define PG8_WAIT_L(n) asm volatile("s_waitcnt lgkmcnt(" #n ")" ::: "memory")
; #define PG8_BAR __builtin_amdgcn_s_barrier()
; #define PG8_SCHED __builtin_amdgcn_sched_barrier(0)
; template <class Epi, class Addr, bool ALIGN_EPI = true, class Order = StaticOrder>
; __device__ __forceinline__ void gemm_phase(LAS unsigned char* lds, const Gemm g, const Order& S, const Epi& E, const int wid) {
;     ...
;         for (int t = 0; t < nt; t += 2) {
;             const bool last = (t == nt - 2);
;             const char* a1 = cA + (size_t)(t + 1) * kstep;
;             const char* a2 = last ? nA : cA + (size_t)(t + 2) * kstep; const char* b2 = last ? nB : cB + (size_t)(t + 2) * kstep;
;             const char* a3 = a2 + kstep; const char* b3 = b2 + kstep;
;             PG8_LDB(B0, 0, 0); PG8_LDB(B1, 0, 1); PG8_SCHED; PG8_LDA(At, 0, 0); PG8_STAGE(PG8_SA(1, 1), a1 + hstepA, voffA);
;             PG8_WAIT_V(8); PG8_WAIT_L(0); PG8_BAR; PG8_MMA(0, 0, At, B0); PG8_MMA(0, 1, At, B1); PG8_BAR; PG8_SCHED;
;             PG8_LDA(At, 0, 1); PG8_STAGE(PG8_SB(0, 0), b2, voffB); PG8_STAGE(PG8_SB(0, 1), b2 + hstepB, voffB); PG8_STAGE(PG8_SA(0, 0), a2, voffA);
;             PG8_WAIT_V(8); PG8_WAIT_L(0); PG8_BAR; PG8_MMA(1, 0, At, B0); PG8_MMA(1, 1, At, B1); PG8_BAR; PG8_SCHED;
;             PG8_LDB(B0, 1, 0); PG8_LDB(B1, 1, 1); PG8_SCHED; PG8_LDA(At, 1, 0); PG8_STAGE(PG8_SA(0, 1), a2 + hstepA, voffA);
;             PG8_WAIT_V(8); PG8_WAIT_L(0); PG8_BAR; PG8_MMA(0, 0, At, B0); PG8_MMA(0, 1, At, B1); PG8_BAR; PG8_SCHED;
;             PG8_LDA(At, 1, 1); PG8_STAGE(PG8_SB(1, 0), b3, voffB); PG8_STAGE(PG8_SB(1, 1), b3 + hstepB, voffB); PG8_STAGE(PG8_SA(1, 0), a3, voffA);
;             PG8_WAIT_V(8); PG8_WAIT_L(0); PG8_BAR; PG8_MMA(1, 0, At, B0); PG8_MMA(1, 1, At, B1); PG8_BAR; PG8_SCHED;
;         }
;         if constexpr (ALIGN_EPI) { if (wr == 0) PG8_BAR; }
	ds_read_b128 v[178:181], v142 offset:49152
	ds_read_b128 v[182:185], v142 offset:50176
	ds_read_b128 v[186:189], v142 offset:51200
	ds_read_b128 v[190:193], v142 offset:52224
	ds_read_b128 v[194:197], v142 offset:53248
	ds_read_b128 v[198:201], v142 offset:54272
	ds_read_b128 v[202:205], v142 offset:55296
	ds_read_b128 v[206:209], v142 offset:56320
	s_add_u32 s18, s44, 0x80
	s_addc_u32 s19, s45, 0
	s_mov_b32 s22, m0
	s_mov_b32 m0, s60
	s_nop 0
	global_load_lds_dwordx4 v137, s[18:19]
	s_mov_b32 m0, s61
	s_nop 0
	global_load_lds_dwordx4 v139, s[18:19]
	s_mov_b32 m0, s22
	s_add_u32 s18, s44, 0x2000080
	s_addc_u32 s19, s45, 0
	s_mov_b32 s22, m0
	s_mov_b32 m0, s64
	s_nop 0
	global_load_lds_dwordx4 v137, s[18:19]
	s_mov_b32 m0, s65
	s_nop 0
	global_load_lds_dwordx4 v139, s[18:19]
	s_mov_b32 m0, s22
	s_mov_b32 s18, m0
	s_mov_b32 m0, s62
	s_nop 0
	global_load_lds_dwordx4 v136, s[26:27]
	s_mov_b32 m0, s63
	s_nop 0
	global_load_lds_dwordx4 v138, s[26:27]
	s_mov_b32 m0, s18
	s_waitcnt vmcnt(8)
	s_waitcnt lgkmcnt(0)
	s_barrier
	s_setprio 1
	s_waitcnt lgkmcnt(7)
	v_mfma_f32_16x16x32_bf16 v[60:63], v[146:149], v[178:181], v[60:63]
	v_mfma_f32_16x16x32_bf16 v[56:59], v[154:157], v[178:181], v[56:59]
	s_waitcnt lgkmcnt(5)
	v_mfma_f32_16x16x32_bf16 v[52:55], v[146:149], v[186:189], v[52:55]
	v_mfma_f32_16x16x32_bf16 v[44:47], v[154:157], v[186:189], v[44:47]
	s_waitcnt lgkmcnt(3)
	v_mfma_f32_16x16x32_bf16 v[36:39], v[146:149], v[194:197], v[36:39]
	v_mfma_f32_16x16x32_bf16 v[28:31], v[154:157], v[194:197], v[28:31]
	s_waitcnt lgkmcnt(1)
	v_mfma_f32_16x16x32_bf16 v[20:23], v[146:149], v[202:205], v[20:23]
	v_mfma_f32_16x16x32_bf16 v[12:15], v[154:157], v[202:205], v[12:15]
	v_mfma_f32_16x16x32_bf16 v[60:63], v[150:153], v[182:185], v[60:63]
	v_mfma_f32_16x16x32_bf16 v[56:59], v[158:161], v[182:185], v[56:59]
	v_mfma_f32_16x16x32_bf16 v[52:55], v[150:153], v[190:193], v[52:55]
	v_mfma_f32_16x16x32_bf16 v[44:47], v[158:161], v[190:193], v[44:47]
	v_mfma_f32_16x16x32_bf16 v[36:39], v[150:153], v[198:201], v[36:39]
	v_mfma_f32_16x16x32_bf16 v[28:31], v[158:161], v[198:201], v[28:31]
	s_waitcnt lgkmcnt(0)
	v_mfma_f32_16x16x32_bf16 v[20:23], v[150:153], v[206:209], v[20:23]
	v_mfma_f32_16x16x32_bf16 v[12:15], v[158:161], v[206:209], v[12:15]
	v_mfma_f32_16x16x32_bf16 v[48:51], v[162:165], v[178:181], v[48:51]
	v_mfma_f32_16x16x32_bf16 v[40:43], v[170:173], v[178:181], v[40:43]
	v_mfma_f32_16x16x32_bf16 v[32:35], v[162:165], v[186:189], v[32:35]
	v_mfma_f32_16x16x32_bf16 v[24:27], v[170:173], v[186:189], v[24:27]
	v_mfma_f32_16x16x32_bf16 v[16:19], v[162:165], v[194:197], v[16:19]
	v_mfma_f32_16x16x32_bf16 v[8:11], v[170:173], v[194:197], v[8:11]
	v_mfma_f32_16x16x32_bf16 v[4:7], v[162:165], v[202:205], v[4:7]
	v_mfma_f32_16x16x32_bf16 v[0:3], v[170:173], v[202:205], v[0:3]
	v_mfma_f32_16x16x32_bf16 v[48:51], v[166:169], v[182:185], v[48:51]
	v_mfma_f32_16x16x32_bf16 v[40:43], v[174:177], v[182:185], v[40:43]
	v_mfma_f32_16x16x32_bf16 v[32:35], v[166:169], v[190:193], v[32:35]
	v_mfma_f32_16x16x32_bf16 v[24:27], v[174:177], v[190:193], v[24:27]
	v_mfma_f32_16x16x32_bf16 v[16:19], v[166:169], v[198:201], v[16:19]
	v_mfma_f32_16x16x32_bf16 v[8:11], v[174:177], v[198:201], v[8:11]
	v_mfma_f32_16x16x32_bf16 v[4:7], v[166:169], v[206:209], v[4:7]
	v_mfma_f32_16x16x32_bf16 v[0:3], v[174:177], v[206:209], v[0:3]
	s_setprio 0
	s_barrier
	s_add_i32 s77, s77, 2
	s_add_u32 s75, s75, 0x100
	s_addc_u32 s76, s76, 0
	s_cmp_gt_u32 s77, 61
	s_mov_b64 s[22:23], s[24:25]
	s_cbranch_scc0 .LBB0_191
	s_and_b64 vcc, exec, s[10:11]
	s_cbranch_vccz .LBB0_194
	s_barrier

; #define PG8_LDA(dst, b, h) do { _Pragma("unroll") for (int m = 0; m < 4; ++m) _Pragma("unroll") for (int k = 0; k < 2; ++k) dst[m][k] = *(const LAS bf16x8*)(lds + PG8_SA(b, h) + aoff + m * 2048 + k * 1024); } while (0)
; #define PG8_LDB(dst, b, h) do { _Pragma("unroll") for (int n = 0; n < 2; ++n) _Pragma("unroll") for (int k = 0; k < 2; ++k) dst[n][k] = *(const LAS bf16x8*)(lds + PG8_SB(b, h) + boff + n * 2048 + k * 1024); } while (0)
; #define PG8_WAIT_V(n) asm volatile("s_waitcnt vmcnt(" #n ")" ::: "memory")
; #define PG8_BAR __builtin_amdgcn_s_barrier()
; template <class Epi, class Addr, bool ALIGN_EPI = true, class Order = StaticOrder>
; __device__ __forceinline__ void gemm_phase(LAS unsigned char* lds, const Gemm g, const Order& S, const Epi& E, const int wid) {
;     ...
;         const bool has_next = S.next(ui + 1, nxt);
;         const char* nA = has_next ? (const char*)g.A + Addr::offA(nxt, g) : cA; const char* nB = has_next ? (const char*)g.Bt + Addr::offB(nxt, g) : cB;
;         for (int t = 0; t < nt; t += 2) {
;             const bool last = (t == nt - 2);
;             const char* a1 = cA + (size_t)(t + 1) * kstep;
;             const char* a2 = last ? nA : cA + (size_t)(t + 2) * kstep; const char* b2 = last ? nB : cB + (size_t)(t + 2) * kstep;
;             const char* a3 = a2 + kstep; const char* b3 = b2 + kstep;
;             PG8_LDB(B0, 0, 0); PG8_LDB(B1, 0, 1); PG8_SCHED; PG8_LDA(At, 0, 0); PG8_STAGE(PG8_SA(1, 1), a1 + hstepA, voffA);
;             PG8_WAIT_V(8); PG8_WAIT_L(0); PG8_BAR; PG8_MMA(0, 0, At, B0); PG8_MMA(0, 1, At, B1); PG8_BAR; PG8_SCHED;
;             PG8_LDA(At, 0, 1); PG8_STAGE(PG8_SB(0, 0), b2, voffB); PG8_STAGE(PG8_SB(0, 1), b2 + hstepB, voffB); PG8_STAGE(PG8_SA(0, 0), a2, voffA);
;             PG8_WAIT_V(8); PG8_WAIT_L(0); PG8_BAR; PG8_MMA(1, 0, At, B0); PG8_MMA(1, 1, At, B1); PG8_BAR; PG8_SCHED;
;             PG8_LDB(B0, 1, 0); PG8_LDB(B1, 1, 1); PG8_SCHED; PG8_LDA(At, 1, 0); PG8_STAGE(PG8_SA(0, 1), a2 + hstepA, voffA);
;             PG8_WAIT_V(8); PG8_WAIT_L(0); PG8_BAR; PG8_MMA(0, 0, At, B0); PG8_MMA(0, 1, At, B1); PG8_BAR; PG8_SCHED;
;             PG8_LDA(At, 1, 1); PG8_STAGE(PG8_SB(1, 0), b3, voffB); PG8_STAGE(PG8_SB(1, 1), b3 + hstepB, voffB); PG8_STAGE(PG8_SA(1, 0), a3, voffA);
;             PG8_WAIT_V(8); PG8_WAIT_L(0); PG8_BAR; PG8_MMA(1, 0, At, B0); PG8_MMA(1, 1, At, B1); PG8_BAR; PG8_SCHED;
.LBB0_267:
	s_ashr_i32 s13, s12, 31
	s_lshl_b64 s[14:15], s[12:13], 17
	s_add_u32 s14, s29, s14
	s_addc_u32 s15, s31, s15
	s_and_b64 s[18:19], s[4:5], exec
	s_cselect_b32 s47, s15, s25
	s_cselect_b32 s46, s14, s24
	s_ashr_i32 s18, s75, 6
	s_ashr_i32 s19, s18, 31
	s_lshl_b32 s13, s75, 9
	s_and_b32 s13, s13, 0x7e00
	s_lshl_b64 s[18:19], s[18:19], 23
	ds_read_b128 v[0:3], v140
	ds_read_b128 v[4:7], v140 offset:1024
	ds_read_b128 v[8:11], v140 offset:2048
	ds_read_b128 v[12:15], v140 offset:3072
	ds_read_b128 v[16:19], v141
	ds_read_b128 v[20:23], v141 offset:1024
	ds_read_b128 v[24:27], v141 offset:2048
	ds_read_b128 v[28:31], v141 offset:3072
	s_add_u32 s17, s38, s18
	s_addc_u32 s18, s39, s19
	s_add_u32 s22, s17, s13
	s_addc_u32 s23, s18, 0
	s_and_b64 s[18:19], s[4:5], exec
	s_cselect_b32 s45, s23, s27
	s_cselect_b32 s44, s22, s26
	s_add_u32 s50, s24, 0x100
	s_addc_u32 s51, s25, 0
	s_add_u32 s18, s26, 0x100
	s_addc_u32 s19, s27, 0
	s_add_u32 s48, s24, 0x180
	s_addc_u32 s49, s25, 0
	ds_read_b128 v[32:35], v142
	ds_read_b128 v[36:39], v142 offset:1024
	ds_read_b128 v[40:43], v142 offset:2048
	ds_read_b128 v[44:47], v142 offset:3072
	ds_read_b128 v[48:51], v142 offset:4096
	ds_read_b128 v[52:55], v142 offset:5120
	ds_read_b128 v[56:59], v142 offset:6144
	ds_read_b128 v[60:63], v142 offset:7168
	s_add_u32 s76, s24, 0x10080
	s_addc_u32 s77, s25, 0
	s_mov_b32 s13, m0
	s_mov_b32 m0, s65
	s_nop 0
	global_load_lds_dwordx4 v136, s[76:77]
	s_mov_b32 m0, s66
	s_nop 0
	global_load_lds_dwordx4 v138, s[76:77]
	s_mov_b32 m0, s13
	s_waitcnt vmcnt(8)
	s_waitcnt lgkmcnt(0)
	s_barrier
	s_setprio 1
	s_waitcnt lgkmcnt(7)
	v_mfma_f32_16x16x32_bf16 v[64:67], v[0:3], v[32:35], 0
	v_mfma_f32_16x16x32_bf16 v[68:71], v[8:11], v[32:35], 0
	s_waitcnt lgkmcnt(5)
	v_mfma_f32_16x16x32_bf16 v[72:75], v[0:3], v[40:43], 0
	v_mfma_f32_16x16x32_bf16 v[76:79], v[8:11], v[40:43], 0
	s_waitcnt lgkmcnt(3)
	v_mfma_f32_16x16x32_bf16 v[80:83], v[0:3], v[48:51], 0
	v_mfma_f32_16x16x32_bf16 v[84:87], v[8:11], v[48:51], 0
	s_waitcnt lgkmcnt(1)
	v_mfma_f32_16x16x32_bf16 v[88:91], v[0:3], v[56:59], 0
	v_mfma_f32_16x16x32_bf16 v[92:95], v[8:11], v[56:59], 0
	v_mfma_f32_16x16x32_bf16 v[64:67], v[4:7], v[36:39], v[64:67]
	v_mfma_f32_16x16x32_bf16 v[68:71], v[12:15], v[36:39], v[68:71]
	v_mfma_f32_16x16x32_bf16 v[72:75], v[4:7], v[44:47], v[72:75]
	v_mfma_f32_16x16x32_bf16 v[76:79], v[12:15], v[44:47], v[76:79]
	v_mfma_f32_16x16x32_bf16 v[80:83], v[4:7], v[52:55], v[80:83]
	v_mfma_f32_16x16x32_bf16 v[84:87], v[12:15], v[52:55], v[84:87]
	s_waitcnt lgkmcnt(0)
	v_mfma_f32_16x16x32_bf16 v[88:91], v[4:7], v[60:63], v[88:91]
	v_mfma_f32_16x16x32_bf16 v[92:95], v[12:15], v[60:63], v[92:95]
	v_mfma_f32_16x16x32_bf16 v[96:99], v[16:19], v[32:35], 0
	v_mfma_f32_16x16x32_bf16 v[32:35], v[24:27], v[32:35], 0
	v_mfma_f32_16x16x32_bf16 v[96:99], v[20:23], v[36:39], v[96:99]
	v_mfma_f32_16x16x32_bf16 v[32:35], v[28:31], v[36:39], v[32:35]
	v_mfma_f32_16x16x32_bf16 v[36:39], v[16:19], v[40:43], 0
	v_mfma_f32_16x16x32_bf16 v[40:43], v[24:27], v[40:43], 0
	v_mfma_f32_16x16x32_bf16 v[36:39], v[20:23], v[44:47], v[36:39]
	v_mfma_f32_16x16x32_bf16 v[40:43], v[28:31], v[44:47], v[40:43]
	v_mfma_f32_16x16x32_bf16 v[44:47], v[16:19], v[48:51], 0
	v_mfma_f32_16x16x32_bf16 v[48:51], v[24:27], v[48:51], 0
	v_mfma_f32_16x16x32_bf16 v[44:47], v[20:23], v[52:55], v[44:47]
	v_mfma_f32_16x16x32_bf16 v[48:51], v[28:31], v[52:55], v[48:51]
	v_mfma_f32_16x16x32_bf16 v[52:55], v[16:19], v[56:59], 0
	v_mfma_f32_16x16x32_bf16 v[56:59], v[24:27], v[56:59], 0
	v_mfma_f32_16x16x32_bf16 v[52:55], v[20:23], v[60:63], v[52:55]
	v_mfma_f32_16x16x32_bf16 v[56:59], v[28:31], v[60:63], v[56:59]
	s_setprio 0
	s_barrier
	ds_read_b128 v[60:63], v142 offset:16384
	ds_read_b128 v[100:103], v142 offset:17408
	ds_read_b128 v[104:107], v142 offset:18432
	ds_read_b128 v[108:111], v142 offset:19456
	ds_read_b128 v[112:115], v142 offset:20480
	ds_read_b128 v[116:119], v142 offset:21504
	ds_read_b128 v[120:123], v142 offset:22528
	ds_read_b128 v[124:127], v142 offset:23552
	s_mov_b32 s13, m0
	s_mov_b32 m0, s41
	s_nop 0
	global_load_lds_dwordx4 v137, s[18:19]
	s_mov_b32 m0, s43
	s_nop 0
	global_load_lds_dwordx4 v139, s[18:19]
	s_mov_b32 m0, s13
	s_add_u32 s18, s26, 0x400100
	s_addc_u32 s19, s27, 0
	s_mov_b32 s13, m0
	s_mov_b32 m0, s52
	s_nop 0
	global_load_lds_dwordx4 v137, s[18:19]
	s_mov_b32 m0, s53
	s_nop 0
	global_load_lds_dwordx4 v139, s[18:19]
	s_mov_b32 m0, s13
	s_nop 0
	s_mov_b32 s13, m0
	s_mov_b32 m0, s40
	s_nop 0
	global_load_lds_dwordx4 v136, s[50:51]
	s_mov_b32 m0, s54
	s_nop 0
	global_load_lds_dwordx4 v138, s[50:51]
	s_mov_b32 m0, s13
	s_waitcnt vmcnt(8)
	s_waitcnt lgkmcnt(0)
	s_barrier
; #define PG8_LDA(dst, b, h) do { _Pragma("unroll") for (int m = 0; m < 4; ++m) _Pragma("unroll") for (int k = 0; k < 2; ++k) dst[m][k] = *(const LAS bf16x8*)(lds + PG8_SA(b, h) + aoff + m * 2048 + k * 1024); } while (0)
; #define PG8_LDB(dst, b, h) do { _Pragma("unroll") for (int n = 0; n < 2; ++n) _Pragma("unroll") for (int k = 0; k < 2; ++k) dst[n][k] = *(const LAS bf16x8*)(lds + PG8_SB(b, h) + boff + n * 2048 + k * 1024); } while (0)
; #define PG8_WAIT_V(n) asm volatile("s_waitcnt vmcnt(" #n ")" ::: "memory")
; #define PG8_WAIT_L(n) asm volatile("s_waitcnt lgkmcnt(" #n ")" ::: "memory")
; #define PG8_BAR __builtin_amdgcn_s_barrier()
; #define PG8_SCHED __builtin_amdgcn_sched_barrier(0)
; template <class Epi, class Addr, bool ALIGN_EPI = true, class Order = StaticOrder>
; __device__ __forceinline__ void gemm_phase(LAS unsigned char* lds, const Gemm g, const Order& S, const Epi& E, const int wid) {
;     ...
;         for (int t = 0; t < nt; t += 2) {
;             const bool last = (t == nt - 2);
;             const char* a1 = cA + (size_t)(t + 1) * kstep;
;             const char* a2 = last ? nA : cA + (size_t)(t + 2) * kstep; const char* b2 = last ? nB : cB + (size_t)(t + 2) * kstep;
;             const char* a3 = a2 + kstep; const char* b3 = b2 + kstep;
;             PG8_LDB(B0, 0, 0); PG8_LDB(B1, 0, 1); PG8_SCHED; PG8_LDA(At, 0, 0); PG8_STAGE(PG8_SA(1, 1), a1 + hstepA, voffA);
;             PG8_WAIT_V(8); PG8_WAIT_L(0); PG8_BAR; PG8_MMA(0, 0, At, B0); PG8_MMA(0, 1, At, B1); PG8_BAR; PG8_SCHED;
;             PG8_LDA(At, 0, 1); PG8_STAGE(PG8_SB(0, 0), b2, voffB); PG8_STAGE(PG8_SB(0, 1), b2 + hstepB, voffB); PG8_STAGE(PG8_SA(0, 0), a2, voffA);
;             PG8_WAIT_V(8); PG8_WAIT_L(0); PG8_BAR; PG8_MMA(1, 0, At, B0); PG8_MMA(1, 1, At, B1); PG8_BAR; PG8_SCHED;
;             PG8_LDB(B0, 1, 0); PG8_LDB(B1, 1, 1); PG8_SCHED; PG8_LDA(At, 1, 0); PG8_STAGE(PG8_SA(0, 1), a2 + hstepA, voffA);
;             PG8_WAIT_V(8); PG8_WAIT_L(0); PG8_BAR; PG8_MMA(0, 0, At, B0); PG8_MMA(0, 1, At, B1); PG8_BAR; PG8_SCHED;
;             PG8_LDA(At, 1, 1); PG8_STAGE(PG8_SB(1, 0), b3, voffB); PG8_STAGE(PG8_SB(1, 1), b3 + hstepB, voffB); PG8_STAGE(PG8_SA(1, 0), a3, voffA);
;             PG8_WAIT_V(8); PG8_WAIT_L(0); PG8_BAR; PG8_MMA(1, 0, At, B0); PG8_MMA(1, 1, At, B1); PG8_BAR; PG8_SCHED;
	s_setprio 1
	s_waitcnt lgkmcnt(7)
	v_mfma_f32_16x16x32_bf16 v[146:149], v[0:3], v[60:63], 0
	s_waitcnt lgkmcnt(5)
	v_mfma_f32_16x16x32_bf16 v[154:157], v[0:3], v[104:107], 0
	s_waitcnt lgkmcnt(3)
	v_mfma_f32_16x16x32_bf16 v[162:165], v[0:3], v[112:115], 0
	s_waitcnt lgkmcnt(1)
	v_mfma_f32_16x16x32_bf16 v[0:3], v[0:3], v[120:123], 0
	v_mfma_f32_16x16x32_bf16 v[146:149], v[4:7], v[100:103], v[146:149]
	v_mfma_f32_16x16x32_bf16 v[154:157], v[4:7], v[108:111], v[154:157]
	v_mfma_f32_16x16x32_bf16 v[162:165], v[4:7], v[116:119], v[162:165]
	s_waitcnt lgkmcnt(0)
	v_mfma_f32_16x16x32_bf16 v[0:3], v[4:7], v[124:127], v[0:3]
	v_mfma_f32_16x16x32_bf16 v[4:7], v[8:11], v[120:123], 0
	v_mfma_f32_16x16x32_bf16 v[150:153], v[8:11], v[60:63], 0
	v_mfma_f32_16x16x32_bf16 v[158:161], v[8:11], v[104:107], 0
	v_mfma_f32_16x16x32_bf16 v[166:169], v[8:11], v[112:115], 0
	v_mfma_f32_16x16x32_bf16 v[4:7], v[12:15], v[124:127], v[4:7]
	v_mfma_f32_16x16x32_bf16 v[150:153], v[12:15], v[100:103], v[150:153]
	v_mfma_f32_16x16x32_bf16 v[158:161], v[12:15], v[108:111], v[158:161]
	v_mfma_f32_16x16x32_bf16 v[166:169], v[12:15], v[116:119], v[166:169]
	v_mfma_f32_16x16x32_bf16 v[8:11], v[16:19], v[60:63], 0
	v_mfma_f32_16x16x32_bf16 v[12:15], v[24:27], v[60:63], 0
	v_mfma_f32_16x16x32_bf16 v[8:11], v[20:23], v[100:103], v[8:11]
	v_mfma_f32_16x16x32_bf16 v[12:15], v[28:31], v[100:103], v[12:15]
	v_mfma_f32_16x16x32_bf16 v[60:63], v[16:19], v[104:107], 0
	v_mfma_f32_16x16x32_bf16 v[100:103], v[24:27], v[104:107], 0
	v_mfma_f32_16x16x32_bf16 v[104:107], v[16:19], v[112:115], 0
	v_mfma_f32_16x16x32_bf16 v[16:19], v[16:19], v[120:123], 0
	v_mfma_f32_16x16x32_bf16 v[60:63], v[20:23], v[108:111], v[60:63]
	v_mfma_f32_16x16x32_bf16 v[100:103], v[28:31], v[108:111], v[100:103]
	v_mfma_f32_16x16x32_bf16 v[104:107], v[20:23], v[116:119], v[104:107]
	v_mfma_f32_16x16x32_bf16 v[108:111], v[24:27], v[112:115], 0
	v_mfma_f32_16x16x32_bf16 v[16:19], v[20:23], v[124:127], v[16:19]
	v_mfma_f32_16x16x32_bf16 v[20:23], v[24:27], v[120:123], 0
	v_mfma_f32_16x16x32_bf16 v[108:111], v[28:31], v[116:119], v[108:111]
	v_mfma_f32_16x16x32_bf16 v[20:23], v[28:31], v[124:127], v[20:23]
	s_setprio 0
	s_barrier
	ds_read_b128 v[24:27], v143
	ds_read_b128 v[28:31], v143 offset:1024
	ds_read_b128 v[112:115], v143 offset:2048
	ds_read_b128 v[116:119], v143 offset:3072
	ds_read_b128 v[120:123], v144
	ds_read_b128 v[124:127], v144 offset:1024
	ds_read_b128 v[170:173], v144 offset:2048
	ds_read_b128 v[174:177], v144 offset:3072
	ds_read_b128 v[178:181], v142 offset:32768
	ds_read_b128 v[182:185], v142 offset:33792
	ds_read_b128 v[186:189], v142 offset:34816
	ds_read_b128 v[190:193], v142 offset:35840
	ds_read_b128 v[194:197], v142 offset:36864
	ds_read_b128 v[198:201], v142 offset:37888
	ds_read_b128 v[202:205], v142 offset:38912
	ds_read_b128 v[206:209], v142 offset:39936
	s_add_u32 s18, s24, 0x10100
	s_addc_u32 s19, s25, 0
	s_mov_b32 s13, m0
	s_mov_b32 m0, s55
	s_nop 0
	global_load_lds_dwordx4 v136, s[18:19]
	s_mov_b32 m0, s56
	s_nop 0
	global_load_lds_dwordx4 v138, s[18:19]
	s_mov_b32 m0, s13
	s_waitcnt vmcnt(8)
	s_waitcnt lgkmcnt(0)
	s_barrier
	s_setprio 1
	s_waitcnt lgkmcnt(7)
	v_mfma_f32_16x16x32_bf16 v[64:67], v[24:27], v[178:181], v[64:67]
	v_mfma_f32_16x16x32_bf16 v[68:71], v[112:115], v[178:181], v[68:71]
	s_waitcnt lgkmcnt(5)
	v_mfma_f32_16x16x32_bf16 v[72:75], v[24:27], v[186:189], v[72:75]
	v_mfma_f32_16x16x32_bf16 v[76:79], v[112:115], v[186:189], v[76:79]
	s_waitcnt lgkmcnt(3)
	v_mfma_f32_16x16x32_bf16 v[80:83], v[24:27], v[194:197], v[80:83]
	v_mfma_f32_16x16x32_bf16 v[84:87], v[112:115], v[194:197], v[84:87]
	s_waitcnt lgkmcnt(1)
	v_mfma_f32_16x16x32_bf16 v[88:91], v[24:27], v[202:205], v[88:91]
	v_mfma_f32_16x16x32_bf16 v[92:95], v[112:115], v[202:205], v[92:95]
	v_mfma_f32_16x16x32_bf16 v[64:67], v[28:31], v[182:185], v[64:67]
	v_mfma_f32_16x16x32_bf16 v[68:71], v[116:119], v[182:185], v[68:71]
	v_mfma_f32_16x16x32_bf16 v[72:75], v[28:31], v[190:193], v[72:75]
	v_mfma_f32_16x16x32_bf16 v[76:79], v[116:119], v[190:193], v[76:79]
	v_mfma_f32_16x16x32_bf16 v[80:83], v[28:31], v[198:201], v[80:83]
	v_mfma_f32_16x16x32_bf16 v[84:87], v[116:119], v[198:201], v[84:87]
	s_waitcnt lgkmcnt(0)
	v_mfma_f32_16x16x32_bf16 v[88:91], v[28:31], v[206:209], v[88:91]
	v_mfma_f32_16x16x32_bf16 v[92:95], v[116:119], v[206:209], v[92:95]
	v_mfma_f32_16x16x32_bf16 v[96:99], v[120:123], v[178:181], v[96:99]
	v_mfma_f32_16x16x32_bf16 v[32:35], v[170:173], v[178:181], v[32:35]
	v_mfma_f32_16x16x32_bf16 v[36:39], v[120:123], v[186:189], v[36:39]
	v_mfma_f32_16x16x32_bf16 v[40:43], v[170:173], v[186:189], v[40:43]
	v_mfma_f32_16x16x32_bf16 v[44:47], v[120:123], v[194:197], v[44:47]
	v_mfma_f32_16x16x32_bf16 v[48:51], v[170:173], v[194:197], v[48:51]
	v_mfma_f32_16x16x32_bf16 v[52:55], v[120:123], v[202:205], v[52:55]
	v_mfma_f32_16x16x32_bf16 v[56:59], v[170:173], v[202:205], v[56:59]
	v_mfma_f32_16x16x32_bf16 v[96:99], v[124:127], v[182:185], v[96:99]
	v_mfma_f32_16x16x32_bf16 v[32:35], v[174:177], v[182:185], v[32:35]
	v_mfma_f32_16x16x32_bf16 v[36:39], v[124:127], v[190:193], v[36:39]
	v_mfma_f32_16x16x32_bf16 v[40:43], v[174:177], v[190:193], v[40:43]
	v_mfma_f32_16x16x32_bf16 v[44:47], v[124:127], v[198:201], v[44:47]
	v_mfma_f32_16x16x32_bf16 v[48:51], v[174:177], v[198:201], v[48:51]
	v_mfma_f32_16x16x32_bf16 v[52:55], v[124:127], v[206:209], v[52:55]
	v_mfma_f32_16x16x32_bf16 v[56:59], v[174:177], v[206:209], v[56:59]
	s_setprio 0
	s_barrier
; #define PG8_LDA(dst, b, h) do { _Pragma("unroll") for (int m = 0; m < 4; ++m) _Pragma("unroll") for (int k = 0; k < 2; ++k) dst[m][k] = *(const LAS bf16x8*)(lds + PG8_SA(b, h) + aoff + m * 2048 + k * 1024); } while (0)
; #define PG8_LDB(dst, b, h) do { _Pragma("unroll") for (int n = 0; n < 2; ++n) _Pragma("unroll") for (int k = 0; k < 2; ++k) dst[n][k] = *(const LAS bf16x8*)(lds + PG8_SB(b, h) + boff + n * 2048 + k * 1024); } while (0)
; #define PG8_WAIT_V(n) asm volatile("s_waitcnt vmcnt(" #n ")" ::: "memory")
; #define PG8_WAIT_L(n) asm volatile("s_waitcnt lgkmcnt(" #n ")" ::: "memory")
; #define PG8_BAR __builtin_amdgcn_s_barrier()
; #define PG8_SCHED __builtin_amdgcn_sched_barrier(0)
; template <class Epi, class Addr, bool ALIGN_EPI = true, class Order = StaticOrder>
; __device__ __forceinline__ void gemm_phase(LAS unsigned char* lds, const Gemm g, const Order& S, const Epi& E, const int wid) {
;     ...
;         for (int t = 0; t < nt; t += 2) {
;             const bool last = (t == nt - 2);
;             const char* a1 = cA + (size_t)(t + 1) * kstep;
;             const char* a2 = last ? nA : cA + (size_t)(t + 2) * kstep; const char* b2 = last ? nB : cB + (size_t)(t + 2) * kstep;
;             const char* a3 = a2 + kstep; const char* b3 = b2 + kstep;
;             PG8_LDB(B0, 0, 0); PG8_LDB(B1, 0, 1); PG8_SCHED; PG8_LDA(At, 0, 0); PG8_STAGE(PG8_SA(1, 1), a1 + hstepA, voffA);
;             PG8_WAIT_V(8); PG8_WAIT_L(0); PG8_BAR; PG8_MMA(0, 0, At, B0); PG8_MMA(0, 1, At, B1); PG8_BAR; PG8_SCHED;
;             PG8_LDA(At, 0, 1); PG8_STAGE(PG8_SB(0, 0), b2, voffB); PG8_STAGE(PG8_SB(0, 1), b2 + hstepB, voffB); PG8_STAGE(PG8_SA(0, 0), a2, voffA);
;             PG8_WAIT_V(8); PG8_WAIT_L(0); PG8_BAR; PG8_MMA(1, 0, At, B0); PG8_MMA(1, 1, At, B1); PG8_BAR; PG8_SCHED;
;             PG8_LDB(B0, 1, 0); PG8_LDB(B1, 1, 1); PG8_SCHED; PG8_LDA(At, 1, 0); PG8_STAGE(PG8_SA(0, 1), a2 + hstepA, voffA);
;             PG8_WAIT_V(8); PG8_WAIT_L(0); PG8_BAR; PG8_MMA(0, 0, At, B0); PG8_MMA(0, 1, At, B1); PG8_BAR; PG8_SCHED;
;             PG8_LDA(At, 1, 1); PG8_STAGE(PG8_SB(1, 0), b3, voffB); PG8_STAGE(PG8_SB(1, 1), b3 + hstepB, voffB); PG8_STAGE(PG8_SA(1, 0), a3, voffA);
;             PG8_WAIT_V(8); PG8_WAIT_L(0); PG8_BAR; PG8_MMA(1, 0, At, B0); PG8_MMA(1, 1, At, B1); PG8_BAR; PG8_SCHED;
	ds_read_b128 v[178:181], v142 offset:49152
	ds_read_b128 v[182:185], v142 offset:50176
	ds_read_b128 v[186:189], v142 offset:51200
	ds_read_b128 v[190:193], v142 offset:52224
	ds_read_b128 v[194:197], v142 offset:53248
	ds_read_b128 v[198:201], v142 offset:54272
	ds_read_b128 v[202:205], v142 offset:55296
	ds_read_b128 v[206:209], v142 offset:56320
	s_add_u32 s18, s26, 0x180
	s_addc_u32 s19, s27, 0
	s_mov_b32 s13, m0
	s_mov_b32 m0, s59
	s_nop 0
	global_load_lds_dwordx4 v137, s[18:19]
	s_mov_b32 m0, s60
	s_nop 0
	global_load_lds_dwordx4 v139, s[18:19]
	s_mov_b32 m0, s13
	s_add_u32 s18, s26, 0x400180
	s_addc_u32 s19, s27, 0
	s_mov_b32 s13, m0
	s_mov_b32 m0, s63
	s_nop 0
	global_load_lds_dwordx4 v137, s[18:19]
	s_mov_b32 m0, s64
	s_nop 0
	global_load_lds_dwordx4 v139, s[18:19]
	s_mov_b32 m0, s13
	s_nop 0
	s_mov_b32 s13, m0
	s_mov_b32 m0, s61
	s_nop 0
	global_load_lds_dwordx4 v136, s[48:49]
	s_mov_b32 m0, s62
	s_nop 0
	global_load_lds_dwordx4 v138, s[48:49]
	s_mov_b32 m0, s13
	s_waitcnt vmcnt(8)
	s_waitcnt lgkmcnt(0)
	s_barrier
	s_setprio 1
	s_waitcnt lgkmcnt(1)
	v_mfma_f32_16x16x32_bf16 v[0:3], v[24:27], v[202:205], v[0:3]
	v_mfma_f32_16x16x32_bf16 v[4:7], v[112:115], v[202:205], v[4:7]
	v_mfma_f32_16x16x32_bf16 v[146:149], v[24:27], v[178:181], v[146:149]
	v_mfma_f32_16x16x32_bf16 v[150:153], v[112:115], v[178:181], v[150:153]
	v_mfma_f32_16x16x32_bf16 v[154:157], v[24:27], v[186:189], v[154:157]
	v_mfma_f32_16x16x32_bf16 v[158:161], v[112:115], v[186:189], v[158:161]
	v_mfma_f32_16x16x32_bf16 v[162:165], v[24:27], v[194:197], v[162:165]
	v_mfma_f32_16x16x32_bf16 v[166:169], v[112:115], v[194:197], v[166:169]
	s_waitcnt lgkmcnt(0)
	v_mfma_f32_16x16x32_bf16 v[0:3], v[28:31], v[206:209], v[0:3]
	v_mfma_f32_16x16x32_bf16 v[4:7], v[116:119], v[206:209], v[4:7]
	v_mfma_f32_16x16x32_bf16 v[146:149], v[28:31], v[182:185], v[146:149]
	v_mfma_f32_16x16x32_bf16 v[150:153], v[116:119], v[182:185], v[150:153]
	v_mfma_f32_16x16x32_bf16 v[154:157], v[28:31], v[190:193], v[154:157]
	v_mfma_f32_16x16x32_bf16 v[158:161], v[116:119], v[190:193], v[158:161]
	v_mfma_f32_16x16x32_bf16 v[162:165], v[28:31], v[198:201], v[162:165]
	v_mfma_f32_16x16x32_bf16 v[166:169], v[116:119], v[198:201], v[166:169]
	v_mfma_f32_16x16x32_bf16 v[8:11], v[120:123], v[178:181], v[8:11]
	v_mfma_f32_16x16x32_bf16 v[12:15], v[170:173], v[178:181], v[12:15]
	v_mfma_f32_16x16x32_bf16 v[24:27], v[120:123], v[186:189], v[60:63]
	v_mfma_f32_16x16x32_bf16 v[28:31], v[170:173], v[186:189], v[100:103]
	v_mfma_f32_16x16x32_bf16 v[60:63], v[120:123], v[194:197], v[104:107]
	v_mfma_f32_16x16x32_bf16 v[100:103], v[170:173], v[194:197], v[108:111]
	v_mfma_f32_16x16x32_bf16 v[16:19], v[120:123], v[202:205], v[16:19]
	v_mfma_f32_16x16x32_bf16 v[20:23], v[170:173], v[202:205], v[20:23]
	v_mfma_f32_16x16x32_bf16 v[8:11], v[124:127], v[182:185], v[8:11]
	v_mfma_f32_16x16x32_bf16 v[12:15], v[174:177], v[182:185], v[12:15]
	v_mfma_f32_16x16x32_bf16 v[24:27], v[124:127], v[190:193], v[24:27]
	v_mfma_f32_16x16x32_bf16 v[28:31], v[174:177], v[190:193], v[28:31]
	v_mfma_f32_16x16x32_bf16 v[60:63], v[124:127], v[198:201], v[60:63]
	v_mfma_f32_16x16x32_bf16 v[100:103], v[174:177], v[198:201], v[100:103]
	v_mfma_f32_16x16x32_bf16 v[16:19], v[124:127], v[206:209], v[16:19]
	v_mfma_f32_16x16x32_bf16 v[20:23], v[174:177], v[206:209], v[20:23]
	s_setprio 0
	s_barrier
	ds_read_b128 v[104:107], v140
	ds_read_b128 v[108:111], v140 offset:1024
	ds_read_b128 v[112:115], v140 offset:2048
	ds_read_b128 v[116:119], v140 offset:3072
	ds_read_b128 v[120:123], v141
	ds_read_b128 v[124:127], v141 offset:1024
	ds_read_b128 v[170:173], v141 offset:2048
	ds_read_b128 v[174:177], v141 offset:3072
	s_add_u32 s26, s46, 0x80
	s_addc_u32 s27, s47, 0
	ds_read_b128 v[178:181], v142
	ds_read_b128 v[182:185], v142 offset:1024
	ds_read_b128 v[186:189], v142 offset:2048
	ds_read_b128 v[190:193], v142 offset:3072
	ds_read_b128 v[194:197], v142 offset:4096
	ds_read_b128 v[198:201], v142 offset:5120
	ds_read_b128 v[202:205], v142 offset:6144
	ds_read_b128 v[206:209], v142 offset:7168
	s_add_u32 s18, s24, 0x10180
	s_addc_u32 s19, s25, 0
	s_mov_b32 s13, m0
	s_mov_b32 m0, s65
	s_nop 0
	global_load_lds_dwordx4 v136, s[18:19]
	s_mov_b32 m0, s66
	s_nop 0
	global_load_lds_dwordx4 v138, s[18:19]
	s_mov_b32 m0, s13
	s_waitcnt vmcnt(8)
	s_waitcnt lgkmcnt(0)
	s_barrier
	s_setprio 1
	s_waitcnt lgkmcnt(7)
	v_mfma_f32_16x16x32_bf16 v[64:67], v[104:107], v[178:181], v[64:67]
	v_mfma_f32_16x16x32_bf16 v[68:71], v[112:115], v[178:181], v[68:71]
	s_waitcnt lgkmcnt(5)
	v_mfma_f32_16x16x32_bf16 v[72:75], v[104:107], v[186:189], v[72:75]
	v_mfma_f32_16x16x32_bf16 v[76:79], v[112:115], v[186:189], v[76:79]
	s_waitcnt lgkmcnt(3)
	v_mfma_f32_16x16x32_bf16 v[80:83], v[104:107], v[194:197], v[80:83]
	v_mfma_f32_16x16x32_bf16 v[84:87], v[112:115], v[194:197], v[84:87]
	s_waitcnt lgkmcnt(1)
	v_mfma_f32_16x16x32_bf16 v[88:91], v[104:107], v[202:205], v[88:91]
	v_mfma_f32_16x16x32_bf16 v[64:67], v[108:111], v[182:185], v[64:67]
	v_mfma_f32_16x16x32_bf16 v[68:71], v[116:119], v[182:185], v[68:71]
	v_mfma_f32_16x16x32_bf16 v[72:75], v[108:111], v[190:193], v[72:75]
	v_mfma_f32_16x16x32_bf16 v[76:79], v[116:119], v[190:193], v[76:79]
	v_mfma_f32_16x16x32_bf16 v[80:83], v[108:111], v[198:201], v[80:83]
	v_mfma_f32_16x16x32_bf16 v[84:87], v[116:119], v[198:201], v[84:87]
	s_waitcnt lgkmcnt(0)
	v_mfma_f32_16x16x32_bf16 v[88:91], v[108:111], v[206:209], v[88:91]
	v_mfma_f32_16x16x32_bf16 v[92:95], v[112:115], v[202:205], v[92:95]
	v_mfma_f32_16x16x32_bf16 v[210:213], v[116:119], v[206:209], v[92:95]
	v_mfma_f32_16x16x32_bf16 v[92:95], v[120:123], v[178:181], v[96:99]
	v_mfma_f32_16x16x32_bf16 v[32:35], v[170:173], v[178:181], v[32:35]
	v_mfma_f32_16x16x32_bf16 v[36:39], v[120:123], v[186:189], v[36:39]
	v_mfma_f32_16x16x32_bf16 v[40:43], v[170:173], v[186:189], v[40:43]
	v_mfma_f32_16x16x32_bf16 v[44:47], v[120:123], v[194:197], v[44:47]
	v_mfma_f32_16x16x32_bf16 v[48:51], v[170:173], v[194:197], v[48:51]
	v_mfma_f32_16x16x32_bf16 v[52:55], v[120:123], v[202:205], v[52:55]
	v_mfma_f32_16x16x32_bf16 v[96:99], v[124:127], v[182:185], v[92:95]
	v_mfma_f32_16x16x32_bf16 v[32:35], v[174:177], v[182:185], v[32:35]
	v_mfma_f32_16x16x32_bf16 v[36:39], v[124:127], v[190:193], v[36:39]
	v_mfma_f32_16x16x32_bf16 v[40:43], v[174:177], v[190:193], v[40:43]
	v_mfma_f32_16x16x32_bf16 v[44:47], v[124:127], v[198:201], v[44:47]
	v_mfma_f32_16x16x32_bf16 v[48:51], v[174:177], v[198:201], v[48:51]
	v_mfma_f32_16x16x32_bf16 v[178:181], v[124:127], v[206:209], v[52:55]
	v_mfma_f32_16x16x32_bf16 v[52:55], v[170:173], v[202:205], v[56:59]
	v_mfma_f32_16x16x32_bf16 v[182:185], v[174:177], v[206:209], v[52:55]
	s_setprio 0
	s_barrier
; #define PG8_LDA(dst, b, h) do { _Pragma("unroll") for (int m = 0; m < 4; ++m) _Pragma("unroll") for (int k = 0; k < 2; ++k) dst[m][k] = *(const LAS bf16x8*)(lds + PG8_SA(b, h) + aoff + m * 2048 + k * 1024); } while (0)
; #define PG8_LDB(dst, b, h) do { _Pragma("unroll") for (int n = 0; n < 2; ++n) _Pragma("unroll") for (int k = 0; k < 2; ++k) dst[n][k] = *(const LAS bf16x8*)(lds + PG8_SB(b, h) + boff + n * 2048 + k * 1024); } while (0)
; #define PG8_WAIT_V(n) asm volatile("s_waitcnt vmcnt(" #n ")" ::: "memory")
; #define PG8_WAIT_L(n) asm volatile("s_waitcnt lgkmcnt(" #n ")" ::: "memory")
; #define PG8_BAR __builtin_amdgcn_s_barrier()
; #define PG8_SCHED __builtin_amdgcn_sched_barrier(0)
; template <class Epi, class Addr, bool ALIGN_EPI = true, class Order = StaticOrder>
; __device__ __forceinline__ void gemm_phase(LAS unsigned char* lds, const Gemm g, const Order& S, const Epi& E, const int wid) {
;     ...
;         for (int t = 0; t < nt; t += 2) {
;             const bool last = (t == nt - 2);
;             const char* a1 = cA + (size_t)(t + 1) * kstep;
;             const char* a2 = last ? nA : cA + (size_t)(t + 2) * kstep; const char* b2 = last ? nB : cB + (size_t)(t + 2) * kstep;
;             const char* a3 = a2 + kstep; const char* b3 = b2 + kstep;
;             PG8_LDB(B0, 0, 0); PG8_LDB(B1, 0, 1); PG8_SCHED; PG8_LDA(At, 0, 0); PG8_STAGE(PG8_SA(1, 1), a1 + hstepA, voffA);
;             PG8_WAIT_V(8); PG8_WAIT_L(0); PG8_BAR; PG8_MMA(0, 0, At, B0); PG8_MMA(0, 1, At, B1); PG8_BAR; PG8_SCHED;
;             PG8_LDA(At, 0, 1); PG8_STAGE(PG8_SB(0, 0), b2, voffB); PG8_STAGE(PG8_SB(0, 1), b2 + hstepB, voffB); PG8_STAGE(PG8_SA(0, 0), a2, voffA);
;             PG8_WAIT_V(8); PG8_WAIT_L(0); PG8_BAR; PG8_MMA(1, 0, At, B0); PG8_MMA(1, 1, At, B1); PG8_BAR; PG8_SCHED;
;             PG8_LDB(B0, 1, 0); PG8_LDB(B1, 1, 1); PG8_SCHED; PG8_LDA(At, 1, 0); PG8_STAGE(PG8_SA(0, 1), a2 + hstepA, voffA);
;             PG8_WAIT_V(8); PG8_WAIT_L(0); PG8_BAR; PG8_MMA(0, 0, At, B0); PG8_MMA(0, 1, At, B1); PG8_BAR; PG8_SCHED;
;             PG8_LDA(At, 1, 1); PG8_STAGE(PG8_SB(1, 0), b3, voffB); PG8_STAGE(PG8_SB(1, 1), b3 + hstepB, voffB); PG8_STAGE(PG8_SA(1, 0), a3, voffA);
;             PG8_WAIT_V(8); PG8_WAIT_L(0); PG8_BAR; PG8_MMA(1, 0, At, B0); PG8_MMA(1, 1, At, B1); PG8_BAR; PG8_SCHED;
	s_nop 4
	ds_read_b128 v[52:55], v142 offset:16384
	ds_read_b128 v[56:59], v142 offset:17408
	ds_read_b128 v[92:95], v142 offset:18432
	ds_read_b128 v[186:189], v142 offset:19456
	ds_read_b128 v[190:193], v142 offset:20480
	ds_read_b128 v[194:197], v142 offset:21504
	ds_read_b128 v[198:201], v142 offset:22528
	ds_read_b128 v[202:205], v142 offset:23552
	s_mov_b32 s13, m0
	s_mov_b32 m0, s41
	s_nop 0
	global_load_lds_dwordx4 v137, s[44:45]
	s_mov_b32 m0, s43
	s_nop 0
	global_load_lds_dwordx4 v139, s[44:45]
	s_mov_b32 m0, s13
	s_add_u32 s18, s44, 0x400000
	s_addc_u32 s19, s45, 0
	s_mov_b32 s13, m0
	s_mov_b32 m0, s52
	s_nop 0
	global_load_lds_dwordx4 v137, s[18:19]
	s_mov_b32 m0, s53
	s_nop 0
	global_load_lds_dwordx4 v139, s[18:19]
	s_mov_b32 m0, s13
	s_nop 0
	s_mov_b32 s13, m0
	s_mov_b32 m0, s40
	s_nop 0
	global_load_lds_dwordx4 v136, s[46:47]
	s_mov_b32 m0, s54
	s_nop 0
	global_load_lds_dwordx4 v138, s[46:47]
	s_mov_b32 m0, s13
	s_waitcnt vmcnt(8)
	s_waitcnt lgkmcnt(0)
	s_barrier
	s_setprio 1
	s_waitcnt lgkmcnt(1)
	v_mfma_f32_16x16x32_bf16 v[0:3], v[104:107], v[198:201], v[0:3]
	v_mfma_f32_16x16x32_bf16 v[4:7], v[112:115], v[198:201], v[4:7]
	v_mfma_f32_16x16x32_bf16 v[146:149], v[104:107], v[52:55], v[146:149]
	v_mfma_f32_16x16x32_bf16 v[150:153], v[112:115], v[52:55], v[150:153]
	v_mfma_f32_16x16x32_bf16 v[154:157], v[104:107], v[92:95], v[154:157]
	v_mfma_f32_16x16x32_bf16 v[158:161], v[112:115], v[92:95], v[158:161]
	v_mfma_f32_16x16x32_bf16 v[162:165], v[104:107], v[190:193], v[162:165]
	v_mfma_f32_16x16x32_bf16 v[166:169], v[112:115], v[190:193], v[166:169]
	s_waitcnt lgkmcnt(0)
	v_mfma_f32_16x16x32_bf16 v[0:3], v[108:111], v[202:205], v[0:3]
	v_mfma_f32_16x16x32_bf16 v[4:7], v[116:119], v[202:205], v[4:7]
	v_mfma_f32_16x16x32_bf16 v[146:149], v[108:111], v[56:59], v[146:149]
	v_mfma_f32_16x16x32_bf16 v[150:153], v[116:119], v[56:59], v[150:153]
	v_mfma_f32_16x16x32_bf16 v[154:157], v[108:111], v[186:189], v[154:157]
	v_mfma_f32_16x16x32_bf16 v[158:161], v[116:119], v[186:189], v[158:161]
	v_mfma_f32_16x16x32_bf16 v[162:165], v[108:111], v[194:197], v[162:165]
	v_mfma_f32_16x16x32_bf16 v[166:169], v[116:119], v[194:197], v[166:169]
	v_mfma_f32_16x16x32_bf16 v[12:15], v[170:173], v[52:55], v[12:15]
	v_mfma_f32_16x16x32_bf16 v[206:209], v[174:177], v[56:59], v[12:15]
	v_mfma_f32_16x16x32_bf16 v[12:15], v[120:123], v[92:95], v[24:27]
	v_mfma_f32_16x16x32_bf16 v[24:27], v[124:127], v[186:189], v[12:15]
	v_mfma_f32_16x16x32_bf16 v[12:15], v[170:173], v[92:95], v[28:31]
	v_mfma_f32_16x16x32_bf16 v[186:189], v[174:177], v[186:189], v[12:15]
	v_mfma_f32_16x16x32_bf16 v[12:15], v[120:123], v[190:193], v[60:63]
	v_mfma_f32_16x16x32_bf16 v[214:217], v[124:127], v[194:197], v[12:15]
	v_mfma_f32_16x16x32_bf16 v[12:15], v[170:173], v[190:193], v[100:103]
	v_mfma_f32_16x16x32_bf16 v[8:11], v[120:123], v[52:55], v[8:11]
	v_mfma_f32_16x16x32_bf16 v[190:193], v[174:177], v[194:197], v[12:15]
	v_mfma_f32_16x16x32_bf16 v[12:15], v[120:123], v[198:201], v[16:19]
	v_mfma_f32_16x16x32_bf16 v[8:11], v[124:127], v[56:59], v[8:11]
	v_mfma_f32_16x16x32_bf16 v[194:197], v[124:127], v[202:205], v[12:15]
	v_mfma_f32_16x16x32_bf16 v[12:15], v[170:173], v[198:201], v[20:23]
	v_mfma_f32_16x16x32_bf16 v[170:173], v[174:177], v[202:205], v[12:15]
	s_setprio 0
	s_barrier
	s_nop 4
	ds_read_b128 v[12:15], v143
	ds_read_b128 v[16:19], v143 offset:1024
	ds_read_b128 v[174:177], v143 offset:2048
	ds_read_b128 v[198:201], v143 offset:3072
	ds_read_b128 v[202:205], v144
	ds_read_b128 v[218:221], v144 offset:1024
	ds_read_b128 v[222:225], v144 offset:2048
	ds_read_b128 v[226:229], v144 offset:3072
	ds_read_b128 v[20:23], v142 offset:32768
	ds_read_b128 v[28:31], v142 offset:33792
	ds_read_b128 v[56:59], v142 offset:34816
	ds_read_b128 v[230:233], v142 offset:35840
	ds_read_b128 v[234:237], v142 offset:36864
	ds_read_b128 v[238:241], v142 offset:37888
	ds_read_b128 v[242:245], v142 offset:38912
	ds_read_b128 v[246:249], v142 offset:39936
	s_add_u32 s18, s46, 0x10000
	s_addc_u32 s19, s47, 0
	s_mov_b32 s13, m0
	s_mov_b32 m0, s55
	s_nop 0
	global_load_lds_dwordx4 v136, s[18:19]
	s_mov_b32 m0, s56
	s_nop 0
	global_load_lds_dwordx4 v138, s[18:19]
	s_mov_b32 m0, s13
	s_waitcnt vmcnt(8)
	s_waitcnt lgkmcnt(0)
	s_barrier
; #define PG8_LDA(dst, b, h) do { _Pragma("unroll") for (int m = 0; m < 4; ++m) _Pragma("unroll") for (int k = 0; k < 2; ++k) dst[m][k] = *(const LAS bf16x8*)(lds + PG8_SA(b, h) + aoff + m * 2048 + k * 1024); } while (0)
; #define PG8_LDB(dst, b, h) do { _Pragma("unroll") for (int n = 0; n < 2; ++n) _Pragma("unroll") for (int k = 0; k < 2; ++k) dst[n][k] = *(const LAS bf16x8*)(lds + PG8_SB(b, h) + boff + n * 2048 + k * 1024); } while (0)
; #define PG8_WAIT_V(n) asm volatile("s_waitcnt vmcnt(" #n ")" ::: "memory")
; #define PG8_WAIT_L(n) asm volatile("s_waitcnt lgkmcnt(" #n ")" ::: "memory")
; #define PG8_BAR __builtin_amdgcn_s_barrier()
; #define PG8_SCHED __builtin_amdgcn_sched_barrier(0)
; template <class Epi, class Addr, bool ALIGN_EPI = true, class Order = StaticOrder>
; __device__ __forceinline__ void gemm_phase(LAS unsigned char* lds, const Gemm g, const Order& S, const Epi& E, const int wid) {
;     ...
;         for (int t = 0; t < nt; t += 2) {
;             const bool last = (t == nt - 2);
;             const char* a1 = cA + (size_t)(t + 1) * kstep;
;             const char* a2 = last ? nA : cA + (size_t)(t + 2) * kstep; const char* b2 = last ? nB : cB + (size_t)(t + 2) * kstep;
;             const char* a3 = a2 + kstep; const char* b3 = b2 + kstep;
;             PG8_LDB(B0, 0, 0); PG8_LDB(B1, 0, 1); PG8_SCHED; PG8_LDA(At, 0, 0); PG8_STAGE(PG8_SA(1, 1), a1 + hstepA, voffA);
;             PG8_WAIT_V(8); PG8_WAIT_L(0); PG8_BAR; PG8_MMA(0, 0, At, B0); PG8_MMA(0, 1, At, B1); PG8_BAR; PG8_SCHED;
;             PG8_LDA(At, 0, 1); PG8_STAGE(PG8_SB(0, 0), b2, voffB); PG8_STAGE(PG8_SB(0, 1), b2 + hstepB, voffB); PG8_STAGE(PG8_SA(0, 0), a2, voffA);
;             PG8_WAIT_V(8); PG8_WAIT_L(0); PG8_BAR; PG8_MMA(1, 0, At, B0); PG8_MMA(1, 1, At, B1); PG8_BAR; PG8_SCHED;
;             PG8_LDB(B0, 1, 0); PG8_LDB(B1, 1, 1); PG8_SCHED; PG8_LDA(At, 1, 0); PG8_STAGE(PG8_SA(0, 1), a2 + hstepA, voffA);
;             PG8_WAIT_V(8); PG8_WAIT_L(0); PG8_BAR; PG8_MMA(0, 0, At, B0); PG8_MMA(0, 1, At, B1); PG8_BAR; PG8_SCHED;
;             PG8_LDA(At, 1, 1); PG8_STAGE(PG8_SB(1, 0), b3, voffB); PG8_STAGE(PG8_SB(1, 1), b3 + hstepB, voffB); PG8_STAGE(PG8_SA(1, 0), a3, voffA);
;             PG8_WAIT_V(8); PG8_WAIT_L(0); PG8_BAR; PG8_MMA(1, 0, At, B0); PG8_MMA(1, 1, At, B1); PG8_BAR; PG8_SCHED;
;         }
;         if constexpr (ALIGN_EPI) { if (wr == 0) PG8_BAR; }
	s_setprio 1
	s_waitcnt lgkmcnt(7)
	v_mfma_f32_16x16x32_bf16 v[52:55], v[12:15], v[20:23], v[64:67]
	s_waitcnt lgkmcnt(6)
	v_mfma_f32_16x16x32_bf16 v[120:123], v[16:19], v[28:31], v[52:55]
	v_mfma_f32_16x16x32_bf16 v[52:55], v[174:177], v[20:23], v[68:71]
	v_mfma_f32_16x16x32_bf16 v[112:115], v[198:201], v[28:31], v[52:55]
	s_waitcnt lgkmcnt(5)
	v_mfma_f32_16x16x32_bf16 v[52:55], v[12:15], v[56:59], v[72:75]
	s_waitcnt lgkmcnt(4)
	v_mfma_f32_16x16x32_bf16 v[108:111], v[16:19], v[230:233], v[52:55]
	v_mfma_f32_16x16x32_bf16 v[52:55], v[174:177], v[56:59], v[76:79]
	v_mfma_f32_16x16x32_bf16 v[100:103], v[198:201], v[230:233], v[52:55]
	s_waitcnt lgkmcnt(3)
	v_mfma_f32_16x16x32_bf16 v[52:55], v[12:15], v[234:237], v[80:83]
	s_waitcnt lgkmcnt(2)
	v_mfma_f32_16x16x32_bf16 v[92:95], v[16:19], v[238:241], v[52:55]
	v_mfma_f32_16x16x32_bf16 v[52:55], v[174:177], v[234:237], v[84:87]
	v_mfma_f32_16x16x32_bf16 v[84:87], v[198:201], v[238:241], v[52:55]
	s_waitcnt lgkmcnt(1)
	v_mfma_f32_16x16x32_bf16 v[52:55], v[12:15], v[242:245], v[88:91]
	s_waitcnt lgkmcnt(0)
	v_mfma_f32_16x16x32_bf16 v[60:63], v[16:19], v[246:249], v[52:55]
	v_mfma_f32_16x16x32_bf16 v[52:55], v[174:177], v[242:245], v[210:213]
	v_mfma_f32_16x16x32_bf16 v[52:55], v[198:201], v[246:249], v[52:55]
	v_mfma_f32_16x16x32_bf16 v[64:67], v[202:205], v[20:23], v[96:99]
	v_mfma_f32_16x16x32_bf16 v[20:23], v[222:225], v[20:23], v[32:35]
	v_mfma_f32_16x16x32_bf16 v[116:119], v[226:229], v[28:31], v[20:23]
	v_mfma_f32_16x16x32_bf16 v[20:23], v[202:205], v[56:59], v[36:39]
	v_mfma_f32_16x16x32_bf16 v[104:107], v[218:221], v[230:233], v[20:23]
	v_mfma_f32_16x16x32_bf16 v[20:23], v[222:225], v[56:59], v[40:43]
	v_mfma_f32_16x16x32_bf16 v[96:99], v[226:229], v[230:233], v[20:23]
	v_mfma_f32_16x16x32_bf16 v[20:23], v[202:205], v[234:237], v[44:47]
	v_mfma_f32_16x16x32_bf16 v[88:91], v[218:221], v[238:241], v[20:23]
	v_mfma_f32_16x16x32_bf16 v[20:23], v[222:225], v[234:237], v[48:51]
	v_mfma_f32_16x16x32_bf16 v[80:83], v[226:229], v[238:241], v[20:23]
	v_mfma_f32_16x16x32_bf16 v[20:23], v[202:205], v[242:245], v[178:181]
	v_mfma_f32_16x16x32_bf16 v[56:59], v[218:221], v[246:249], v[20:23]
	v_mfma_f32_16x16x32_bf16 v[20:23], v[222:225], v[242:245], v[182:185]
	v_mfma_f32_16x16x32_bf16 v[124:127], v[218:221], v[28:31], v[64:67]
	v_mfma_f32_16x16x32_bf16 v[48:51], v[226:229], v[246:249], v[20:23]
	s_setprio 0
	s_barrier
	ds_read_b128 v[32:35], v142 offset:49152
	ds_read_b128 v[40:43], v142 offset:50176
	ds_read_b128 v[178:181], v142 offset:51200
	ds_read_b128 v[182:185], v142 offset:52224
	ds_read_b128 v[210:213], v142 offset:53248
	ds_read_b128 v[230:233], v142 offset:54272
	ds_read_b128 v[234:237], v142 offset:55296
	ds_read_b128 v[238:241], v142 offset:56320
	s_add_u32 s18, s44, 0x80
	s_addc_u32 s19, s45, 0
	s_mov_b32 s13, m0
	s_mov_b32 m0, s59
	s_nop 0
	global_load_lds_dwordx4 v137, s[18:19]
	s_mov_b32 m0, s60
	s_nop 0
	global_load_lds_dwordx4 v139, s[18:19]
	s_mov_b32 m0, s13
	s_add_u32 s18, s44, 0x400080
	s_addc_u32 s19, s45, 0
	s_mov_b32 s13, m0
	s_mov_b32 m0, s63
	s_nop 0
	global_load_lds_dwordx4 v137, s[18:19]
	s_mov_b32 m0, s64
	s_nop 0
	global_load_lds_dwordx4 v139, s[18:19]
	s_mov_b32 m0, s13
	s_nop 0
	s_mov_b32 s13, m0
	s_mov_b32 m0, s61
	s_nop 0
	global_load_lds_dwordx4 v136, s[26:27]
	s_mov_b32 m0, s62
	s_nop 0
	global_load_lds_dwordx4 v138, s[26:27]
	s_mov_b32 m0, s13
	s_waitcnt vmcnt(8)
	s_waitcnt lgkmcnt(0)
	s_barrier
	s_setprio 1
	s_waitcnt lgkmcnt(7)
	v_mfma_f32_16x16x32_bf16 v[20:23], v[12:15], v[32:35], v[146:149]
	s_waitcnt lgkmcnt(6)
	v_mfma_f32_16x16x32_bf16 v[76:79], v[16:19], v[40:43], v[20:23]
	v_mfma_f32_16x16x32_bf16 v[20:23], v[174:177], v[32:35], v[150:153]
	v_mfma_f32_16x16x32_bf16 v[68:71], v[198:201], v[40:43], v[20:23]
	s_waitcnt lgkmcnt(5)
	v_mfma_f32_16x16x32_bf16 v[20:23], v[12:15], v[178:181], v[154:157]
	s_waitcnt lgkmcnt(4)
	v_mfma_f32_16x16x32_bf16 v[44:47], v[16:19], v[182:185], v[20:23]
	v_mfma_f32_16x16x32_bf16 v[20:23], v[174:177], v[178:181], v[158:161]
	v_mfma_f32_16x16x32_bf16 v[36:39], v[198:201], v[182:185], v[20:23]
	s_waitcnt lgkmcnt(3)
	v_mfma_f32_16x16x32_bf16 v[20:23], v[12:15], v[210:213], v[162:165]
	s_waitcnt lgkmcnt(1)
	v_mfma_f32_16x16x32_bf16 v[0:3], v[12:15], v[234:237], v[0:3]
	v_mfma_f32_16x16x32_bf16 v[28:31], v[16:19], v[230:233], v[20:23]
	v_mfma_f32_16x16x32_bf16 v[20:23], v[174:177], v[210:213], v[166:169]
	s_waitcnt lgkmcnt(0)
	v_mfma_f32_16x16x32_bf16 v[12:15], v[16:19], v[238:241], v[0:3]
	v_mfma_f32_16x16x32_bf16 v[0:3], v[174:177], v[234:237], v[4:7]
	v_mfma_f32_16x16x32_bf16 v[20:23], v[198:201], v[230:233], v[20:23]
	v_mfma_f32_16x16x32_bf16 v[4:7], v[198:201], v[238:241], v[0:3]
	v_mfma_f32_16x16x32_bf16 v[0:3], v[202:205], v[32:35], v[8:11]
	v_mfma_f32_16x16x32_bf16 v[72:75], v[218:221], v[40:43], v[0:3]
	v_mfma_f32_16x16x32_bf16 v[0:3], v[222:225], v[32:35], v[206:209]
	v_mfma_f32_16x16x32_bf16 v[64:67], v[226:229], v[40:43], v[0:3]
	v_mfma_f32_16x16x32_bf16 v[0:3], v[202:205], v[178:181], v[24:27]
	v_mfma_f32_16x16x32_bf16 v[40:43], v[218:221], v[182:185], v[0:3]
	v_mfma_f32_16x16x32_bf16 v[0:3], v[222:225], v[178:181], v[186:189]
	v_mfma_f32_16x16x32_bf16 v[32:35], v[226:229], v[182:185], v[0:3]
	v_mfma_f32_16x16x32_bf16 v[0:3], v[202:205], v[210:213], v[214:217]
	v_mfma_f32_16x16x32_bf16 v[24:27], v[218:221], v[230:233], v[0:3]
	v_mfma_f32_16x16x32_bf16 v[0:3], v[222:225], v[210:213], v[190:193]
	v_mfma_f32_16x16x32_bf16 v[16:19], v[226:229], v[230:233], v[0:3]
	v_mfma_f32_16x16x32_bf16 v[0:3], v[202:205], v[234:237], v[194:197]
	v_mfma_f32_16x16x32_bf16 v[8:11], v[218:221], v[238:241], v[0:3]
	v_mfma_f32_16x16x32_bf16 v[0:3], v[222:225], v[234:237], v[170:173]
	v_mfma_f32_16x16x32_bf16 v[0:3], v[226:229], v[238:241], v[0:3]
	s_setprio 0
	s_barrier
	s_andn2_b64 vcc, exec, s[8:9]
	s_cbranch_vccnz .LBB0_269
	s_barrier

; #define PG8_LDA(dst, b, h) do { _Pragma("unroll") for (int m = 0; m < 4; ++m) _Pragma("unroll") for (int k = 0; k < 2; ++k) dst[m][k] = *(const LAS bf16x8*)(lds + PG8_SA(b, h) + aoff + m * 2048 + k * 1024); } while (0)
; #define PG8_LDB(dst, b, h) do { _Pragma("unroll") for (int n = 0; n < 2; ++n) _Pragma("unroll") for (int k = 0; k < 2; ++k) dst[n][k] = *(const LAS bf16x8*)(lds + PG8_SB(b, h) + boff + n * 2048 + k * 1024); } while (0)
; #define PG8_WAIT_V(n) asm volatile("s_waitcnt vmcnt(" #n ")" ::: "memory")
; #define PG8_BAR __builtin_amdgcn_s_barrier()
; template <class Epi, class Addr, bool ALIGN_EPI = true, class Order = StaticOrder>
; __device__ __forceinline__ void gemm_phase(LAS unsigned char* lds, const Gemm g, const Order& S, const Epi& E, const int wid) {
;     ...
;         const bool has_next = S.next(ui + 1, nxt);
;         const char* nA = has_next ? (const char*)g.A + Addr::offA(nxt, g) : cA; const char* nB = has_next ? (const char*)g.Bt + Addr::offB(nxt, g) : cB;
;         for (int t = 0; t < nt; t += 2) {
;             const bool last = (t == nt - 2);
;             const char* a1 = cA + (size_t)(t + 1) * kstep;
;             const char* a2 = last ? nA : cA + (size_t)(t + 2) * kstep; const char* b2 = last ? nB : cB + (size_t)(t + 2) * kstep;
;             const char* a3 = a2 + kstep; const char* b3 = b2 + kstep;
;             PG8_LDB(B0, 0, 0); PG8_LDB(B1, 0, 1); PG8_SCHED; PG8_LDA(At, 0, 0); PG8_STAGE(PG8_SA(1, 1), a1 + hstepA, voffA);
;             PG8_WAIT_V(8); PG8_WAIT_L(0); PG8_BAR; PG8_MMA(0, 0, At, B0); PG8_MMA(0, 1, At, B1); PG8_BAR; PG8_SCHED;
;             PG8_LDA(At, 0, 1); PG8_STAGE(PG8_SB(0, 0), b2, voffB); PG8_STAGE(PG8_SB(0, 1), b2 + hstepB, voffB); PG8_STAGE(PG8_SA(0, 0), a2, voffA);
;             PG8_WAIT_V(8); PG8_WAIT_L(0); PG8_BAR; PG8_MMA(1, 0, At, B0); PG8_MMA(1, 1, At, B1); PG8_BAR; PG8_SCHED;
;             PG8_LDB(B0, 1, 0); PG8_LDB(B1, 1, 1); PG8_SCHED; PG8_LDA(At, 1, 0); PG8_STAGE(PG8_SA(0, 1), a2 + hstepA, voffA);
;             PG8_WAIT_V(8); PG8_WAIT_L(0); PG8_BAR; PG8_MMA(0, 0, At, B0); PG8_MMA(0, 1, At, B1); PG8_BAR; PG8_SCHED;
;             PG8_LDA(At, 1, 1); PG8_STAGE(PG8_SB(1, 0), b3, voffB); PG8_STAGE(PG8_SB(1, 1), b3 + hstepB, voffB); PG8_STAGE(PG8_SA(1, 0), a3, voffA);
;             PG8_WAIT_V(8); PG8_WAIT_L(0); PG8_BAR; PG8_MMA(1, 0, At, B0); PG8_MMA(1, 1, At, B1); PG8_BAR; PG8_SCHED;
.LBB0_559:
	s_add_u32 s44, s26, 0x100
	ds_read_b128 v[146:149], v140
	ds_read_b128 v[150:153], v140 offset:1024
	ds_read_b128 v[154:157], v140 offset:2048
	ds_read_b128 v[158:161], v140 offset:3072
	ds_read_b128 v[162:165], v141
	ds_read_b128 v[166:169], v141 offset:1024
	ds_read_b128 v[170:173], v141 offset:2048
	ds_read_b128 v[174:177], v141 offset:3072
	s_addc_u32 s45, s27, 0
	s_add_u32 s18, s22, s26
	s_addc_u32 s19, s23, s27
	s_add_u32 s25, s18, 0x100
	s_addc_u32 s26, s19, 0
	s_cmp_eq_u32 s17, 4
	s_cselect_b32 s48, s15, s25
	s_cselect_b32 s49, s13, s26
	s_cselect_b32 s25, 0, s45
	s_cselect_b32 s36, 0, s44
	s_add_u32 s26, s48, 0x80
	s_addc_u32 s27, s49, 0
	s_add_u32 s46, s6, s36
	s_addc_u32 s47, s7, s25
	ds_read_b128 v[178:181], v142
	ds_read_b128 v[182:185], v142 offset:1024
	ds_read_b128 v[186:189], v142 offset:2048
	ds_read_b128 v[190:193], v142 offset:3072
	ds_read_b128 v[194:197], v142 offset:4096
	ds_read_b128 v[198:201], v142 offset:5120
	ds_read_b128 v[202:205], v142 offset:6144
	ds_read_b128 v[206:209], v142 offset:7168
	s_add_u32 s18, s18, 0x100080
	s_addc_u32 s19, s19, 0
	s_mov_b32 s25, m0
	s_mov_b32 m0, s64
	s_nop 0
	global_load_lds_dwordx4 v136, s[18:19]
	s_mov_b32 m0, s65
	s_nop 0
	global_load_lds_dwordx4 v138, s[18:19]
	s_mov_b32 m0, s25
	s_waitcnt vmcnt(8)
	s_waitcnt lgkmcnt(0)
	s_barrier
	s_setprio 1
	s_waitcnt lgkmcnt(7)
	v_mfma_f32_16x16x32_bf16 v[124:127], v[146:149], v[178:181], v[124:127]
	v_mfma_f32_16x16x32_bf16 v[120:123], v[154:157], v[178:181], v[120:123]
	s_waitcnt lgkmcnt(5)
	v_mfma_f32_16x16x32_bf16 v[116:119], v[146:149], v[186:189], v[116:119]
	v_mfma_f32_16x16x32_bf16 v[108:111], v[154:157], v[186:189], v[108:111]
	s_waitcnt lgkmcnt(3)
	v_mfma_f32_16x16x32_bf16 v[100:103], v[146:149], v[194:197], v[100:103]
	v_mfma_f32_16x16x32_bf16 v[92:95], v[154:157], v[194:197], v[92:95]
	s_waitcnt lgkmcnt(1)
	v_mfma_f32_16x16x32_bf16 v[84:87], v[146:149], v[202:205], v[84:87]
	v_mfma_f32_16x16x32_bf16 v[76:79], v[154:157], v[202:205], v[76:79]
	v_mfma_f32_16x16x32_bf16 v[124:127], v[150:153], v[182:185], v[124:127]
	v_mfma_f32_16x16x32_bf16 v[120:123], v[158:161], v[182:185], v[120:123]
	v_mfma_f32_16x16x32_bf16 v[116:119], v[150:153], v[190:193], v[116:119]
	v_mfma_f32_16x16x32_bf16 v[108:111], v[158:161], v[190:193], v[108:111]
	v_mfma_f32_16x16x32_bf16 v[100:103], v[150:153], v[198:201], v[100:103]
	v_mfma_f32_16x16x32_bf16 v[92:95], v[158:161], v[198:201], v[92:95]
	s_waitcnt lgkmcnt(0)
	v_mfma_f32_16x16x32_bf16 v[84:87], v[150:153], v[206:209], v[84:87]
	v_mfma_f32_16x16x32_bf16 v[76:79], v[158:161], v[206:209], v[76:79]
	v_mfma_f32_16x16x32_bf16 v[112:115], v[162:165], v[178:181], v[112:115]
	v_mfma_f32_16x16x32_bf16 v[104:107], v[170:173], v[178:181], v[104:107]
	v_mfma_f32_16x16x32_bf16 v[96:99], v[162:165], v[186:189], v[96:99]
	v_mfma_f32_16x16x32_bf16 v[88:91], v[170:173], v[186:189], v[88:91]
	v_mfma_f32_16x16x32_bf16 v[80:83], v[162:165], v[194:197], v[80:83]
	v_mfma_f32_16x16x32_bf16 v[72:75], v[170:173], v[194:197], v[72:75]
	v_mfma_f32_16x16x32_bf16 v[68:71], v[162:165], v[202:205], v[68:71]
	v_mfma_f32_16x16x32_bf16 v[64:67], v[170:173], v[202:205], v[64:67]
	v_mfma_f32_16x16x32_bf16 v[112:115], v[166:169], v[182:185], v[112:115]
	v_mfma_f32_16x16x32_bf16 v[104:107], v[174:177], v[182:185], v[104:107]
	v_mfma_f32_16x16x32_bf16 v[96:99], v[166:169], v[190:193], v[96:99]
	v_mfma_f32_16x16x32_bf16 v[88:91], v[174:177], v[190:193], v[88:91]
	v_mfma_f32_16x16x32_bf16 v[80:83], v[166:169], v[198:201], v[80:83]
	v_mfma_f32_16x16x32_bf16 v[72:75], v[174:177], v[198:201], v[72:75]
	v_mfma_f32_16x16x32_bf16 v[68:71], v[166:169], v[206:209], v[68:71]
	v_mfma_f32_16x16x32_bf16 v[64:67], v[174:177], v[206:209], v[64:67]
	s_setprio 0
	s_barrier
	ds_read_b128 v[178:181], v142 offset:16384
	ds_read_b128 v[182:185], v142 offset:17408
	ds_read_b128 v[186:189], v142 offset:18432
	ds_read_b128 v[190:193], v142 offset:19456
	ds_read_b128 v[194:197], v142 offset:20480
	ds_read_b128 v[198:201], v142 offset:21504
	ds_read_b128 v[202:205], v142 offset:22528
	ds_read_b128 v[206:209], v142 offset:23552
	s_mov_b32 s18, m0
	s_mov_b32 m0, s41
	s_nop 0
	global_load_lds_dwordx4 v137, s[46:47]
	s_mov_b32 m0, s43
	s_nop 0
	global_load_lds_dwordx4 v139, s[46:47]
	s_mov_b32 m0, s18
	s_add_u32 s18, s46, 0x20000
	s_addc_u32 s19, s47, 0
	s_mov_b32 s25, m0
	s_mov_b32 m0, s50
	s_nop 0
	global_load_lds_dwordx4 v137, s[18:19]
	s_mov_b32 m0, s51
	s_nop 0
	global_load_lds_dwordx4 v139, s[18:19]
	s_mov_b32 m0, s25
	s_mov_b32 s18, m0
	s_mov_b32 m0, s39
	s_nop 0
	global_load_lds_dwordx4 v136, s[48:49]
	s_mov_b32 m0, s52
	s_nop 0
	global_load_lds_dwordx4 v138, s[48:49]
	s_mov_b32 m0, s18
	s_waitcnt vmcnt(8)
	s_waitcnt lgkmcnt(0)
	s_barrier
; #define PG8_LDA(dst, b, h) do { _Pragma("unroll") for (int m = 0; m < 4; ++m) _Pragma("unroll") for (int k = 0; k < 2; ++k) dst[m][k] = *(const LAS bf16x8*)(lds + PG8_SA(b, h) + aoff + m * 2048 + k * 1024); } while (0)
; #define PG8_LDB(dst, b, h) do { _Pragma("unroll") for (int n = 0; n < 2; ++n) _Pragma("unroll") for (int k = 0; k < 2; ++k) dst[n][k] = *(const LAS bf16x8*)(lds + PG8_SB(b, h) + boff + n * 2048 + k * 1024); } while (0)
; #define PG8_WAIT_V(n) asm volatile("s_waitcnt vmcnt(" #n ")" ::: "memory")
; #define PG8_WAIT_L(n) asm volatile("s_waitcnt lgkmcnt(" #n ")" ::: "memory")
; #define PG8_BAR __builtin_amdgcn_s_barrier()
; #define PG8_SCHED __builtin_amdgcn_sched_barrier(0)
; template <class Epi, class Addr, bool ALIGN_EPI = true, class Order = StaticOrder>
; __device__ __forceinline__ void gemm_phase(LAS unsigned char* lds, const Gemm g, const Order& S, const Epi& E, const int wid) {
;     ...
;         for (int t = 0; t < nt; t += 2) {
;             const bool last = (t == nt - 2);
;             const char* a1 = cA + (size_t)(t + 1) * kstep;
;             const char* a2 = last ? nA : cA + (size_t)(t + 2) * kstep; const char* b2 = last ? nB : cB + (size_t)(t + 2) * kstep;
;             const char* a3 = a2 + kstep; const char* b3 = b2 + kstep;
;             PG8_LDB(B0, 0, 0); PG8_LDB(B1, 0, 1); PG8_SCHED; PG8_LDA(At, 0, 0); PG8_STAGE(PG8_SA(1, 1), a1 + hstepA, voffA);
;             PG8_WAIT_V(8); PG8_WAIT_L(0); PG8_BAR; PG8_MMA(0, 0, At, B0); PG8_MMA(0, 1, At, B1); PG8_BAR; PG8_SCHED;
;             PG8_LDA(At, 0, 1); PG8_STAGE(PG8_SB(0, 0), b2, voffB); PG8_STAGE(PG8_SB(0, 1), b2 + hstepB, voffB); PG8_STAGE(PG8_SA(0, 0), a2, voffA);
;             PG8_WAIT_V(8); PG8_WAIT_L(0); PG8_BAR; PG8_MMA(1, 0, At, B0); PG8_MMA(1, 1, At, B1); PG8_BAR; PG8_SCHED;
;             PG8_LDB(B0, 1, 0); PG8_LDB(B1, 1, 1); PG8_SCHED; PG8_LDA(At, 1, 0); PG8_STAGE(PG8_SA(0, 1), a2 + hstepA, voffA);
;             PG8_WAIT_V(8); PG8_WAIT_L(0); PG8_BAR; PG8_MMA(0, 0, At, B0); PG8_MMA(0, 1, At, B1); PG8_BAR; PG8_SCHED;
;             PG8_LDA(At, 1, 1); PG8_STAGE(PG8_SB(1, 0), b3, voffB); PG8_STAGE(PG8_SB(1, 1), b3 + hstepB, voffB); PG8_STAGE(PG8_SA(1, 0), a3, voffA);
;             PG8_WAIT_V(8); PG8_WAIT_L(0); PG8_BAR; PG8_MMA(1, 0, At, B0); PG8_MMA(1, 1, At, B1); PG8_BAR; PG8_SCHED;
	s_setprio 1
	s_waitcnt lgkmcnt(7)
	v_mfma_f32_16x16x32_bf16 v[60:63], v[146:149], v[178:181], v[60:63]
	v_mfma_f32_16x16x32_bf16 v[56:59], v[154:157], v[178:181], v[56:59]
	s_waitcnt lgkmcnt(5)
	v_mfma_f32_16x16x32_bf16 v[52:55], v[146:149], v[186:189], v[52:55]
	v_mfma_f32_16x16x32_bf16 v[44:47], v[154:157], v[186:189], v[44:47]
	s_waitcnt lgkmcnt(3)
	v_mfma_f32_16x16x32_bf16 v[36:39], v[146:149], v[194:197], v[36:39]
	v_mfma_f32_16x16x32_bf16 v[28:31], v[154:157], v[194:197], v[28:31]
	s_waitcnt lgkmcnt(1)
	v_mfma_f32_16x16x32_bf16 v[20:23], v[146:149], v[202:205], v[20:23]
	v_mfma_f32_16x16x32_bf16 v[12:15], v[154:157], v[202:205], v[12:15]
	v_mfma_f32_16x16x32_bf16 v[60:63], v[150:153], v[182:185], v[60:63]
	v_mfma_f32_16x16x32_bf16 v[56:59], v[158:161], v[182:185], v[56:59]
	v_mfma_f32_16x16x32_bf16 v[52:55], v[150:153], v[190:193], v[52:55]
	v_mfma_f32_16x16x32_bf16 v[44:47], v[158:161], v[190:193], v[44:47]
	v_mfma_f32_16x16x32_bf16 v[36:39], v[150:153], v[198:201], v[36:39]
	v_mfma_f32_16x16x32_bf16 v[28:31], v[158:161], v[198:201], v[28:31]
	s_waitcnt lgkmcnt(0)
	v_mfma_f32_16x16x32_bf16 v[20:23], v[150:153], v[206:209], v[20:23]
	v_mfma_f32_16x16x32_bf16 v[12:15], v[158:161], v[206:209], v[12:15]
	v_mfma_f32_16x16x32_bf16 v[48:51], v[162:165], v[178:181], v[48:51]
	v_mfma_f32_16x16x32_bf16 v[40:43], v[170:173], v[178:181], v[40:43]
	v_mfma_f32_16x16x32_bf16 v[32:35], v[162:165], v[186:189], v[32:35]
	v_mfma_f32_16x16x32_bf16 v[24:27], v[170:173], v[186:189], v[24:27]
	v_mfma_f32_16x16x32_bf16 v[16:19], v[162:165], v[194:197], v[16:19]
	v_mfma_f32_16x16x32_bf16 v[8:11], v[170:173], v[194:197], v[8:11]
	v_mfma_f32_16x16x32_bf16 v[4:7], v[162:165], v[202:205], v[4:7]
	v_mfma_f32_16x16x32_bf16 v[0:3], v[170:173], v[202:205], v[0:3]
	v_mfma_f32_16x16x32_bf16 v[48:51], v[166:169], v[182:185], v[48:51]
	v_mfma_f32_16x16x32_bf16 v[40:43], v[174:177], v[182:185], v[40:43]
	v_mfma_f32_16x16x32_bf16 v[32:35], v[166:169], v[190:193], v[32:35]
	v_mfma_f32_16x16x32_bf16 v[24:27], v[174:177], v[190:193], v[24:27]
	v_mfma_f32_16x16x32_bf16 v[16:19], v[166:169], v[198:201], v[16:19]
	v_mfma_f32_16x16x32_bf16 v[8:11], v[174:177], v[198:201], v[8:11]
	v_mfma_f32_16x16x32_bf16 v[4:7], v[166:169], v[206:209], v[4:7]
	v_mfma_f32_16x16x32_bf16 v[0:3], v[174:177], v[206:209], v[0:3]
	s_setprio 0
	s_barrier
	ds_read_b128 v[146:149], v143
	ds_read_b128 v[150:153], v143 offset:1024
	ds_read_b128 v[154:157], v143 offset:2048
	ds_read_b128 v[158:161], v143 offset:3072
	ds_read_b128 v[162:165], v144
	ds_read_b128 v[166:169], v144 offset:1024
	ds_read_b128 v[170:173], v144 offset:2048
	ds_read_b128 v[174:177], v144 offset:3072
	ds_read_b128 v[178:181], v142 offset:32768
	ds_read_b128 v[182:185], v142 offset:33792
	ds_read_b128 v[186:189], v142 offset:34816
	ds_read_b128 v[190:193], v142 offset:35840
	ds_read_b128 v[194:197], v142 offset:36864
	ds_read_b128 v[198:201], v142 offset:37888
	ds_read_b128 v[202:205], v142 offset:38912
	ds_read_b128 v[206:209], v142 offset:39936
	s_add_u32 s18, s48, 0x100000
	s_addc_u32 s19, s49, 0
	s_mov_b32 s25, m0
	s_mov_b32 m0, s53
	s_nop 0
	global_load_lds_dwordx4 v136, s[18:19]
	s_mov_b32 m0, s54
	s_nop 0
	global_load_lds_dwordx4 v138, s[18:19]
	s_mov_b32 m0, s25
	s_waitcnt vmcnt(8)
	s_waitcnt lgkmcnt(0)
	s_barrier
	s_setprio 1
	s_waitcnt lgkmcnt(7)
	v_mfma_f32_16x16x32_bf16 v[124:127], v[146:149], v[178:181], v[124:127]
	v_mfma_f32_16x16x32_bf16 v[120:123], v[154:157], v[178:181], v[120:123]
	s_waitcnt lgkmcnt(5)
	v_mfma_f32_16x16x32_bf16 v[116:119], v[146:149], v[186:189], v[116:119]
	v_mfma_f32_16x16x32_bf16 v[108:111], v[154:157], v[186:189], v[108:111]
	s_waitcnt lgkmcnt(3)
	v_mfma_f32_16x16x32_bf16 v[100:103], v[146:149], v[194:197], v[100:103]
	v_mfma_f32_16x16x32_bf16 v[92:95], v[154:157], v[194:197], v[92:95]
	s_waitcnt lgkmcnt(1)
	v_mfma_f32_16x16x32_bf16 v[84:87], v[146:149], v[202:205], v[84:87]
	v_mfma_f32_16x16x32_bf16 v[76:79], v[154:157], v[202:205], v[76:79]
	v_mfma_f32_16x16x32_bf16 v[124:127], v[150:153], v[182:185], v[124:127]
	v_mfma_f32_16x16x32_bf16 v[120:123], v[158:161], v[182:185], v[120:123]
	v_mfma_f32_16x16x32_bf16 v[116:119], v[150:153], v[190:193], v[116:119]
	v_mfma_f32_16x16x32_bf16 v[108:111], v[158:161], v[190:193], v[108:111]
	v_mfma_f32_16x16x32_bf16 v[100:103], v[150:153], v[198:201], v[100:103]
	v_mfma_f32_16x16x32_bf16 v[92:95], v[158:161], v[198:201], v[92:95]
	s_waitcnt lgkmcnt(0)
	v_mfma_f32_16x16x32_bf16 v[84:87], v[150:153], v[206:209], v[84:87]
	v_mfma_f32_16x16x32_bf16 v[76:79], v[158:161], v[206:209], v[76:79]
	v_mfma_f32_16x16x32_bf16 v[112:115], v[162:165], v[178:181], v[112:115]
	v_mfma_f32_16x16x32_bf16 v[104:107], v[170:173], v[178:181], v[104:107]
	v_mfma_f32_16x16x32_bf16 v[96:99], v[162:165], v[186:189], v[96:99]
	v_mfma_f32_16x16x32_bf16 v[88:91], v[170:173], v[186:189], v[88:91]
	v_mfma_f32_16x16x32_bf16 v[80:83], v[162:165], v[194:197], v[80:83]
	v_mfma_f32_16x16x32_bf16 v[72:75], v[170:173], v[194:197], v[72:75]
	v_mfma_f32_16x16x32_bf16 v[68:71], v[162:165], v[202:205], v[68:71]
	v_mfma_f32_16x16x32_bf16 v[64:67], v[170:173], v[202:205], v[64:67]
	v_mfma_f32_16x16x32_bf16 v[112:115], v[166:169], v[182:185], v[112:115]
	v_mfma_f32_16x16x32_bf16 v[104:107], v[174:177], v[182:185], v[104:107]
	v_mfma_f32_16x16x32_bf16 v[96:99], v[166:169], v[190:193], v[96:99]
	v_mfma_f32_16x16x32_bf16 v[88:91], v[174:177], v[190:193], v[88:91]
	v_mfma_f32_16x16x32_bf16 v[80:83], v[166:169], v[198:201], v[80:83]
	v_mfma_f32_16x16x32_bf16 v[72:75], v[174:177], v[198:201], v[72:75]
	v_mfma_f32_16x16x32_bf16 v[68:71], v[166:169], v[206:209], v[68:71]
	v_mfma_f32_16x16x32_bf16 v[64:67], v[174:177], v[206:209], v[64:67]
	s_setprio 0
	s_barrier
; template <class Epi, class Addr, bool ALIGN_EPI = true, class Order = StaticOrder>
; __device__ __forceinline__ void gemm_phase(LAS unsigned char* lds, const Gemm g, const Order& S, const Epi& E, const int wid) {
;     ...
;     Unit cur, nxt; int ui = 0;
;     if (!S.next(0, cur)) return;
;     f32x4 acc[2][2][4][2];
; #pragma unroll
;     for (int a = 0; a < 2; ++a)
; #pragma unroll
;         for (int b = 0; b < 2; ++b)
; #pragma unroll
;             for (int m = 0; m < 4; ++m)
; #pragma unroll
;                 for (int n = 0; n < 2; ++n) acc[a][b][m][n] = (f32x4){0.f, 0.f, 0.f, 0.f};
;     bf16x8 At[4][2], B0[2][2], B1[2][2];
;     const char* cA = (const char*)g.A + Addr::offA(cur, g); const char* cB = (const char*)g.Bt + Addr::offB(cur, g);
;     PG8_STAGE(PG8_SB(0, 0), cB, voffB); PG8_STAGE(PG8_SB(0, 1), cB + hstepB, voffB); PG8_STAGE(PG8_SA(0, 0), cA, voffA); PG8_STAGE(PG8_SA(0, 1), cA + hstepA, voffA);
;     if (wr == 1) PG8_BAR;
;     PG8_WAIT_V(2); PG8_BAR;
;     PG8_STAGE(PG8_SB(1, 0), cB + kstep, voffB); PG8_STAGE(PG8_SA(1, 0), cA + kstep, voffA); PG8_STAGE(PG8_SB(1, 1), cB + hstepB + kstep, voffB);
;     PG8_WAIT_V(6); PG8_BAR;
;     for (;;) {
;         const bool has_next = S.next(ui + 1, nxt);
;         const char* nA = has_next ? (const char*)g.A + Addr::offA(nxt, g) : cA; const char* nB = has_next ? (const char*)g.Bt + Addr::offB(nxt, g) : cB;
;         for (int t = 0; t < nt; t += 2) {
;             const bool last = (t == nt - 2);
;             const char* a1 = cA + (size_t)(t + 1) * kstep;
;             const char* a2 = last ? nA : cA + (size_t)(t + 2) * kstep; const char* b2 = last ? nB : cB + (size_t)(t + 2) * kstep;
;             const char* a3 = a2 + kstep; const char* b3 = b2 + kstep;
;             PG8_LDB(B0, 0, 0); PG8_LDB(B1, 0, 1); PG8_SCHED; PG8_LDA(At, 0, 0); PG8_STAGE(PG8_SA(1, 1), a1 + hstepA, voffA);
;             PG8_WAIT_V(8); PG8_WAIT_L(0); PG8_BAR; PG8_MMA(0, 0, At, B0); PG8_MMA(0, 1, At, B1); PG8_BAR; PG8_SCHED;
;             PG8_LDA(At, 0, 1); PG8_STAGE(PG8_SB(0, 0), b2, voffB); PG8_STAGE(PG8_SB(0, 1), b2 + hstepB, voffB); PG8_STAGE(PG8_SA(0, 0), a2, voffA);
;             PG8_WAIT_V(8); PG8_WAIT_L(0); PG8_BAR; PG8_MMA(1, 0, At, B0); PG8_MMA(1, 1, At, B1); PG8_BAR; PG8_SCHED;
;             PG8_LDB(B0, 1, 0); PG8_LDB(B1, 1, 1); PG8_SCHED; PG8_LDA(At, 1, 0); PG8_STAGE(PG8_SA(0, 1), a2 + hstepA, voffA);
	ds_read_b128 v[178:181], v142 offset:49152
	ds_read_b128 v[182:185], v142 offset:50176
	ds_read_b128 v[186:189], v142 offset:51200
	ds_read_b128 v[190:193], v142 offset:52224
	ds_read_b128 v[194:197], v142 offset:53248
	ds_read_b128 v[198:201], v142 offset:54272
	ds_read_b128 v[202:205], v142 offset:55296
	ds_read_b128 v[206:209], v142 offset:56320
	s_add_u32 s18, s46, 0x80
	s_addc_u32 s19, s47, 0
	s_mov_b32 s25, m0
	s_mov_b32 m0, s58
	s_nop 0
	global_load_lds_dwordx4 v137, s[18:19]
	s_mov_b32 m0, s59
	s_nop 0
	global_load_lds_dwordx4 v139, s[18:19]
	s_mov_b32 m0, s25
	s_add_u32 s18, s46, 0x20080
	s_addc_u32 s19, s47, 0
	s_mov_b32 s25, m0
	s_mov_b32 m0, s62
	s_nop 0
	global_load_lds_dwordx4 v137, s[18:19]
	s_mov_b32 m0, s63
	s_nop 0
	global_load_lds_dwordx4 v139, s[18:19]
	s_mov_b32 m0, s25
	s_mov_b32 s18, m0
	s_mov_b32 m0, s60
	s_nop 0
	global_load_lds_dwordx4 v136, s[26:27]
	s_mov_b32 m0, s61
	s_nop 0
	global_load_lds_dwordx4 v138, s[26:27]
	s_mov_b32 m0, s18
	s_waitcnt vmcnt(8)
	s_waitcnt lgkmcnt(0)
	s_barrier
	s_setprio 1
	s_waitcnt lgkmcnt(7)
	v_mfma_f32_16x16x32_bf16 v[60:63], v[146:149], v[178:181], v[60:63]
	v_mfma_f32_16x16x32_bf16 v[56:59], v[154:157], v[178:181], v[56:59]
	s_waitcnt lgkmcnt(5)
	v_mfma_f32_16x16x32_bf16 v[52:55], v[146:149], v[186:189], v[52:55]
	v_mfma_f32_16x16x32_bf16 v[44:47], v[154:157], v[186:189], v[44:47]
	s_waitcnt lgkmcnt(3)
	v_mfma_f32_16x16x32_bf16 v[36:39], v[146:149], v[194:197], v[36:39]
	v_mfma_f32_16x16x32_bf16 v[28:31], v[154:157], v[194:197], v[28:31]
	s_waitcnt lgkmcnt(1)
	v_mfma_f32_16x16x32_bf16 v[20:23], v[146:149], v[202:205], v[20:23]
	v_mfma_f32_16x16x32_bf16 v[12:15], v[154:157], v[202:205], v[12:15]
	v_mfma_f32_16x16x32_bf16 v[60:63], v[150:153], v[182:185], v[60:63]
	v_mfma_f32_16x16x32_bf16 v[56:59], v[158:161], v[182:185], v[56:59]
	v_mfma_f32_16x16x32_bf16 v[52:55], v[150:153], v[190:193], v[52:55]
	v_mfma_f32_16x16x32_bf16 v[44:47], v[158:161], v[190:193], v[44:47]
	v_mfma_f32_16x16x32_bf16 v[36:39], v[150:153], v[198:201], v[36:39]
	v_mfma_f32_16x16x32_bf16 v[28:31], v[158:161], v[198:201], v[28:31]
	s_waitcnt lgkmcnt(0)
	v_mfma_f32_16x16x32_bf16 v[20:23], v[150:153], v[206:209], v[20:23]
	v_mfma_f32_16x16x32_bf16 v[12:15], v[158:161], v[206:209], v[12:15]
	v_mfma_f32_16x16x32_bf16 v[48:51], v[162:165], v[178:181], v[48:51]
	v_mfma_f32_16x16x32_bf16 v[40:43], v[170:173], v[178:181], v[40:43]
	v_mfma_f32_16x16x32_bf16 v[32:35], v[162:165], v[186:189], v[32:35]
	v_mfma_f32_16x16x32_bf16 v[24:27], v[170:173], v[186:189], v[24:27]
	v_mfma_f32_16x16x32_bf16 v[16:19], v[162:165], v[194:197], v[16:19]
	v_mfma_f32_16x16x32_bf16 v[8:11], v[170:173], v[194:197], v[8:11]
	v_mfma_f32_16x16x32_bf16 v[4:7], v[162:165], v[202:205], v[4:7]
	v_mfma_f32_16x16x32_bf16 v[0:3], v[170:173], v[202:205], v[0:3]
	v_mfma_f32_16x16x32_bf16 v[48:51], v[166:169], v[182:185], v[48:51]
	v_mfma_f32_16x16x32_bf16 v[40:43], v[174:177], v[182:185], v[40:43]
	v_mfma_f32_16x16x32_bf16 v[32:35], v[166:169], v[190:193], v[32:35]
	v_mfma_f32_16x16x32_bf16 v[24:27], v[174:177], v[190:193], v[24:27]
	v_mfma_f32_16x16x32_bf16 v[16:19], v[166:169], v[198:201], v[16:19]
	v_mfma_f32_16x16x32_bf16 v[8:11], v[174:177], v[198:201], v[8:11]
	v_mfma_f32_16x16x32_bf16 v[4:7], v[166:169], v[206:209], v[4:7]
	v_mfma_f32_16x16x32_bf16 v[0:3], v[174:177], v[206:209], v[0:3]
	s_setprio 0
	s_barrier
	s_add_i32 s17, s17, 2
	s_cmp_gt_u32 s17, 5
	s_mov_b64 s[26:27], s[44:45]
	s_cbranch_scc0 .LBB0_559
	s_and_b64 vcc, exec, s[10:11]
	s_cbranch_vccz .LBB0_562
	s_barrier

; #define PG8_LDA(dst, b, h) do { _Pragma("unroll") for (int m = 0; m < 4; ++m) _Pragma("unroll") for (int k = 0; k < 2; ++k) dst[m][k] = *(const LAS bf16x8*)(lds + PG8_SA(b, h) + aoff + m * 2048 + k * 1024); } while (0)
; #define PG8_LDB(dst, b, h) do { _Pragma("unroll") for (int n = 0; n < 2; ++n) _Pragma("unroll") for (int k = 0; k < 2; ++k) dst[n][k] = *(const LAS bf16x8*)(lds + PG8_SB(b, h) + boff + n * 2048 + k * 1024); } while (0)
; #define PG8_WAIT_V(n) asm volatile("s_waitcnt vmcnt(" #n ")" ::: "memory")
; #define PG8_BAR __builtin_amdgcn_s_barrier()
; template <class Epi, class Addr, bool ALIGN_EPI = true, class Order = StaticOrder>
; __device__ __forceinline__ void gemm_phase(LAS unsigned char* lds, const Gemm g, const Order& S, const Epi& E, const int wid) {
;     ...
;         const bool has_next = S.next(ui + 1, nxt);
;         const char* nA = has_next ? (const char*)g.A + Addr::offA(nxt, g) : cA; const char* nB = has_next ? (const char*)g.Bt + Addr::offB(nxt, g) : cB;
;         for (int t = 0; t < nt; t += 2) {
;             const bool last = (t == nt - 2);
;             const char* a1 = cA + (size_t)(t + 1) * kstep;
;             const char* a2 = last ? nA : cA + (size_t)(t + 2) * kstep; const char* b2 = last ? nB : cB + (size_t)(t + 2) * kstep;
;             const char* a3 = a2 + kstep; const char* b3 = b2 + kstep;
;             PG8_LDB(B0, 0, 0); PG8_LDB(B1, 0, 1); PG8_SCHED; PG8_LDA(At, 0, 0); PG8_STAGE(PG8_SA(1, 1), a1 + hstepA, voffA);
;             PG8_WAIT_V(8); PG8_WAIT_L(0); PG8_BAR; PG8_MMA(0, 0, At, B0); PG8_MMA(0, 1, At, B1); PG8_BAR; PG8_SCHED;
;             PG8_LDA(At, 0, 1); PG8_STAGE(PG8_SB(0, 0), b2, voffB); PG8_STAGE(PG8_SB(0, 1), b2 + hstepB, voffB); PG8_STAGE(PG8_SA(0, 0), a2, voffA);
;             PG8_WAIT_V(8); PG8_WAIT_L(0); PG8_BAR; PG8_MMA(1, 0, At, B0); PG8_MMA(1, 1, At, B1); PG8_BAR; PG8_SCHED;
;             PG8_LDB(B0, 1, 0); PG8_LDB(B1, 1, 1); PG8_SCHED; PG8_LDA(At, 1, 0); PG8_STAGE(PG8_SA(0, 1), a2 + hstepA, voffA);
;             PG8_WAIT_V(8); PG8_WAIT_L(0); PG8_BAR; PG8_MMA(0, 0, At, B0); PG8_MMA(0, 1, At, B1); PG8_BAR; PG8_SCHED;
;             PG8_LDA(At, 1, 1); PG8_STAGE(PG8_SB(1, 0), b3, voffB); PG8_STAGE(PG8_SB(1, 1), b3 + hstepB, voffB); PG8_STAGE(PG8_SA(1, 0), a3, voffA);
;             PG8_WAIT_V(8); PG8_WAIT_L(0); PG8_BAR; PG8_MMA(1, 0, At, B0); PG8_MMA(1, 1, At, B1); PG8_BAR; PG8_SCHED;
.LBB0_636:
	ds_read_b128 v[146:149], v140
	ds_read_b128 v[150:153], v140 offset:1024
	ds_read_b128 v[154:157], v140 offset:2048
	ds_read_b128 v[158:161], v140 offset:3072
	ds_read_b128 v[162:165], v141
	ds_read_b128 v[166:169], v141 offset:1024
	ds_read_b128 v[170:173], v141 offset:2048
	ds_read_b128 v[174:177], v141 offset:3072
	s_add_u32 s46, s44, 0x100
	s_addc_u32 s47, s45, 0
	s_cmp_eq_u32 s89, 28
	s_cselect_b32 s52, s25, s46
	s_cselect_b32 s53, s17, s47
	s_cselect_b32 s50, s27, s87
	s_cselect_b32 s51, s15, s88
	s_add_u32 s48, s52, 0x80
	s_addc_u32 s49, s53, 0
	ds_read_b128 v[178:181], v142
	ds_read_b128 v[182:185], v142 offset:1024
	ds_read_b128 v[186:189], v142 offset:2048
	ds_read_b128 v[190:193], v142 offset:3072
	ds_read_b128 v[194:197], v142 offset:4096
	ds_read_b128 v[198:201], v142 offset:5120
	ds_read_b128 v[202:205], v142 offset:6144
	ds_read_b128 v[206:209], v142 offset:7168
	s_add_u32 s18, s44, 0x80080
	s_addc_u32 s19, s45, 0
	s_mov_b32 s36, m0
	s_mov_b32 m0, s61
	s_nop 0
	global_load_lds_dwordx4 v136, s[18:19]
	s_mov_b32 m0, s62
	s_nop 0
	global_load_lds_dwordx4 v138, s[18:19]
	s_mov_b32 m0, s36
	s_waitcnt vmcnt(8)
	s_waitcnt lgkmcnt(0)
	s_barrier
	s_setprio 1
	s_waitcnt lgkmcnt(7)
	v_mfma_f32_16x16x32_bf16 v[124:127], v[146:149], v[178:181], v[124:127]
	v_mfma_f32_16x16x32_bf16 v[120:123], v[154:157], v[178:181], v[120:123]
	s_waitcnt lgkmcnt(5)
	v_mfma_f32_16x16x32_bf16 v[116:119], v[146:149], v[186:189], v[116:119]
	v_mfma_f32_16x16x32_bf16 v[108:111], v[154:157], v[186:189], v[108:111]
	s_waitcnt lgkmcnt(3)
	v_mfma_f32_16x16x32_bf16 v[100:103], v[146:149], v[194:197], v[100:103]
	v_mfma_f32_16x16x32_bf16 v[92:95], v[154:157], v[194:197], v[92:95]
	s_waitcnt lgkmcnt(1)
	v_mfma_f32_16x16x32_bf16 v[84:87], v[146:149], v[202:205], v[84:87]
	v_mfma_f32_16x16x32_bf16 v[76:79], v[154:157], v[202:205], v[76:79]
	v_mfma_f32_16x16x32_bf16 v[124:127], v[150:153], v[182:185], v[124:127]
	v_mfma_f32_16x16x32_bf16 v[120:123], v[158:161], v[182:185], v[120:123]
	v_mfma_f32_16x16x32_bf16 v[116:119], v[150:153], v[190:193], v[116:119]
	v_mfma_f32_16x16x32_bf16 v[108:111], v[158:161], v[190:193], v[108:111]
	v_mfma_f32_16x16x32_bf16 v[100:103], v[150:153], v[198:201], v[100:103]
	v_mfma_f32_16x16x32_bf16 v[92:95], v[158:161], v[198:201], v[92:95]
	s_waitcnt lgkmcnt(0)
	v_mfma_f32_16x16x32_bf16 v[84:87], v[150:153], v[206:209], v[84:87]
	v_mfma_f32_16x16x32_bf16 v[76:79], v[158:161], v[206:209], v[76:79]
	v_mfma_f32_16x16x32_bf16 v[112:115], v[162:165], v[178:181], v[112:115]
	v_mfma_f32_16x16x32_bf16 v[104:107], v[170:173], v[178:181], v[104:107]
	v_mfma_f32_16x16x32_bf16 v[96:99], v[162:165], v[186:189], v[96:99]
	v_mfma_f32_16x16x32_bf16 v[88:91], v[170:173], v[186:189], v[88:91]
	v_mfma_f32_16x16x32_bf16 v[80:83], v[162:165], v[194:197], v[80:83]
	v_mfma_f32_16x16x32_bf16 v[72:75], v[170:173], v[194:197], v[72:75]
	v_mfma_f32_16x16x32_bf16 v[68:71], v[162:165], v[202:205], v[68:71]
	v_mfma_f32_16x16x32_bf16 v[64:67], v[170:173], v[202:205], v[64:67]
	v_mfma_f32_16x16x32_bf16 v[112:115], v[166:169], v[182:185], v[112:115]
	v_mfma_f32_16x16x32_bf16 v[104:107], v[174:177], v[182:185], v[104:107]
	v_mfma_f32_16x16x32_bf16 v[96:99], v[166:169], v[190:193], v[96:99]
	v_mfma_f32_16x16x32_bf16 v[88:91], v[174:177], v[190:193], v[88:91]
	v_mfma_f32_16x16x32_bf16 v[80:83], v[166:169], v[198:201], v[80:83]
	v_mfma_f32_16x16x32_bf16 v[72:75], v[174:177], v[198:201], v[72:75]
	v_mfma_f32_16x16x32_bf16 v[68:71], v[166:169], v[206:209], v[68:71]
	v_mfma_f32_16x16x32_bf16 v[64:67], v[174:177], v[206:209], v[64:67]
	s_setprio 0
	s_barrier
	ds_read_b128 v[178:181], v142 offset:16384
	ds_read_b128 v[182:185], v142 offset:17408
	ds_read_b128 v[186:189], v142 offset:18432
	ds_read_b128 v[190:193], v142 offset:19456
	ds_read_b128 v[194:197], v142 offset:20480
	ds_read_b128 v[198:201], v142 offset:21504
	ds_read_b128 v[202:205], v142 offset:22528
	ds_read_b128 v[206:209], v142 offset:23552
	s_mov_b32 s18, m0
	s_mov_b32 m0, s31
	s_nop 0
	global_load_lds_dwordx4 v137, s[50:51]
	s_mov_b32 m0, s38
	s_nop 0
	global_load_lds_dwordx4 v139, s[50:51]
	s_mov_b32 m0, s18
	s_add_u32 s18, s50, 0x80000
	s_addc_u32 s19, s51, 0
	s_mov_b32 s36, m0
	s_mov_b32 m0, s39
	s_nop 0
	global_load_lds_dwordx4 v137, s[18:19]
	s_mov_b32 m0, s40
	s_nop 0
	global_load_lds_dwordx4 v139, s[18:19]
	s_mov_b32 m0, s36
	s_mov_b32 s18, m0
	s_mov_b32 m0, s29
	s_nop 0
	global_load_lds_dwordx4 v136, s[52:53]
	s_mov_b32 m0, s41
	s_nop 0
	global_load_lds_dwordx4 v138, s[52:53]
	s_mov_b32 m0, s18
	s_waitcnt vmcnt(8)
	s_waitcnt lgkmcnt(0)
	s_barrier
; #define PG8_LDA(dst, b, h) do { _Pragma("unroll") for (int m = 0; m < 4; ++m) _Pragma("unroll") for (int k = 0; k < 2; ++k) dst[m][k] = *(const LAS bf16x8*)(lds + PG8_SA(b, h) + aoff + m * 2048 + k * 1024); } while (0)
; #define PG8_LDB(dst, b, h) do { _Pragma("unroll") for (int n = 0; n < 2; ++n) _Pragma("unroll") for (int k = 0; k < 2; ++k) dst[n][k] = *(const LAS bf16x8*)(lds + PG8_SB(b, h) + boff + n * 2048 + k * 1024); } while (0)
; #define PG8_MMA(ai, bj, At, Bt) do { __builtin_amdgcn_s_setprio(1); _Pragma("unroll") for (int m = 0; m < 4; ++m) _Pragma("unroll") for (int n = 0; n < 2; ++n) _Pragma("unroll") for (int k = 0; k < 2; ++k) \
;         acc[ai][bj][m][n] = __builtin_amdgcn_mfma_f32_16x16x32_bf16(Bt[n][k], At[m][k], acc[ai][bj][m][n], 0, 0, 0); __builtin_amdgcn_s_setprio(0); } while (0)
; #define PG8_WAIT_V(n) asm volatile("s_waitcnt vmcnt(" #n ")" ::: "memory")
; #define PG8_WAIT_L(n) asm volatile("s_waitcnt lgkmcnt(" #n ")" ::: "memory")
; #define PG8_BAR __builtin_amdgcn_s_barrier()
; #define PG8_SCHED __builtin_amdgcn_sched_barrier(0)
; template <class Epi, class Addr, bool ALIGN_EPI = true, class Order = StaticOrder>
; __device__ __forceinline__ void gemm_phase(LAS unsigned char* lds, const Gemm g, const Order& S, const Epi& E, const int wid) {
;     ...
;             PG8_LDB(B0, 0, 0); PG8_LDB(B1, 0, 1); PG8_SCHED; PG8_LDA(At, 0, 0); PG8_STAGE(PG8_SA(1, 1), a1 + hstepA, voffA);
;             PG8_WAIT_V(8); PG8_WAIT_L(0); PG8_BAR; PG8_MMA(0, 0, At, B0); PG8_MMA(0, 1, At, B1); PG8_BAR; PG8_SCHED;
;             PG8_LDA(At, 0, 1); PG8_STAGE(PG8_SB(0, 0), b2, voffB); PG8_STAGE(PG8_SB(0, 1), b2 + hstepB, voffB); PG8_STAGE(PG8_SA(0, 0), a2, voffA);
;             PG8_WAIT_V(8); PG8_WAIT_L(0); PG8_BAR; PG8_MMA(1, 0, At, B0); PG8_MMA(1, 1, At, B1); PG8_BAR; PG8_SCHED;
;             PG8_LDB(B0, 1, 0); PG8_LDB(B1, 1, 1); PG8_SCHED; PG8_LDA(At, 1, 0); PG8_STAGE(PG8_SA(0, 1), a2 + hstepA, voffA);
;             PG8_WAIT_V(8); PG8_WAIT_L(0); PG8_BAR; PG8_MMA(0, 0, At, B0); PG8_MMA(0, 1, At, B1); PG8_BAR; PG8_SCHED;
;             PG8_LDA(At, 1, 1); PG8_STAGE(PG8_SB(1, 0), b3, voffB); PG8_STAGE(PG8_SB(1, 1), b3 + hstepB, voffB); PG8_STAGE(PG8_SA(1, 0), a3, voffA);
;             PG8_WAIT_V(8); PG8_WAIT_L(0); PG8_BAR; PG8_MMA(1, 0, At, B0); PG8_MMA(1, 1, At, B1); PG8_BAR; PG8_SCHED;
	s_setprio 1
	s_waitcnt lgkmcnt(7)
	v_mfma_f32_16x16x32_bf16 v[60:63], v[146:149], v[178:181], v[60:63]
	v_mfma_f32_16x16x32_bf16 v[56:59], v[154:157], v[178:181], v[56:59]
	s_waitcnt lgkmcnt(5)
	v_mfma_f32_16x16x32_bf16 v[52:55], v[146:149], v[186:189], v[52:55]
	v_mfma_f32_16x16x32_bf16 v[44:47], v[154:157], v[186:189], v[44:47]
	s_waitcnt lgkmcnt(3)
	v_mfma_f32_16x16x32_bf16 v[36:39], v[146:149], v[194:197], v[36:39]
	v_mfma_f32_16x16x32_bf16 v[28:31], v[154:157], v[194:197], v[28:31]
	s_waitcnt lgkmcnt(1)
	v_mfma_f32_16x16x32_bf16 v[20:23], v[146:149], v[202:205], v[20:23]
	v_mfma_f32_16x16x32_bf16 v[12:15], v[154:157], v[202:205], v[12:15]
	v_mfma_f32_16x16x32_bf16 v[60:63], v[150:153], v[182:185], v[60:63]
	v_mfma_f32_16x16x32_bf16 v[56:59], v[158:161], v[182:185], v[56:59]
	v_mfma_f32_16x16x32_bf16 v[52:55], v[150:153], v[190:193], v[52:55]
	v_mfma_f32_16x16x32_bf16 v[44:47], v[158:161], v[190:193], v[44:47]
	v_mfma_f32_16x16x32_bf16 v[36:39], v[150:153], v[198:201], v[36:39]
	v_mfma_f32_16x16x32_bf16 v[28:31], v[158:161], v[198:201], v[28:31]
	s_waitcnt lgkmcnt(0)
	v_mfma_f32_16x16x32_bf16 v[20:23], v[150:153], v[206:209], v[20:23]
	v_mfma_f32_16x16x32_bf16 v[12:15], v[158:161], v[206:209], v[12:15]
	v_mfma_f32_16x16x32_bf16 v[48:51], v[162:165], v[178:181], v[48:51]
	v_mfma_f32_16x16x32_bf16 v[40:43], v[170:173], v[178:181], v[40:43]
	v_mfma_f32_16x16x32_bf16 v[32:35], v[162:165], v[186:189], v[32:35]
	v_mfma_f32_16x16x32_bf16 v[24:27], v[170:173], v[186:189], v[24:27]
	v_mfma_f32_16x16x32_bf16 v[16:19], v[162:165], v[194:197], v[16:19]
	v_mfma_f32_16x16x32_bf16 v[8:11], v[170:173], v[194:197], v[8:11]
	v_mfma_f32_16x16x32_bf16 v[4:7], v[162:165], v[202:205], v[4:7]
	v_mfma_f32_16x16x32_bf16 v[0:3], v[170:173], v[202:205], v[0:3]
	v_mfma_f32_16x16x32_bf16 v[48:51], v[166:169], v[182:185], v[48:51]
	v_mfma_f32_16x16x32_bf16 v[40:43], v[174:177], v[182:185], v[40:43]
	v_mfma_f32_16x16x32_bf16 v[32:35], v[166:169], v[190:193], v[32:35]
	v_mfma_f32_16x16x32_bf16 v[24:27], v[174:177], v[190:193], v[24:27]
	v_mfma_f32_16x16x32_bf16 v[16:19], v[166:169], v[198:201], v[16:19]
	v_mfma_f32_16x16x32_bf16 v[8:11], v[174:177], v[198:201], v[8:11]
	v_mfma_f32_16x16x32_bf16 v[4:7], v[166:169], v[206:209], v[4:7]
	v_mfma_f32_16x16x32_bf16 v[0:3], v[174:177], v[206:209], v[0:3]
	s_setprio 0
	s_barrier
	ds_read_b128 v[146:149], v143
	ds_read_b128 v[150:153], v143 offset:1024
	ds_read_b128 v[154:157], v143 offset:2048
	ds_read_b128 v[158:161], v143 offset:3072
	ds_read_b128 v[162:165], v144
	ds_read_b128 v[166:169], v144 offset:1024
	ds_read_b128 v[170:173], v144 offset:2048
	ds_read_b128 v[174:177], v144 offset:3072
	ds_read_b128 v[178:181], v142 offset:32768
	ds_read_b128 v[182:185], v142 offset:33792
	ds_read_b128 v[186:189], v142 offset:34816
	ds_read_b128 v[190:193], v142 offset:35840
	ds_read_b128 v[194:197], v142 offset:36864
	ds_read_b128 v[198:201], v142 offset:37888
	ds_read_b128 v[202:205], v142 offset:38912
	ds_read_b128 v[206:209], v142 offset:39936
	s_add_u32 s18, s52, 0x80000
	s_addc_u32 s19, s53, 0
	s_mov_b32 s36, m0
	s_mov_b32 m0, s43
	s_nop 0
	global_load_lds_dwordx4 v136, s[18:19]
	s_mov_b32 m0, s54
	s_nop 0
	global_load_lds_dwordx4 v138, s[18:19]
	s_mov_b32 m0, s36
	s_waitcnt vmcnt(8)
	s_waitcnt lgkmcnt(0)
	s_barrier
	s_setprio 1
	s_waitcnt lgkmcnt(7)
	v_mfma_f32_16x16x32_bf16 v[124:127], v[146:149], v[178:181], v[124:127]
	v_mfma_f32_16x16x32_bf16 v[120:123], v[154:157], v[178:181], v[120:123]
	s_waitcnt lgkmcnt(5)
	v_mfma_f32_16x16x32_bf16 v[116:119], v[146:149], v[186:189], v[116:119]
	v_mfma_f32_16x16x32_bf16 v[108:111], v[154:157], v[186:189], v[108:111]
	s_waitcnt lgkmcnt(3)
	v_mfma_f32_16x16x32_bf16 v[100:103], v[146:149], v[194:197], v[100:103]
	v_mfma_f32_16x16x32_bf16 v[92:95], v[154:157], v[194:197], v[92:95]
	s_waitcnt lgkmcnt(1)
	v_mfma_f32_16x16x32_bf16 v[84:87], v[146:149], v[202:205], v[84:87]
	v_mfma_f32_16x16x32_bf16 v[76:79], v[154:157], v[202:205], v[76:79]
	v_mfma_f32_16x16x32_bf16 v[124:127], v[150:153], v[182:185], v[124:127]
	v_mfma_f32_16x16x32_bf16 v[120:123], v[158:161], v[182:185], v[120:123]
	v_mfma_f32_16x16x32_bf16 v[116:119], v[150:153], v[190:193], v[116:119]
	v_mfma_f32_16x16x32_bf16 v[108:111], v[158:161], v[190:193], v[108:111]
	v_mfma_f32_16x16x32_bf16 v[100:103], v[150:153], v[198:201], v[100:103]
	v_mfma_f32_16x16x32_bf16 v[92:95], v[158:161], v[198:201], v[92:95]
	s_waitcnt lgkmcnt(0)
	v_mfma_f32_16x16x32_bf16 v[84:87], v[150:153], v[206:209], v[84:87]
	v_mfma_f32_16x16x32_bf16 v[76:79], v[158:161], v[206:209], v[76:79]
	v_mfma_f32_16x16x32_bf16 v[112:115], v[162:165], v[178:181], v[112:115]
	v_mfma_f32_16x16x32_bf16 v[104:107], v[170:173], v[178:181], v[104:107]
	v_mfma_f32_16x16x32_bf16 v[96:99], v[162:165], v[186:189], v[96:99]
	v_mfma_f32_16x16x32_bf16 v[88:91], v[170:173], v[186:189], v[88:91]
	v_mfma_f32_16x16x32_bf16 v[80:83], v[162:165], v[194:197], v[80:83]
	v_mfma_f32_16x16x32_bf16 v[72:75], v[170:173], v[194:197], v[72:75]
	v_mfma_f32_16x16x32_bf16 v[68:71], v[162:165], v[202:205], v[68:71]
	v_mfma_f32_16x16x32_bf16 v[64:67], v[170:173], v[202:205], v[64:67]
	v_mfma_f32_16x16x32_bf16 v[112:115], v[166:169], v[182:185], v[112:115]
	v_mfma_f32_16x16x32_bf16 v[104:107], v[174:177], v[182:185], v[104:107]
	v_mfma_f32_16x16x32_bf16 v[96:99], v[166:169], v[190:193], v[96:99]
	v_mfma_f32_16x16x32_bf16 v[88:91], v[174:177], v[190:193], v[88:91]
	v_mfma_f32_16x16x32_bf16 v[80:83], v[166:169], v[198:201], v[80:83]
	v_mfma_f32_16x16x32_bf16 v[72:75], v[174:177], v[198:201], v[72:75]
	v_mfma_f32_16x16x32_bf16 v[68:71], v[166:169], v[206:209], v[68:71]
	v_mfma_f32_16x16x32_bf16 v[64:67], v[174:177], v[206:209], v[64:67]
	s_setprio 0
	s_barrier
; #define PG8_LDA(dst, b, h) do { _Pragma("unroll") for (int m = 0; m < 4; ++m) _Pragma("unroll") for (int k = 0; k < 2; ++k) dst[m][k] = *(const LAS bf16x8*)(lds + PG8_SA(b, h) + aoff + m * 2048 + k * 1024); } while (0)
; #define PG8_LDB(dst, b, h) do { _Pragma("unroll") for (int n = 0; n < 2; ++n) _Pragma("unroll") for (int k = 0; k < 2; ++k) dst[n][k] = *(const LAS bf16x8*)(lds + PG8_SB(b, h) + boff + n * 2048 + k * 1024); } while (0)
; #define PG8_MMA(ai, bj, At, Bt) do { __builtin_amdgcn_s_setprio(1); _Pragma("unroll") for (int m = 0; m < 4; ++m) _Pragma("unroll") for (int n = 0; n < 2; ++n) _Pragma("unroll") for (int k = 0; k < 2; ++k) \
;         acc[ai][bj][m][n] = __builtin_amdgcn_mfma_f32_16x16x32_bf16(Bt[n][k], At[m][k], acc[ai][bj][m][n], 0, 0, 0); __builtin_amdgcn_s_setprio(0); } while (0)
; #define PG8_WAIT_V(n) asm volatile("s_waitcnt vmcnt(" #n ")" ::: "memory")
; #define PG8_WAIT_L(n) asm volatile("s_waitcnt lgkmcnt(" #n ")" ::: "memory")
; #define PG8_BAR __builtin_amdgcn_s_barrier()
; #define PG8_SCHED __builtin_amdgcn_sched_barrier(0)
; template <class Epi, class Addr, bool ALIGN_EPI = true, class Order = StaticOrder>
; __device__ __forceinline__ void gemm_phase(LAS unsigned char* lds, const Gemm g, const Order& S, const Epi& E, const int wid) {
;     ...
;             PG8_LDB(B0, 1, 0); PG8_LDB(B1, 1, 1); PG8_SCHED; PG8_LDA(At, 1, 0); PG8_STAGE(PG8_SA(0, 1), a2 + hstepA, voffA);
;             PG8_WAIT_V(8); PG8_WAIT_L(0); PG8_BAR; PG8_MMA(0, 0, At, B0); PG8_MMA(0, 1, At, B1); PG8_BAR; PG8_SCHED;
;             PG8_LDA(At, 1, 1); PG8_STAGE(PG8_SB(1, 0), b3, voffB); PG8_STAGE(PG8_SB(1, 1), b3 + hstepB, voffB); PG8_STAGE(PG8_SA(1, 0), a3, voffA);
;             PG8_WAIT_V(8); PG8_WAIT_L(0); PG8_BAR; PG8_MMA(1, 0, At, B0); PG8_MMA(1, 1, At, B1); PG8_BAR; PG8_SCHED;
;         }
;         if constexpr (ALIGN_EPI) { if (wr == 0) PG8_BAR; }
	ds_read_b128 v[178:181], v142 offset:49152
	ds_read_b128 v[182:185], v142 offset:50176
	ds_read_b128 v[186:189], v142 offset:51200
	ds_read_b128 v[190:193], v142 offset:52224
	ds_read_b128 v[194:197], v142 offset:53248
	ds_read_b128 v[198:201], v142 offset:54272
	ds_read_b128 v[202:205], v142 offset:55296
	ds_read_b128 v[206:209], v142 offset:56320
	s_add_u32 s18, s50, 0x80
	s_addc_u32 s19, s51, 0
	s_mov_b32 s36, m0
	s_mov_b32 m0, s55
	s_nop 0
	global_load_lds_dwordx4 v137, s[18:19]
	s_mov_b32 m0, s56
	s_nop 0
	global_load_lds_dwordx4 v139, s[18:19]
	s_mov_b32 m0, s36
	s_add_u32 s18, s50, 0x80080
	s_addc_u32 s19, s51, 0
	s_mov_b32 s36, m0
	s_mov_b32 m0, s59
	s_nop 0
	global_load_lds_dwordx4 v137, s[18:19]
	s_mov_b32 m0, s60
	s_nop 0
	global_load_lds_dwordx4 v139, s[18:19]
	s_mov_b32 m0, s36
	s_mov_b32 s18, m0
	s_mov_b32 m0, s57
	s_nop 0
	global_load_lds_dwordx4 v136, s[48:49]
	s_mov_b32 m0, s58
	s_nop 0
	global_load_lds_dwordx4 v138, s[48:49]
	s_mov_b32 m0, s18
	s_waitcnt vmcnt(8)
	s_waitcnt lgkmcnt(0)
	s_barrier
	s_setprio 1
	s_waitcnt lgkmcnt(7)
	v_mfma_f32_16x16x32_bf16 v[60:63], v[146:149], v[178:181], v[60:63]
	v_mfma_f32_16x16x32_bf16 v[56:59], v[154:157], v[178:181], v[56:59]
	s_waitcnt lgkmcnt(5)
	v_mfma_f32_16x16x32_bf16 v[52:55], v[146:149], v[186:189], v[52:55]
	v_mfma_f32_16x16x32_bf16 v[44:47], v[154:157], v[186:189], v[44:47]
	s_waitcnt lgkmcnt(3)
	v_mfma_f32_16x16x32_bf16 v[36:39], v[146:149], v[194:197], v[36:39]
	v_mfma_f32_16x16x32_bf16 v[28:31], v[154:157], v[194:197], v[28:31]
	s_waitcnt lgkmcnt(1)
	v_mfma_f32_16x16x32_bf16 v[20:23], v[146:149], v[202:205], v[20:23]
	v_mfma_f32_16x16x32_bf16 v[12:15], v[154:157], v[202:205], v[12:15]
	v_mfma_f32_16x16x32_bf16 v[60:63], v[150:153], v[182:185], v[60:63]
	v_mfma_f32_16x16x32_bf16 v[56:59], v[158:161], v[182:185], v[56:59]
	v_mfma_f32_16x16x32_bf16 v[52:55], v[150:153], v[190:193], v[52:55]
	v_mfma_f32_16x16x32_bf16 v[44:47], v[158:161], v[190:193], v[44:47]
	v_mfma_f32_16x16x32_bf16 v[36:39], v[150:153], v[198:201], v[36:39]
	v_mfma_f32_16x16x32_bf16 v[28:31], v[158:161], v[198:201], v[28:31]
	s_waitcnt lgkmcnt(0)
	v_mfma_f32_16x16x32_bf16 v[20:23], v[150:153], v[206:209], v[20:23]
	v_mfma_f32_16x16x32_bf16 v[12:15], v[158:161], v[206:209], v[12:15]
	v_mfma_f32_16x16x32_bf16 v[48:51], v[162:165], v[178:181], v[48:51]
	v_mfma_f32_16x16x32_bf16 v[40:43], v[170:173], v[178:181], v[40:43]
	v_mfma_f32_16x16x32_bf16 v[32:35], v[162:165], v[186:189], v[32:35]
	v_mfma_f32_16x16x32_bf16 v[24:27], v[170:173], v[186:189], v[24:27]
	v_mfma_f32_16x16x32_bf16 v[16:19], v[162:165], v[194:197], v[16:19]
	v_mfma_f32_16x16x32_bf16 v[8:11], v[170:173], v[194:197], v[8:11]
	v_mfma_f32_16x16x32_bf16 v[4:7], v[162:165], v[202:205], v[4:7]
	v_mfma_f32_16x16x32_bf16 v[0:3], v[170:173], v[202:205], v[0:3]
	v_mfma_f32_16x16x32_bf16 v[48:51], v[166:169], v[182:185], v[48:51]
	v_mfma_f32_16x16x32_bf16 v[40:43], v[174:177], v[182:185], v[40:43]
	v_mfma_f32_16x16x32_bf16 v[32:35], v[166:169], v[190:193], v[32:35]
	v_mfma_f32_16x16x32_bf16 v[24:27], v[174:177], v[190:193], v[24:27]
	v_mfma_f32_16x16x32_bf16 v[16:19], v[166:169], v[198:201], v[16:19]
	v_mfma_f32_16x16x32_bf16 v[8:11], v[174:177], v[198:201], v[8:11]
	v_mfma_f32_16x16x32_bf16 v[4:7], v[166:169], v[206:209], v[4:7]
	v_mfma_f32_16x16x32_bf16 v[0:3], v[174:177], v[206:209], v[0:3]
	s_setprio 0
	s_barrier
	s_add_i32 s89, s89, 2
	s_add_u32 s87, s87, 0x100
	s_addc_u32 s88, s88, 0
	s_cmp_gt_u32 s89, 29
	s_mov_b64 s[44:45], s[46:47]
	s_cbranch_scc0 .LBB0_636
	s_and_b64 vcc, exec, s[8:9]
	s_cbranch_vccz .LBB0_639
	s_barrier

; #define PG8_LDA(dst, b, h) do { _Pragma("unroll") for (int m = 0; m < 4; ++m) _Pragma("unroll") for (int k = 0; k < 2; ++k) dst[m][k] = *(const LAS bf16x8*)(lds + PG8_SA(b, h) + aoff + m * 2048 + k * 1024); } while (0)
; #define PG8_LDB(dst, b, h) do { _Pragma("unroll") for (int n = 0; n < 2; ++n) _Pragma("unroll") for (int k = 0; k < 2; ++k) dst[n][k] = *(const LAS bf16x8*)(lds + PG8_SB(b, h) + boff + n * 2048 + k * 1024); } while (0)
; #define PG8_MMA(ai, bj, At, Bt) do { __builtin_amdgcn_s_setprio(1); _Pragma("unroll") for (int m = 0; m < 4; ++m) _Pragma("unroll") for (int n = 0; n < 2; ++n) _Pragma("unroll") for (int k = 0; k < 2; ++k) \
;         acc[ai][bj][m][n] = __builtin_amdgcn_mfma_f32_16x16x32_bf16(Bt[n][k], At[m][k], acc[ai][bj][m][n], 0, 0, 0); __builtin_amdgcn_s_setprio(0); } while (0)
; template <class Epi, class Addr, bool ALIGN_EPI = true, class Order = StaticOrder>
; __device__ __forceinline__ void gemm_phase(LAS unsigned char* lds, const Gemm g, const Order& S, const Epi& E, const int wid) {
;     ...
;             const bool last = (t == nt - 2);
;             const char* a1 = cA + (size_t)(t + 1) * kstep;
;             const char* a2 = last ? nA : cA + (size_t)(t + 2) * kstep; const char* b2 = last ? nB : cB + (size_t)(t + 2) * kstep;
;             const char* a3 = a2 + kstep; const char* b3 = b2 + kstep;
;             PG8_LDB(B0, 0, 0); PG8_LDB(B1, 0, 1); PG8_SCHED; PG8_LDA(At, 0, 0); PG8_STAGE(PG8_SA(1, 1), a1 + hstepA, voffA);
;             PG8_WAIT_V(8); PG8_WAIT_L(0); PG8_BAR; PG8_MMA(0, 0, At, B0); PG8_MMA(0, 1, At, B1); PG8_BAR; PG8_SCHED;
;             PG8_LDA(At, 0, 1); PG8_STAGE(PG8_SB(0, 0), b2, voffB); PG8_STAGE(PG8_SB(0, 1), b2 + hstepB, voffB); PG8_STAGE(PG8_SA(0, 0), a2, voffA);
;             PG8_WAIT_V(8); PG8_WAIT_L(0); PG8_BAR; PG8_MMA(1, 0, At, B0); PG8_MMA(1, 1, At, B1); PG8_BAR; PG8_SCHED;
;             PG8_LDB(B0, 1, 0); PG8_LDB(B1, 1, 1); PG8_SCHED; PG8_LDA(At, 1, 0); PG8_STAGE(PG8_SA(0, 1), a2 + hstepA, voffA);
;             PG8_WAIT_V(8); PG8_WAIT_L(0); PG8_BAR; PG8_MMA(0, 0, At, B0); PG8_MMA(0, 1, At, B1); PG8_BAR; PG8_SCHED;
;             PG8_LDA(At, 1, 1); PG8_STAGE(PG8_SB(1, 0), b3, voffB); PG8_STAGE(PG8_SB(1, 1), b3 + hstepB, voffB); PG8_STAGE(PG8_SA(1, 0), a3, voffA);
;             PG8_WAIT_V(8); PG8_WAIT_L(0); PG8_BAR; PG8_MMA(1, 0, At, B0); PG8_MMA(1, 1, At, B1); PG8_BAR; PG8_SCHED;
.LBB0_656:
	ds_read_b128 v[146:149], v140
	ds_read_b128 v[150:153], v140 offset:1024
	ds_read_b128 v[154:157], v140 offset:2048
	ds_read_b128 v[158:161], v140 offset:3072
	ds_read_b128 v[162:165], v141
	ds_read_b128 v[166:169], v141 offset:1024
	ds_read_b128 v[170:173], v141 offset:2048
	ds_read_b128 v[174:177], v141 offset:3072
	s_add_u32 s26, s24, 0x100
	s_addc_u32 s27, s25, 0
	s_cmp_eq_u32 s77, 28
	s_cselect_b32 s48, s21, s26
	s_cselect_b32 s49, s13, s27
	s_cselect_b32 s46, s23, s75
	s_cselect_b32 s47, s11, s76
	s_add_u32 s44, s48, 0x80
	s_addc_u32 s45, s49, 0
	ds_read_b128 v[178:181], v142
	ds_read_b128 v[182:185], v142 offset:1024
	ds_read_b128 v[186:189], v142 offset:2048
	ds_read_b128 v[190:193], v142 offset:3072
	ds_read_b128 v[194:197], v142 offset:4096
	ds_read_b128 v[198:201], v142 offset:5120
	ds_read_b128 v[202:205], v142 offset:6144
	ds_read_b128 v[206:209], v142 offset:7168
	s_add_u32 s18, s24, 0x80080
	s_addc_u32 s19, s25, 0
	s_mov_b32 s24, m0
	s_mov_b32 m0, s61
	s_nop 0
	global_load_lds_dwordx4 v136, s[18:19]
	s_mov_b32 m0, s62
	s_nop 0
	global_load_lds_dwordx4 v138, s[18:19]
	s_mov_b32 m0, s24
	s_waitcnt vmcnt(8)
	s_waitcnt lgkmcnt(0)
	s_barrier
	s_setprio 1
	s_waitcnt lgkmcnt(7)
	v_mfma_f32_16x16x32_bf16 v[124:127], v[146:149], v[178:181], v[124:127]
	v_mfma_f32_16x16x32_bf16 v[120:123], v[154:157], v[178:181], v[120:123]
	s_waitcnt lgkmcnt(5)
	v_mfma_f32_16x16x32_bf16 v[116:119], v[146:149], v[186:189], v[116:119]
	v_mfma_f32_16x16x32_bf16 v[108:111], v[154:157], v[186:189], v[108:111]
	s_waitcnt lgkmcnt(3)
	v_mfma_f32_16x16x32_bf16 v[100:103], v[146:149], v[194:197], v[100:103]
	v_mfma_f32_16x16x32_bf16 v[92:95], v[154:157], v[194:197], v[92:95]
	s_waitcnt lgkmcnt(1)
	v_mfma_f32_16x16x32_bf16 v[84:87], v[146:149], v[202:205], v[84:87]
	v_mfma_f32_16x16x32_bf16 v[76:79], v[154:157], v[202:205], v[76:79]
	v_mfma_f32_16x16x32_bf16 v[124:127], v[150:153], v[182:185], v[124:127]
	v_mfma_f32_16x16x32_bf16 v[120:123], v[158:161], v[182:185], v[120:123]
	v_mfma_f32_16x16x32_bf16 v[116:119], v[150:153], v[190:193], v[116:119]
	v_mfma_f32_16x16x32_bf16 v[108:111], v[158:161], v[190:193], v[108:111]
	v_mfma_f32_16x16x32_bf16 v[100:103], v[150:153], v[198:201], v[100:103]
	v_mfma_f32_16x16x32_bf16 v[92:95], v[158:161], v[198:201], v[92:95]
	s_waitcnt lgkmcnt(0)
	v_mfma_f32_16x16x32_bf16 v[84:87], v[150:153], v[206:209], v[84:87]
	v_mfma_f32_16x16x32_bf16 v[76:79], v[158:161], v[206:209], v[76:79]
	v_mfma_f32_16x16x32_bf16 v[112:115], v[162:165], v[178:181], v[112:115]
	v_mfma_f32_16x16x32_bf16 v[104:107], v[170:173], v[178:181], v[104:107]
	v_mfma_f32_16x16x32_bf16 v[96:99], v[162:165], v[186:189], v[96:99]
	v_mfma_f32_16x16x32_bf16 v[88:91], v[170:173], v[186:189], v[88:91]
	v_mfma_f32_16x16x32_bf16 v[80:83], v[162:165], v[194:197], v[80:83]
	v_mfma_f32_16x16x32_bf16 v[72:75], v[170:173], v[194:197], v[72:75]
	v_mfma_f32_16x16x32_bf16 v[68:71], v[162:165], v[202:205], v[68:71]
	v_mfma_f32_16x16x32_bf16 v[64:67], v[170:173], v[202:205], v[64:67]
	v_mfma_f32_16x16x32_bf16 v[112:115], v[166:169], v[182:185], v[112:115]
	v_mfma_f32_16x16x32_bf16 v[104:107], v[174:177], v[182:185], v[104:107]
	v_mfma_f32_16x16x32_bf16 v[96:99], v[166:169], v[190:193], v[96:99]
	v_mfma_f32_16x16x32_bf16 v[88:91], v[174:177], v[190:193], v[88:91]
	v_mfma_f32_16x16x32_bf16 v[80:83], v[166:169], v[198:201], v[80:83]
	v_mfma_f32_16x16x32_bf16 v[72:75], v[174:177], v[198:201], v[72:75]
	v_mfma_f32_16x16x32_bf16 v[68:71], v[166:169], v[206:209], v[68:71]
	v_mfma_f32_16x16x32_bf16 v[64:67], v[174:177], v[206:209], v[64:67]
	s_setprio 0
	s_barrier
	ds_read_b128 v[178:181], v142 offset:16384
	ds_read_b128 v[182:185], v142 offset:17408
	ds_read_b128 v[186:189], v142 offset:18432
	ds_read_b128 v[190:193], v142 offset:19456
	ds_read_b128 v[194:197], v142 offset:20480
	ds_read_b128 v[198:201], v142 offset:21504
	ds_read_b128 v[202:205], v142 offset:22528
	ds_read_b128 v[206:209], v142 offset:23552
	s_mov_b32 s18, m0
	s_mov_b32 m0, s31
	s_nop 0
	global_load_lds_dwordx4 v137, s[46:47]
	s_mov_b32 m0, s38
	s_nop 0
	global_load_lds_dwordx4 v139, s[46:47]
	s_mov_b32 m0, s18
	s_add_u32 s18, s46, 0x80000
	s_addc_u32 s19, s47, 0
	s_mov_b32 s24, m0
	s_mov_b32 m0, s39
	s_nop 0
	global_load_lds_dwordx4 v137, s[18:19]
	s_mov_b32 m0, s40
	s_nop 0
	global_load_lds_dwordx4 v139, s[18:19]
	s_mov_b32 m0, s24
	s_mov_b32 s18, m0
	s_mov_b32 m0, s29
	s_nop 0
	global_load_lds_dwordx4 v136, s[48:49]
	s_mov_b32 m0, s41
	s_nop 0
	global_load_lds_dwordx4 v138, s[48:49]
	s_mov_b32 m0, s18
	s_waitcnt vmcnt(8)
	s_waitcnt lgkmcnt(0)
	s_barrier
; #define PG8_LDA(dst, b, h) do { _Pragma("unroll") for (int m = 0; m < 4; ++m) _Pragma("unroll") for (int k = 0; k < 2; ++k) dst[m][k] = *(const LAS bf16x8*)(lds + PG8_SA(b, h) + aoff + m * 2048 + k * 1024); } while (0)
; #define PG8_LDB(dst, b, h) do { _Pragma("unroll") for (int n = 0; n < 2; ++n) _Pragma("unroll") for (int k = 0; k < 2; ++k) dst[n][k] = *(const LAS bf16x8*)(lds + PG8_SB(b, h) + boff + n * 2048 + k * 1024); } while (0)
; #define PG8_MMA(ai, bj, At, Bt) do { __builtin_amdgcn_s_setprio(1); _Pragma("unroll") for (int m = 0; m < 4; ++m) _Pragma("unroll") for (int n = 0; n < 2; ++n) _Pragma("unroll") for (int k = 0; k < 2; ++k) \
;         acc[ai][bj][m][n] = __builtin_amdgcn_mfma_f32_16x16x32_bf16(Bt[n][k], At[m][k], acc[ai][bj][m][n], 0, 0, 0); __builtin_amdgcn_s_setprio(0); } while (0)
; #define PG8_WAIT_V(n) asm volatile("s_waitcnt vmcnt(" #n ")" ::: "memory")
; #define PG8_WAIT_L(n) asm volatile("s_waitcnt lgkmcnt(" #n ")" ::: "memory")
; #define PG8_BAR __builtin_amdgcn_s_barrier()
; #define PG8_SCHED __builtin_amdgcn_sched_barrier(0)
; template <class Epi, class Addr, bool ALIGN_EPI = true, class Order = StaticOrder>
; __device__ __forceinline__ void gemm_phase(LAS unsigned char* lds, const Gemm g, const Order& S, const Epi& E, const int wid) {
;     ...
;             PG8_LDB(B0, 0, 0); PG8_LDB(B1, 0, 1); PG8_SCHED; PG8_LDA(At, 0, 0); PG8_STAGE(PG8_SA(1, 1), a1 + hstepA, voffA);
;             PG8_WAIT_V(8); PG8_WAIT_L(0); PG8_BAR; PG8_MMA(0, 0, At, B0); PG8_MMA(0, 1, At, B1); PG8_BAR; PG8_SCHED;
;             PG8_LDA(At, 0, 1); PG8_STAGE(PG8_SB(0, 0), b2, voffB); PG8_STAGE(PG8_SB(0, 1), b2 + hstepB, voffB); PG8_STAGE(PG8_SA(0, 0), a2, voffA);
;             PG8_WAIT_V(8); PG8_WAIT_L(0); PG8_BAR; PG8_MMA(1, 0, At, B0); PG8_MMA(1, 1, At, B1); PG8_BAR; PG8_SCHED;
;             PG8_LDB(B0, 1, 0); PG8_LDB(B1, 1, 1); PG8_SCHED; PG8_LDA(At, 1, 0); PG8_STAGE(PG8_SA(0, 1), a2 + hstepA, voffA);
;             PG8_WAIT_V(8); PG8_WAIT_L(0); PG8_BAR; PG8_MMA(0, 0, At, B0); PG8_MMA(0, 1, At, B1); PG8_BAR; PG8_SCHED;
;             PG8_LDA(At, 1, 1); PG8_STAGE(PG8_SB(1, 0), b3, voffB); PG8_STAGE(PG8_SB(1, 1), b3 + hstepB, voffB); PG8_STAGE(PG8_SA(1, 0), a3, voffA);
;             PG8_WAIT_V(8); PG8_WAIT_L(0); PG8_BAR; PG8_MMA(1, 0, At, B0); PG8_MMA(1, 1, At, B1); PG8_BAR; PG8_SCHED;
	s_setprio 1
	s_waitcnt lgkmcnt(7)
	v_mfma_f32_16x16x32_bf16 v[60:63], v[146:149], v[178:181], v[60:63]
	v_mfma_f32_16x16x32_bf16 v[56:59], v[154:157], v[178:181], v[56:59]
	s_waitcnt lgkmcnt(5)
	v_mfma_f32_16x16x32_bf16 v[52:55], v[146:149], v[186:189], v[52:55]
	v_mfma_f32_16x16x32_bf16 v[44:47], v[154:157], v[186:189], v[44:47]
	s_waitcnt lgkmcnt(3)
	v_mfma_f32_16x16x32_bf16 v[36:39], v[146:149], v[194:197], v[36:39]
	v_mfma_f32_16x16x32_bf16 v[28:31], v[154:157], v[194:197], v[28:31]
	s_waitcnt lgkmcnt(1)
	v_mfma_f32_16x16x32_bf16 v[20:23], v[146:149], v[202:205], v[20:23]
	v_mfma_f32_16x16x32_bf16 v[12:15], v[154:157], v[202:205], v[12:15]
	v_mfma_f32_16x16x32_bf16 v[60:63], v[150:153], v[182:185], v[60:63]
	v_mfma_f32_16x16x32_bf16 v[56:59], v[158:161], v[182:185], v[56:59]
	v_mfma_f32_16x16x32_bf16 v[52:55], v[150:153], v[190:193], v[52:55]
	v_mfma_f32_16x16x32_bf16 v[44:47], v[158:161], v[190:193], v[44:47]
	v_mfma_f32_16x16x32_bf16 v[36:39], v[150:153], v[198:201], v[36:39]
	v_mfma_f32_16x16x32_bf16 v[28:31], v[158:161], v[198:201], v[28:31]
	s_waitcnt lgkmcnt(0)
	v_mfma_f32_16x16x32_bf16 v[20:23], v[150:153], v[206:209], v[20:23]
	v_mfma_f32_16x16x32_bf16 v[12:15], v[158:161], v[206:209], v[12:15]
	v_mfma_f32_16x16x32_bf16 v[48:51], v[162:165], v[178:181], v[48:51]
	v_mfma_f32_16x16x32_bf16 v[40:43], v[170:173], v[178:181], v[40:43]
	v_mfma_f32_16x16x32_bf16 v[32:35], v[162:165], v[186:189], v[32:35]
	v_mfma_f32_16x16x32_bf16 v[24:27], v[170:173], v[186:189], v[24:27]
	v_mfma_f32_16x16x32_bf16 v[16:19], v[162:165], v[194:197], v[16:19]
	v_mfma_f32_16x16x32_bf16 v[8:11], v[170:173], v[194:197], v[8:11]
	v_mfma_f32_16x16x32_bf16 v[4:7], v[162:165], v[202:205], v[4:7]
	v_mfma_f32_16x16x32_bf16 v[0:3], v[170:173], v[202:205], v[0:3]
	v_mfma_f32_16x16x32_bf16 v[48:51], v[166:169], v[182:185], v[48:51]
	v_mfma_f32_16x16x32_bf16 v[40:43], v[174:177], v[182:185], v[40:43]
	v_mfma_f32_16x16x32_bf16 v[32:35], v[166:169], v[190:193], v[32:35]
	v_mfma_f32_16x16x32_bf16 v[24:27], v[174:177], v[190:193], v[24:27]
	v_mfma_f32_16x16x32_bf16 v[16:19], v[166:169], v[198:201], v[16:19]
	v_mfma_f32_16x16x32_bf16 v[8:11], v[174:177], v[198:201], v[8:11]
	v_mfma_f32_16x16x32_bf16 v[4:7], v[166:169], v[206:209], v[4:7]
	v_mfma_f32_16x16x32_bf16 v[0:3], v[174:177], v[206:209], v[0:3]
	s_setprio 0
	s_barrier
	ds_read_b128 v[146:149], v143
	ds_read_b128 v[150:153], v143 offset:1024
	ds_read_b128 v[154:157], v143 offset:2048
	ds_read_b128 v[158:161], v143 offset:3072
	ds_read_b128 v[162:165], v144
	ds_read_b128 v[166:169], v144 offset:1024
	ds_read_b128 v[170:173], v144 offset:2048
	ds_read_b128 v[174:177], v144 offset:3072
	ds_read_b128 v[178:181], v142 offset:32768
	ds_read_b128 v[182:185], v142 offset:33792
	ds_read_b128 v[186:189], v142 offset:34816
	ds_read_b128 v[190:193], v142 offset:35840
	ds_read_b128 v[194:197], v142 offset:36864
	ds_read_b128 v[198:201], v142 offset:37888
	ds_read_b128 v[202:205], v142 offset:38912
	ds_read_b128 v[206:209], v142 offset:39936
	s_add_u32 s18, s48, 0x80000
	s_addc_u32 s19, s49, 0
	s_mov_b32 s24, m0
	s_mov_b32 m0, s43
	s_nop 0
	global_load_lds_dwordx4 v136, s[18:19]
	s_mov_b32 m0, s54
	s_nop 0
	global_load_lds_dwordx4 v138, s[18:19]
	s_mov_b32 m0, s24
	s_waitcnt vmcnt(8)
	s_waitcnt lgkmcnt(0)
	s_barrier
	s_setprio 1
	s_waitcnt lgkmcnt(7)
	v_mfma_f32_16x16x32_bf16 v[124:127], v[146:149], v[178:181], v[124:127]
	v_mfma_f32_16x16x32_bf16 v[120:123], v[154:157], v[178:181], v[120:123]
	s_waitcnt lgkmcnt(5)
	v_mfma_f32_16x16x32_bf16 v[116:119], v[146:149], v[186:189], v[116:119]
	v_mfma_f32_16x16x32_bf16 v[108:111], v[154:157], v[186:189], v[108:111]
	s_waitcnt lgkmcnt(3)
	v_mfma_f32_16x16x32_bf16 v[100:103], v[146:149], v[194:197], v[100:103]
	v_mfma_f32_16x16x32_bf16 v[92:95], v[154:157], v[194:197], v[92:95]
	s_waitcnt lgkmcnt(1)
	v_mfma_f32_16x16x32_bf16 v[84:87], v[146:149], v[202:205], v[84:87]
	v_mfma_f32_16x16x32_bf16 v[76:79], v[154:157], v[202:205], v[76:79]
	v_mfma_f32_16x16x32_bf16 v[124:127], v[150:153], v[182:185], v[124:127]
	v_mfma_f32_16x16x32_bf16 v[120:123], v[158:161], v[182:185], v[120:123]
	v_mfma_f32_16x16x32_bf16 v[116:119], v[150:153], v[190:193], v[116:119]
	v_mfma_f32_16x16x32_bf16 v[108:111], v[158:161], v[190:193], v[108:111]
	v_mfma_f32_16x16x32_bf16 v[100:103], v[150:153], v[198:201], v[100:103]
	v_mfma_f32_16x16x32_bf16 v[92:95], v[158:161], v[198:201], v[92:95]
	s_waitcnt lgkmcnt(0)
	v_mfma_f32_16x16x32_bf16 v[84:87], v[150:153], v[206:209], v[84:87]
	v_mfma_f32_16x16x32_bf16 v[76:79], v[158:161], v[206:209], v[76:79]
	v_mfma_f32_16x16x32_bf16 v[112:115], v[162:165], v[178:181], v[112:115]
	v_mfma_f32_16x16x32_bf16 v[104:107], v[170:173], v[178:181], v[104:107]
	v_mfma_f32_16x16x32_bf16 v[96:99], v[162:165], v[186:189], v[96:99]
	v_mfma_f32_16x16x32_bf16 v[88:91], v[170:173], v[186:189], v[88:91]
	v_mfma_f32_16x16x32_bf16 v[80:83], v[162:165], v[194:197], v[80:83]
	v_mfma_f32_16x16x32_bf16 v[72:75], v[170:173], v[194:197], v[72:75]
	v_mfma_f32_16x16x32_bf16 v[68:71], v[162:165], v[202:205], v[68:71]
	v_mfma_f32_16x16x32_bf16 v[64:67], v[170:173], v[202:205], v[64:67]
	v_mfma_f32_16x16x32_bf16 v[112:115], v[166:169], v[182:185], v[112:115]
	v_mfma_f32_16x16x32_bf16 v[104:107], v[174:177], v[182:185], v[104:107]
	v_mfma_f32_16x16x32_bf16 v[96:99], v[166:169], v[190:193], v[96:99]
	v_mfma_f32_16x16x32_bf16 v[88:91], v[174:177], v[190:193], v[88:91]
	v_mfma_f32_16x16x32_bf16 v[80:83], v[166:169], v[198:201], v[80:83]
	v_mfma_f32_16x16x32_bf16 v[72:75], v[174:177], v[198:201], v[72:75]
	v_mfma_f32_16x16x32_bf16 v[68:71], v[166:169], v[206:209], v[68:71]
	v_mfma_f32_16x16x32_bf16 v[64:67], v[174:177], v[206:209], v[64:67]
	s_setprio 0
	s_barrier
; #define PG8_LDA(dst, b, h) do { _Pragma("unroll") for (int m = 0; m < 4; ++m) _Pragma("unroll") for (int k = 0; k < 2; ++k) dst[m][k] = *(const LAS bf16x8*)(lds + PG8_SA(b, h) + aoff + m * 2048 + k * 1024); } while (0)
; #define PG8_LDB(dst, b, h) do { _Pragma("unroll") for (int n = 0; n < 2; ++n) _Pragma("unroll") for (int k = 0; k < 2; ++k) dst[n][k] = *(const LAS bf16x8*)(lds + PG8_SB(b, h) + boff + n * 2048 + k * 1024); } while (0)
; #define PG8_MMA(ai, bj, At, Bt) do { __builtin_amdgcn_s_setprio(1); _Pragma("unroll") for (int m = 0; m < 4; ++m) _Pragma("unroll") for (int n = 0; n < 2; ++n) _Pragma("unroll") for (int k = 0; k < 2; ++k) \
;         acc[ai][bj][m][n] = __builtin_amdgcn_mfma_f32_16x16x32_bf16(Bt[n][k], At[m][k], acc[ai][bj][m][n], 0, 0, 0); __builtin_amdgcn_s_setprio(0); } while (0)
; #define PG8_WAIT_V(n) asm volatile("s_waitcnt vmcnt(" #n ")" ::: "memory")
; #define PG8_WAIT_L(n) asm volatile("s_waitcnt lgkmcnt(" #n ")" ::: "memory")
; #define PG8_BAR __builtin_amdgcn_s_barrier()
; #define PG8_SCHED __builtin_amdgcn_sched_barrier(0)
; template <class Epi, class Addr, bool ALIGN_EPI = true, class Order = StaticOrder>
; __device__ __forceinline__ void gemm_phase(LAS unsigned char* lds, const Gemm g, const Order& S, const Epi& E, const int wid) {
;     ...
;             PG8_LDB(B0, 1, 0); PG8_LDB(B1, 1, 1); PG8_SCHED; PG8_LDA(At, 1, 0); PG8_STAGE(PG8_SA(0, 1), a2 + hstepA, voffA);
;             PG8_WAIT_V(8); PG8_WAIT_L(0); PG8_BAR; PG8_MMA(0, 0, At, B0); PG8_MMA(0, 1, At, B1); PG8_BAR; PG8_SCHED;
;             PG8_LDA(At, 1, 1); PG8_STAGE(PG8_SB(1, 0), b3, voffB); PG8_STAGE(PG8_SB(1, 1), b3 + hstepB, voffB); PG8_STAGE(PG8_SA(1, 0), a3, voffA);
;             PG8_WAIT_V(8); PG8_WAIT_L(0); PG8_BAR; PG8_MMA(1, 0, At, B0); PG8_MMA(1, 1, At, B1); PG8_BAR; PG8_SCHED;
;         }
;         if constexpr (ALIGN_EPI) { if (wr == 0) PG8_BAR; }
	ds_read_b128 v[178:181], v142 offset:49152
	ds_read_b128 v[182:185], v142 offset:50176
	ds_read_b128 v[186:189], v142 offset:51200
	ds_read_b128 v[190:193], v142 offset:52224
	ds_read_b128 v[194:197], v142 offset:53248
	ds_read_b128 v[198:201], v142 offset:54272
	ds_read_b128 v[202:205], v142 offset:55296
	ds_read_b128 v[206:209], v142 offset:56320
	s_add_u32 s18, s46, 0x80
	s_addc_u32 s19, s47, 0
	s_mov_b32 s24, m0
	s_mov_b32 m0, s55
	s_nop 0
	global_load_lds_dwordx4 v137, s[18:19]
	s_mov_b32 m0, s56
	s_nop 0
	global_load_lds_dwordx4 v139, s[18:19]
	s_mov_b32 m0, s24
	s_add_u32 s18, s46, 0x80080
	s_addc_u32 s19, s47, 0
	s_mov_b32 s24, m0
	s_mov_b32 m0, s59
	s_nop 0
	global_load_lds_dwordx4 v137, s[18:19]
	s_mov_b32 m0, s60
	s_nop 0
	global_load_lds_dwordx4 v139, s[18:19]
	s_mov_b32 m0, s24
	s_mov_b32 s18, m0
	s_mov_b32 m0, s57
	s_nop 0
	global_load_lds_dwordx4 v136, s[44:45]
	s_mov_b32 m0, s58
	s_nop 0
	global_load_lds_dwordx4 v138, s[44:45]
	s_mov_b32 m0, s18
	s_waitcnt vmcnt(8)
	s_waitcnt lgkmcnt(0)
	s_barrier
	s_setprio 1
	s_waitcnt lgkmcnt(7)
	v_mfma_f32_16x16x32_bf16 v[60:63], v[146:149], v[178:181], v[60:63]
	v_mfma_f32_16x16x32_bf16 v[56:59], v[154:157], v[178:181], v[56:59]
	s_waitcnt lgkmcnt(5)
	v_mfma_f32_16x16x32_bf16 v[52:55], v[146:149], v[186:189], v[52:55]
	v_mfma_f32_16x16x32_bf16 v[44:47], v[154:157], v[186:189], v[44:47]
	s_waitcnt lgkmcnt(3)
	v_mfma_f32_16x16x32_bf16 v[36:39], v[146:149], v[194:197], v[36:39]
	v_mfma_f32_16x16x32_bf16 v[28:31], v[154:157], v[194:197], v[28:31]
	s_waitcnt lgkmcnt(1)
	v_mfma_f32_16x16x32_bf16 v[20:23], v[146:149], v[202:205], v[20:23]
	v_mfma_f32_16x16x32_bf16 v[12:15], v[154:157], v[202:205], v[12:15]
	v_mfma_f32_16x16x32_bf16 v[60:63], v[150:153], v[182:185], v[60:63]
	v_mfma_f32_16x16x32_bf16 v[56:59], v[158:161], v[182:185], v[56:59]
	v_mfma_f32_16x16x32_bf16 v[52:55], v[150:153], v[190:193], v[52:55]
	v_mfma_f32_16x16x32_bf16 v[44:47], v[158:161], v[190:193], v[44:47]
	v_mfma_f32_16x16x32_bf16 v[36:39], v[150:153], v[198:201], v[36:39]
	v_mfma_f32_16x16x32_bf16 v[28:31], v[158:161], v[198:201], v[28:31]
	s_waitcnt lgkmcnt(0)
	v_mfma_f32_16x16x32_bf16 v[20:23], v[150:153], v[206:209], v[20:23]
	v_mfma_f32_16x16x32_bf16 v[12:15], v[158:161], v[206:209], v[12:15]
	v_mfma_f32_16x16x32_bf16 v[48:51], v[162:165], v[178:181], v[48:51]
	v_mfma_f32_16x16x32_bf16 v[40:43], v[170:173], v[178:181], v[40:43]
	v_mfma_f32_16x16x32_bf16 v[32:35], v[162:165], v[186:189], v[32:35]
	v_mfma_f32_16x16x32_bf16 v[24:27], v[170:173], v[186:189], v[24:27]
	v_mfma_f32_16x16x32_bf16 v[16:19], v[162:165], v[194:197], v[16:19]
	v_mfma_f32_16x16x32_bf16 v[8:11], v[170:173], v[194:197], v[8:11]
	v_mfma_f32_16x16x32_bf16 v[4:7], v[162:165], v[202:205], v[4:7]
	v_mfma_f32_16x16x32_bf16 v[0:3], v[170:173], v[202:205], v[0:3]
	v_mfma_f32_16x16x32_bf16 v[48:51], v[166:169], v[182:185], v[48:51]
	v_mfma_f32_16x16x32_bf16 v[40:43], v[174:177], v[182:185], v[40:43]
	v_mfma_f32_16x16x32_bf16 v[32:35], v[166:169], v[190:193], v[32:35]
	v_mfma_f32_16x16x32_bf16 v[24:27], v[174:177], v[190:193], v[24:27]
	v_mfma_f32_16x16x32_bf16 v[16:19], v[166:169], v[198:201], v[16:19]
	v_mfma_f32_16x16x32_bf16 v[8:11], v[174:177], v[198:201], v[8:11]
	v_mfma_f32_16x16x32_bf16 v[4:7], v[166:169], v[206:209], v[4:7]
	v_mfma_f32_16x16x32_bf16 v[0:3], v[174:177], v[206:209], v[0:3]
	s_setprio 0
	s_barrier
	s_add_i32 s77, s77, 2
	s_add_u32 s75, s75, 0x100
	s_addc_u32 s76, s76, 0
	s_cmp_gt_u32 s77, 29
	s_mov_b64 s[24:25], s[26:27]
	s_cbranch_scc0 .LBB0_656
	s_and_b64 vcc, exec, s[8:9]
	s_cbranch_vccz .LBB0_659
	s_barrier

; #define PG8_LDA(dst, b, h) do { _Pragma("unroll") for (int m = 0; m < 4; ++m) _Pragma("unroll") for (int k = 0; k < 2; ++k) dst[m][k] = *(const LAS bf16x8*)(lds + PG8_SA(b, h) + aoff + m * 2048 + k * 1024); } while (0)
; #define PG8_LDB(dst, b, h) do { _Pragma("unroll") for (int n = 0; n < 2; ++n) _Pragma("unroll") for (int k = 0; k < 2; ++k) dst[n][k] = *(const LAS bf16x8*)(lds + PG8_SB(b, h) + boff + n * 2048 + k * 1024); } while (0)
; #define PG8_MMA(ai, bj, At, Bt) do { __builtin_amdgcn_s_setprio(1); _Pragma("unroll") for (int m = 0; m < 4; ++m) _Pragma("unroll") for (int n = 0; n < 2; ++n) _Pragma("unroll") for (int k = 0; k < 2; ++k) \
;         acc[ai][bj][m][n] = __builtin_amdgcn_mfma_f32_16x16x32_bf16(Bt[n][k], At[m][k], acc[ai][bj][m][n], 0, 0, 0); __builtin_amdgcn_s_setprio(0); } while (0)
; template <class Epi, class Addr, bool ALIGN_EPI = true, class Order = StaticOrder>
; __device__ __forceinline__ void gemm_phase(LAS unsigned char* lds, const Gemm g, const Order& S, const Epi& E, const int wid) {
;     ...
;             const bool last = (t == nt - 2);
;             const char* a1 = cA + (size_t)(t + 1) * kstep;
;             const char* a2 = last ? nA : cA + (size_t)(t + 2) * kstep; const char* b2 = last ? nB : cB + (size_t)(t + 2) * kstep;
;             const char* a3 = a2 + kstep; const char* b3 = b2 + kstep;
;             PG8_LDB(B0, 0, 0); PG8_LDB(B1, 0, 1); PG8_SCHED; PG8_LDA(At, 0, 0); PG8_STAGE(PG8_SA(1, 1), a1 + hstepA, voffA);
;             PG8_WAIT_V(8); PG8_WAIT_L(0); PG8_BAR; PG8_MMA(0, 0, At, B0); PG8_MMA(0, 1, At, B1); PG8_BAR; PG8_SCHED;
;             PG8_LDA(At, 0, 1); PG8_STAGE(PG8_SB(0, 0), b2, voffB); PG8_STAGE(PG8_SB(0, 1), b2 + hstepB, voffB); PG8_STAGE(PG8_SA(0, 0), a2, voffA);
;             PG8_WAIT_V(8); PG8_WAIT_L(0); PG8_BAR; PG8_MMA(1, 0, At, B0); PG8_MMA(1, 1, At, B1); PG8_BAR; PG8_SCHED;
;             PG8_LDB(B0, 1, 0); PG8_LDB(B1, 1, 1); PG8_SCHED; PG8_LDA(At, 1, 0); PG8_STAGE(PG8_SA(0, 1), a2 + hstepA, voffA);
;             PG8_WAIT_V(8); PG8_WAIT_L(0); PG8_BAR; PG8_MMA(0, 0, At, B0); PG8_MMA(0, 1, At, B1); PG8_BAR; PG8_SCHED;
;             PG8_LDA(At, 1, 1); PG8_STAGE(PG8_SB(1, 0), b3, voffB); PG8_STAGE(PG8_SB(1, 1), b3 + hstepB, voffB); PG8_STAGE(PG8_SA(1, 0), a3, voffA);
;             PG8_WAIT_V(8); PG8_WAIT_L(0); PG8_BAR; PG8_MMA(1, 0, At, B0); PG8_MMA(1, 1, At, B1); PG8_BAR; PG8_SCHED;
.LBB0_733:
	ds_read_b128 v[68:71], v164
	ds_read_b128 v[72:75], v164 offset:1024
	ds_read_b128 v[76:79], v164 offset:2048
	ds_read_b128 v[84:87], v164 offset:3072
	ds_read_b128 v[156:159], v165
	ds_read_b128 v[170:173], v165 offset:1024
	ds_read_b128 v[174:177], v165 offset:2048
	ds_read_b128 v[178:181], v165 offset:3072
	s_add_u32 s46, s44, 0x100
	s_addc_u32 s47, s45, 0
	s_cmp_eq_u32 s80, 60
	s_cselect_b32 s52, s25, s46
	s_cselect_b32 s53, s17, s47
	s_cselect_b32 s50, s27, s78
	s_cselect_b32 s51, s15, s79
	s_add_u32 s48, s52, 0x80
	s_addc_u32 s49, s53, 0
	ds_read_b128 v[182:185], v166
	ds_read_b128 v[186:189], v166 offset:1024
	ds_read_b128 v[190:193], v166 offset:2048
	ds_read_b128 v[194:197], v166 offset:3072
	ds_read_b128 v[198:201], v166 offset:4096
	ds_read_b128 v[202:205], v166 offset:5120
	ds_read_b128 v[206:209], v166 offset:6144
	ds_read_b128 v[210:213], v166 offset:7168
	s_add_u32 s18, s44, 0x100080
	s_addc_u32 s19, s45, 0
	s_mov_b32 s36, m0
	s_mov_b32 m0, s68
	s_nop 0
	global_load_lds_dwordx4 v160, s[18:19]
	s_mov_b32 m0, s69
	s_nop 0
	global_load_lds_dwordx4 v162, s[18:19]
	s_mov_b32 m0, s36
	s_waitcnt vmcnt(8)
	s_waitcnt lgkmcnt(0)
	s_barrier
	s_setprio 1
	s_waitcnt lgkmcnt(0)
	v_mfma_f32_16x16x32_bf16 v[140:143], v[68:71], v[182:185], v[140:143]
	v_mfma_f32_16x16x32_bf16 v[136:139], v[76:79], v[182:185], v[136:139]
	v_mfma_f32_16x16x32_bf16 v[124:127], v[68:71], v[190:193], v[124:127]
	v_mfma_f32_16x16x32_bf16 v[120:123], v[76:79], v[190:193], v[120:123]
	v_mfma_f32_16x16x32_bf16 v[108:111], v[68:71], v[198:201], v[108:111]
	v_mfma_f32_16x16x32_bf16 v[104:107], v[76:79], v[198:201], v[104:107]
	v_mfma_f32_16x16x32_bf16 v[92:95], v[68:71], v[206:209], v[92:95]
	v_mfma_f32_16x16x32_bf16 v[88:91], v[76:79], v[206:209], v[88:91]
	v_mfma_f32_16x16x32_bf16 v[140:143], v[72:75], v[186:189], v[140:143]
	v_mfma_f32_16x16x32_bf16 v[136:139], v[84:87], v[186:189], v[136:139]
	v_mfma_f32_16x16x32_bf16 v[124:127], v[72:75], v[194:197], v[124:127]
	v_mfma_f32_16x16x32_bf16 v[120:123], v[84:87], v[194:197], v[120:123]
	v_mfma_f32_16x16x32_bf16 v[108:111], v[72:75], v[202:205], v[108:111]
	v_mfma_f32_16x16x32_bf16 v[104:107], v[84:87], v[202:205], v[104:107]
	v_mfma_f32_16x16x32_bf16 v[92:95], v[72:75], v[210:213], v[92:95]
	v_mfma_f32_16x16x32_bf16 v[88:91], v[84:87], v[210:213], v[88:91]
	v_mfma_f32_16x16x32_bf16 v[132:135], v[156:159], v[182:185], v[132:135]
	v_mfma_f32_16x16x32_bf16 v[128:131], v[174:177], v[182:185], v[128:131]
	v_mfma_f32_16x16x32_bf16 v[116:119], v[156:159], v[190:193], v[116:119]
	v_mfma_f32_16x16x32_bf16 v[112:115], v[174:177], v[190:193], v[112:115]
	v_mfma_f32_16x16x32_bf16 v[100:103], v[156:159], v[198:201], v[100:103]
	v_mfma_f32_16x16x32_bf16 v[96:99], v[174:177], v[198:201], v[96:99]
	v_mfma_f32_16x16x32_bf16 v[80:83], v[156:159], v[206:209], v[80:83]
	v_mfma_f32_16x16x32_bf16 v[64:67], v[174:177], v[206:209], v[64:67]
	v_mfma_f32_16x16x32_bf16 v[132:135], v[170:173], v[186:189], v[132:135]
	v_mfma_f32_16x16x32_bf16 v[128:131], v[178:181], v[186:189], v[128:131]
	v_mfma_f32_16x16x32_bf16 v[116:119], v[170:173], v[194:197], v[116:119]
	v_mfma_f32_16x16x32_bf16 v[112:115], v[178:181], v[194:197], v[112:115]
	v_mfma_f32_16x16x32_bf16 v[100:103], v[170:173], v[202:205], v[100:103]
	v_mfma_f32_16x16x32_bf16 v[96:99], v[178:181], v[202:205], v[96:99]
	v_mfma_f32_16x16x32_bf16 v[80:83], v[170:173], v[210:213], v[80:83]
	v_mfma_f32_16x16x32_bf16 v[64:67], v[178:181], v[210:213], v[64:67]
	s_setprio 0
	s_barrier
	ds_read_b128 v[182:185], v166 offset:16384
	ds_read_b128 v[186:189], v166 offset:17408
	ds_read_b128 v[190:193], v166 offset:18432
	ds_read_b128 v[194:197], v166 offset:19456
	ds_read_b128 v[198:201], v166 offset:20480
	ds_read_b128 v[202:205], v166 offset:21504
	ds_read_b128 v[206:209], v166 offset:22528
	ds_read_b128 v[210:213], v166 offset:23552
	s_mov_b32 s18, m0
	s_mov_b32 m0, s43
	s_nop 0
	global_load_lds_dwordx4 v161, s[50:51]
	s_mov_b32 m0, s54
	s_nop 0
	global_load_lds_dwordx4 v163, s[50:51]
	s_mov_b32 m0, s18
	s_add_u32 s18, s50, 0x100000
	s_addc_u32 s19, s51, 0
	s_mov_b32 s36, m0
	s_mov_b32 m0, s55
	s_nop 0
	global_load_lds_dwordx4 v161, s[18:19]
	s_mov_b32 m0, s56
	s_nop 0
	global_load_lds_dwordx4 v163, s[18:19]
	s_mov_b32 m0, s36
	s_mov_b32 s18, m0
	s_mov_b32 m0, s41
	s_nop 0
	global_load_lds_dwordx4 v160, s[52:53]
	s_mov_b32 m0, s57
	s_nop 0
	global_load_lds_dwordx4 v162, s[52:53]
	s_mov_b32 m0, s18
	s_waitcnt vmcnt(8)
	s_waitcnt lgkmcnt(0)
	s_barrier
	s_setprio 1
	s_waitcnt lgkmcnt(7)
	v_mfma_f32_16x16x32_bf16 v[60:63], v[68:71], v[182:185], v[60:63]
	v_mfma_f32_16x16x32_bf16 v[56:59], v[76:79], v[182:185], v[56:59]
	s_waitcnt lgkmcnt(5)
	v_mfma_f32_16x16x32_bf16 v[44:47], v[68:71], v[190:193], v[44:47]
	v_mfma_f32_16x16x32_bf16 v[40:43], v[76:79], v[190:193], v[40:43]
	s_waitcnt lgkmcnt(3)
	v_mfma_f32_16x16x32_bf16 v[28:31], v[68:71], v[198:201], v[28:31]
	v_mfma_f32_16x16x32_bf16 v[24:27], v[76:79], v[198:201], v[24:27]
	s_waitcnt lgkmcnt(1)
	v_mfma_f32_16x16x32_bf16 v[12:15], v[68:71], v[206:209], v[12:15]
	v_mfma_f32_16x16x32_bf16 v[8:11], v[76:79], v[206:209], v[8:11]
	v_mfma_f32_16x16x32_bf16 v[60:63], v[72:75], v[186:189], v[60:63]
	v_mfma_f32_16x16x32_bf16 v[56:59], v[84:87], v[186:189], v[56:59]
	v_mfma_f32_16x16x32_bf16 v[44:47], v[72:75], v[194:197], v[44:47]
	v_mfma_f32_16x16x32_bf16 v[40:43], v[84:87], v[194:197], v[40:43]
	v_mfma_f32_16x16x32_bf16 v[28:31], v[72:75], v[202:205], v[28:31]
	v_mfma_f32_16x16x32_bf16 v[24:27], v[84:87], v[202:205], v[24:27]
	s_waitcnt lgkmcnt(0)
	v_mfma_f32_16x16x32_bf16 v[12:15], v[72:75], v[210:213], v[12:15]
	v_mfma_f32_16x16x32_bf16 v[8:11], v[84:87], v[210:213], v[8:11]
	v_mfma_f32_16x16x32_bf16 v[52:55], v[156:159], v[182:185], v[52:55]
	v_mfma_f32_16x16x32_bf16 v[48:51], v[174:177], v[182:185], v[48:51]
	v_mfma_f32_16x16x32_bf16 v[36:39], v[156:159], v[190:193], v[36:39]
	v_mfma_f32_16x16x32_bf16 v[32:35], v[174:177], v[190:193], v[32:35]
	v_mfma_f32_16x16x32_bf16 v[20:23], v[156:159], v[198:201], v[20:23]
	v_mfma_f32_16x16x32_bf16 v[16:19], v[174:177], v[198:201], v[16:19]
	v_mfma_f32_16x16x32_bf16 v[4:7], v[156:159], v[206:209], v[4:7]
	v_mfma_f32_16x16x32_bf16 v[0:3], v[174:177], v[206:209], v[0:3]
	v_mfma_f32_16x16x32_bf16 v[52:55], v[170:173], v[186:189], v[52:55]
	v_mfma_f32_16x16x32_bf16 v[48:51], v[178:181], v[186:189], v[48:51]
	v_mfma_f32_16x16x32_bf16 v[36:39], v[170:173], v[194:197], v[36:39]
	v_mfma_f32_16x16x32_bf16 v[32:35], v[178:181], v[194:197], v[32:35]
	v_mfma_f32_16x16x32_bf16 v[20:23], v[170:173], v[202:205], v[20:23]
	v_mfma_f32_16x16x32_bf16 v[16:19], v[178:181], v[202:205], v[16:19]
	v_mfma_f32_16x16x32_bf16 v[4:7], v[170:173], v[210:213], v[4:7]
	v_mfma_f32_16x16x32_bf16 v[0:3], v[178:181], v[210:213], v[0:3]
	s_setprio 0
	s_barrier
; #define PG8_LDA(dst, b, h) do { _Pragma("unroll") for (int m = 0; m < 4; ++m) _Pragma("unroll") for (int k = 0; k < 2; ++k) dst[m][k] = *(const LAS bf16x8*)(lds + PG8_SA(b, h) + aoff + m * 2048 + k * 1024); } while (0)
; #define PG8_LDB(dst, b, h) do { _Pragma("unroll") for (int n = 0; n < 2; ++n) _Pragma("unroll") for (int k = 0; k < 2; ++k) dst[n][k] = *(const LAS bf16x8*)(lds + PG8_SB(b, h) + boff + n * 2048 + k * 1024); } while (0)
; #define PG8_MMA(ai, bj, At, Bt) do { __builtin_amdgcn_s_setprio(1); _Pragma("unroll") for (int m = 0; m < 4; ++m) _Pragma("unroll") for (int n = 0; n < 2; ++n) _Pragma("unroll") for (int k = 0; k < 2; ++k) \
;         acc[ai][bj][m][n] = __builtin_amdgcn_mfma_f32_16x16x32_bf16(Bt[n][k], At[m][k], acc[ai][bj][m][n], 0, 0, 0); __builtin_amdgcn_s_setprio(0); } while (0)
; #define PG8_WAIT_V(n) asm volatile("s_waitcnt vmcnt(" #n ")" ::: "memory")
; #define PG8_WAIT_L(n) asm volatile("s_waitcnt lgkmcnt(" #n ")" ::: "memory")
; #define PG8_BAR __builtin_amdgcn_s_barrier()
; #define PG8_SCHED __builtin_amdgcn_sched_barrier(0)
; template <class Epi, class Addr, bool ALIGN_EPI = true, class Order = StaticOrder>
; __device__ __forceinline__ void gemm_phase(LAS unsigned char* lds, const Gemm g, const Order& S, const Epi& E, const int wid) {
;     ...
;             PG8_LDB(B0, 1, 0); PG8_LDB(B1, 1, 1); PG8_SCHED; PG8_LDA(At, 1, 0); PG8_STAGE(PG8_SA(0, 1), a2 + hstepA, voffA);
;             PG8_WAIT_V(8); PG8_WAIT_L(0); PG8_BAR; PG8_MMA(0, 0, At, B0); PG8_MMA(0, 1, At, B1); PG8_BAR; PG8_SCHED;
;             PG8_LDA(At, 1, 1); PG8_STAGE(PG8_SB(1, 0), b3, voffB); PG8_STAGE(PG8_SB(1, 1), b3 + hstepB, voffB); PG8_STAGE(PG8_SA(1, 0), a3, voffA);
;             PG8_WAIT_V(8); PG8_WAIT_L(0); PG8_BAR; PG8_MMA(1, 0, At, B0); PG8_MMA(1, 1, At, B1); PG8_BAR; PG8_SCHED;
;         }
;         if constexpr (ALIGN_EPI) { if (wr == 0) PG8_BAR; }
	ds_read_b128 v[68:71], v167
	ds_read_b128 v[72:75], v167 offset:1024
	ds_read_b128 v[76:79], v167 offset:2048
	ds_read_b128 v[84:87], v167 offset:3072
	ds_read_b128 v[156:159], v168
	ds_read_b128 v[170:173], v168 offset:1024
	ds_read_b128 v[174:177], v168 offset:2048
	ds_read_b128 v[178:181], v168 offset:3072
	ds_read_b128 v[182:185], v166 offset:32768
	ds_read_b128 v[186:189], v166 offset:33792
	ds_read_b128 v[190:193], v166 offset:34816
	ds_read_b128 v[194:197], v166 offset:35840
	ds_read_b128 v[198:201], v166 offset:36864
	ds_read_b128 v[202:205], v166 offset:37888
	ds_read_b128 v[206:209], v166 offset:38912
	ds_read_b128 v[210:213], v166 offset:39936
	s_add_u32 s18, s52, 0x100000
	s_addc_u32 s19, s53, 0
	s_mov_b32 s36, m0
	s_mov_b32 m0, s59
	s_nop 0
	global_load_lds_dwordx4 v160, s[18:19]
	s_mov_b32 m0, s60
	s_nop 0
	global_load_lds_dwordx4 v162, s[18:19]
	s_mov_b32 m0, s36
	s_waitcnt vmcnt(8)
	s_waitcnt lgkmcnt(0)
	s_barrier
	s_setprio 1
	s_waitcnt lgkmcnt(7)
	v_mfma_f32_16x16x32_bf16 v[140:143], v[68:71], v[182:185], v[140:143]
	v_mfma_f32_16x16x32_bf16 v[136:139], v[76:79], v[182:185], v[136:139]
	s_waitcnt lgkmcnt(5)
	v_mfma_f32_16x16x32_bf16 v[124:127], v[68:71], v[190:193], v[124:127]
	v_mfma_f32_16x16x32_bf16 v[120:123], v[76:79], v[190:193], v[120:123]
	s_waitcnt lgkmcnt(3)
	v_mfma_f32_16x16x32_bf16 v[108:111], v[68:71], v[198:201], v[108:111]
	v_mfma_f32_16x16x32_bf16 v[104:107], v[76:79], v[198:201], v[104:107]
	s_waitcnt lgkmcnt(1)
	v_mfma_f32_16x16x32_bf16 v[92:95], v[68:71], v[206:209], v[92:95]
	v_mfma_f32_16x16x32_bf16 v[88:91], v[76:79], v[206:209], v[88:91]
	v_mfma_f32_16x16x32_bf16 v[140:143], v[72:75], v[186:189], v[140:143]
	v_mfma_f32_16x16x32_bf16 v[136:139], v[84:87], v[186:189], v[136:139]
	v_mfma_f32_16x16x32_bf16 v[124:127], v[72:75], v[194:197], v[124:127]
	v_mfma_f32_16x16x32_bf16 v[120:123], v[84:87], v[194:197], v[120:123]
	v_mfma_f32_16x16x32_bf16 v[108:111], v[72:75], v[202:205], v[108:111]
	v_mfma_f32_16x16x32_bf16 v[104:107], v[84:87], v[202:205], v[104:107]
	s_waitcnt lgkmcnt(0)
	v_mfma_f32_16x16x32_bf16 v[92:95], v[72:75], v[210:213], v[92:95]
	v_mfma_f32_16x16x32_bf16 v[88:91], v[84:87], v[210:213], v[88:91]
	v_mfma_f32_16x16x32_bf16 v[132:135], v[156:159], v[182:185], v[132:135]
	v_mfma_f32_16x16x32_bf16 v[128:131], v[174:177], v[182:185], v[128:131]
	v_mfma_f32_16x16x32_bf16 v[116:119], v[156:159], v[190:193], v[116:119]
	v_mfma_f32_16x16x32_bf16 v[112:115], v[174:177], v[190:193], v[112:115]
	v_mfma_f32_16x16x32_bf16 v[100:103], v[156:159], v[198:201], v[100:103]
	v_mfma_f32_16x16x32_bf16 v[96:99], v[174:177], v[198:201], v[96:99]
	v_mfma_f32_16x16x32_bf16 v[80:83], v[156:159], v[206:209], v[80:83]
	v_mfma_f32_16x16x32_bf16 v[64:67], v[174:177], v[206:209], v[64:67]
	v_mfma_f32_16x16x32_bf16 v[132:135], v[170:173], v[186:189], v[132:135]
	v_mfma_f32_16x16x32_bf16 v[128:131], v[178:181], v[186:189], v[128:131]
	v_mfma_f32_16x16x32_bf16 v[116:119], v[170:173], v[194:197], v[116:119]
	v_mfma_f32_16x16x32_bf16 v[112:115], v[178:181], v[194:197], v[112:115]
	v_mfma_f32_16x16x32_bf16 v[100:103], v[170:173], v[202:205], v[100:103]
	v_mfma_f32_16x16x32_bf16 v[96:99], v[178:181], v[202:205], v[96:99]
	v_mfma_f32_16x16x32_bf16 v[80:83], v[170:173], v[210:213], v[80:83]
	v_mfma_f32_16x16x32_bf16 v[64:67], v[178:181], v[210:213], v[64:67]
	s_setprio 0
	s_barrier
	ds_read_b128 v[182:185], v166 offset:49152
	ds_read_b128 v[186:189], v166 offset:50176
	ds_read_b128 v[190:193], v166 offset:51200
	ds_read_b128 v[194:197], v166 offset:52224
	ds_read_b128 v[198:201], v166 offset:53248
	ds_read_b128 v[202:205], v166 offset:54272
	ds_read_b128 v[206:209], v166 offset:55296
	ds_read_b128 v[210:213], v166 offset:56320
	s_add_u32 s18, s50, 0x80
	s_addc_u32 s19, s51, 0
	s_mov_b32 s36, m0
	s_mov_b32 m0, s62
	s_nop 0
	global_load_lds_dwordx4 v161, s[18:19]
	s_mov_b32 m0, s63
	s_nop 0
	global_load_lds_dwordx4 v163, s[18:19]
	s_mov_b32 m0, s36
	s_add_u32 s18, s50, 0x100080
	s_addc_u32 s19, s51, 0
	s_mov_b32 s36, m0
	s_mov_b32 m0, s66
	s_nop 0
	global_load_lds_dwordx4 v161, s[18:19]
	s_mov_b32 m0, s67
	s_nop 0
	global_load_lds_dwordx4 v163, s[18:19]
	s_mov_b32 m0, s36
	s_mov_b32 s18, m0
	s_mov_b32 m0, s64
	s_nop 0
	global_load_lds_dwordx4 v160, s[48:49]
	s_mov_b32 m0, s65
	s_nop 0
	global_load_lds_dwordx4 v162, s[48:49]
	s_mov_b32 m0, s18
	s_waitcnt vmcnt(8)
	s_waitcnt lgkmcnt(0)
	s_barrier
	s_setprio 1
	s_waitcnt lgkmcnt(7)
	v_mfma_f32_16x16x32_bf16 v[60:63], v[68:71], v[182:185], v[60:63]
	v_mfma_f32_16x16x32_bf16 v[56:59], v[76:79], v[182:185], v[56:59]
	s_waitcnt lgkmcnt(5)
	v_mfma_f32_16x16x32_bf16 v[44:47], v[68:71], v[190:193], v[44:47]
	v_mfma_f32_16x16x32_bf16 v[40:43], v[76:79], v[190:193], v[40:43]
	s_waitcnt lgkmcnt(3)
	v_mfma_f32_16x16x32_bf16 v[28:31], v[68:71], v[198:201], v[28:31]
	v_mfma_f32_16x16x32_bf16 v[24:27], v[76:79], v[198:201], v[24:27]
	s_waitcnt lgkmcnt(1)
	v_mfma_f32_16x16x32_bf16 v[12:15], v[68:71], v[206:209], v[12:15]
	v_mfma_f32_16x16x32_bf16 v[8:11], v[76:79], v[206:209], v[8:11]
	v_mfma_f32_16x16x32_bf16 v[60:63], v[72:75], v[186:189], v[60:63]
	v_mfma_f32_16x16x32_bf16 v[56:59], v[84:87], v[186:189], v[56:59]
	v_mfma_f32_16x16x32_bf16 v[44:47], v[72:75], v[194:197], v[44:47]
	v_mfma_f32_16x16x32_bf16 v[40:43], v[84:87], v[194:197], v[40:43]
	v_mfma_f32_16x16x32_bf16 v[28:31], v[72:75], v[202:205], v[28:31]
	v_mfma_f32_16x16x32_bf16 v[24:27], v[84:87], v[202:205], v[24:27]
	s_waitcnt lgkmcnt(0)
	v_mfma_f32_16x16x32_bf16 v[12:15], v[72:75], v[210:213], v[12:15]
	v_mfma_f32_16x16x32_bf16 v[8:11], v[84:87], v[210:213], v[8:11]
	v_mfma_f32_16x16x32_bf16 v[52:55], v[156:159], v[182:185], v[52:55]
	v_mfma_f32_16x16x32_bf16 v[48:51], v[174:177], v[182:185], v[48:51]
	v_mfma_f32_16x16x32_bf16 v[36:39], v[156:159], v[190:193], v[36:39]
	v_mfma_f32_16x16x32_bf16 v[32:35], v[174:177], v[190:193], v[32:35]
	v_mfma_f32_16x16x32_bf16 v[20:23], v[156:159], v[198:201], v[20:23]
	v_mfma_f32_16x16x32_bf16 v[16:19], v[174:177], v[198:201], v[16:19]
	v_mfma_f32_16x16x32_bf16 v[4:7], v[156:159], v[206:209], v[4:7]
	v_mfma_f32_16x16x32_bf16 v[0:3], v[174:177], v[206:209], v[0:3]
	v_mfma_f32_16x16x32_bf16 v[52:55], v[170:173], v[186:189], v[52:55]
	v_mfma_f32_16x16x32_bf16 v[48:51], v[178:181], v[186:189], v[48:51]
	v_mfma_f32_16x16x32_bf16 v[36:39], v[170:173], v[194:197], v[36:39]
	v_mfma_f32_16x16x32_bf16 v[32:35], v[178:181], v[194:197], v[32:35]
	v_mfma_f32_16x16x32_bf16 v[20:23], v[170:173], v[202:205], v[20:23]
	v_mfma_f32_16x16x32_bf16 v[16:19], v[178:181], v[202:205], v[16:19]
	v_mfma_f32_16x16x32_bf16 v[4:7], v[170:173], v[210:213], v[4:7]
	v_mfma_f32_16x16x32_bf16 v[0:3], v[178:181], v[210:213], v[0:3]
	s_setprio 0
	s_barrier
	s_add_i32 s80, s80, 2
	s_add_u32 s78, s78, 0x100
	s_addc_u32 s79, s79, 0
	s_cmp_gt_u32 s80, 61
	s_mov_b64 s[44:45], s[46:47]
	s_cbranch_scc0 .LBB0_733
	s_and_b64 vcc, exec, s[10:11]
	s_cbranch_vccz .LBB0_736
	s_barrier

; #define PG8_LDA(dst, b, h) do { _Pragma("unroll") for (int m = 0; m < 4; ++m) _Pragma("unroll") for (int k = 0; k < 2; ++k) dst[m][k] = *(const LAS bf16x8*)(lds + PG8_SA(b, h) + aoff + m * 2048 + k * 1024); } while (0)
; #define PG8_LDB(dst, b, h) do { _Pragma("unroll") for (int n = 0; n < 2; ++n) _Pragma("unroll") for (int k = 0; k < 2; ++k) dst[n][k] = *(const LAS bf16x8*)(lds + PG8_SB(b, h) + boff + n * 2048 + k * 1024); } while (0)
; #define PG8_MMA(ai, bj, At, Bt) do { __builtin_amdgcn_s_setprio(1); _Pragma("unroll") for (int m = 0; m < 4; ++m) _Pragma("unroll") for (int n = 0; n < 2; ++n) _Pragma("unroll") for (int k = 0; k < 2; ++k) \
;         acc[ai][bj][m][n] = __builtin_amdgcn_mfma_f32_16x16x32_bf16(Bt[n][k], At[m][k], acc[ai][bj][m][n], 0, 0, 0); __builtin_amdgcn_s_setprio(0); } while (0)
; template <class Epi, class Addr, bool ALIGN_EPI = true, class Order = StaticOrder>
; __device__ __forceinline__ void gemm_phase(LAS unsigned char* lds, const Gemm g, const Order& S, const Epi& E, const int wid) {
;     ...
;             const bool last = (t == nt - 2);
;             const char* a1 = cA + (size_t)(t + 1) * kstep;
;             const char* a2 = last ? nA : cA + (size_t)(t + 2) * kstep; const char* b2 = last ? nB : cB + (size_t)(t + 2) * kstep;
;             const char* a3 = a2 + kstep; const char* b3 = b2 + kstep;
;             PG8_LDB(B0, 0, 0); PG8_LDB(B1, 0, 1); PG8_SCHED; PG8_LDA(At, 0, 0); PG8_STAGE(PG8_SA(1, 1), a1 + hstepA, voffA);
;             PG8_WAIT_V(8); PG8_WAIT_L(0); PG8_BAR; PG8_MMA(0, 0, At, B0); PG8_MMA(0, 1, At, B1); PG8_BAR; PG8_SCHED;
;             PG8_LDA(At, 0, 1); PG8_STAGE(PG8_SB(0, 0), b2, voffB); PG8_STAGE(PG8_SB(0, 1), b2 + hstepB, voffB); PG8_STAGE(PG8_SA(0, 0), a2, voffA);
;             PG8_WAIT_V(8); PG8_WAIT_L(0); PG8_BAR; PG8_MMA(1, 0, At, B0); PG8_MMA(1, 1, At, B1); PG8_BAR; PG8_SCHED;
;             PG8_LDB(B0, 1, 0); PG8_LDB(B1, 1, 1); PG8_SCHED; PG8_LDA(At, 1, 0); PG8_STAGE(PG8_SA(0, 1), a2 + hstepA, voffA);
;             PG8_WAIT_V(8); PG8_WAIT_L(0); PG8_BAR; PG8_MMA(0, 0, At, B0); PG8_MMA(0, 1, At, B1); PG8_BAR; PG8_SCHED;
;             PG8_LDA(At, 1, 1); PG8_STAGE(PG8_SB(1, 0), b3, voffB); PG8_STAGE(PG8_SB(1, 1), b3 + hstepB, voffB); PG8_STAGE(PG8_SA(1, 0), a3, voffA);
;             PG8_WAIT_V(8); PG8_WAIT_L(0); PG8_BAR; PG8_MMA(1, 0, At, B0); PG8_MMA(1, 1, At, B1); PG8_BAR; PG8_SCHED;
.LBB0_814:
	ds_read_b128 v[134:137], v160
	ds_read_b128 v[138:141], v160 offset:1024
	ds_read_b128 v[142:145], v160 offset:2048
	ds_read_b128 v[146:149], v160 offset:3072
	ds_read_b128 v[150:153], v161
	ds_read_b128 v[166:169], v161 offset:1024
	ds_read_b128 v[170:173], v161 offset:2048
	ds_read_b128 v[174:177], v161 offset:3072
	s_add_u32 s50, s48, 0x100
	s_addc_u32 s51, s49, 0
	s_cmp_eq_u32 s77, 60
	s_cselect_b32 s56, s45, s50
	s_cselect_b32 s57, s23, s51
	s_cselect_b32 s54, s47, s75
	s_cselect_b32 s55, s21, s76
	s_add_u32 s52, s56, 0x80
	s_addc_u32 s53, s57, 0
	ds_read_b128 v[178:181], v162
	ds_read_b128 v[182:185], v162 offset:1024
	ds_read_b128 v[186:189], v162 offset:2048
	ds_read_b128 v[190:193], v162 offset:3072
	ds_read_b128 v[194:197], v162 offset:4096
	ds_read_b128 v[198:201], v162 offset:5120
	ds_read_b128 v[202:205], v162 offset:6144
	ds_read_b128 v[206:209], v162 offset:7168
	s_add_u32 s18, s48, 0x100080
	s_addc_u32 s19, s49, 0
	s_mov_b32 s36, m0
	s_mov_b32 m0, s72
	s_nop 0
	global_load_lds_dwordx4 v156, s[18:19]
	s_mov_b32 m0, s73
	s_nop 0
	global_load_lds_dwordx4 v157, s[18:19]
	s_mov_b32 m0, s36
	s_waitcnt vmcnt(8)
	s_waitcnt lgkmcnt(0)
	s_barrier
	s_setprio 1
	s_waitcnt lgkmcnt(0)
	v_mfma_f32_16x16x32_bf16 v[124:127], v[134:137], v[178:181], v[124:127]
	v_mfma_f32_16x16x32_bf16 v[120:123], v[142:145], v[178:181], v[120:123]
	v_mfma_f32_16x16x32_bf16 v[108:111], v[134:137], v[186:189], v[108:111]
	v_mfma_f32_16x16x32_bf16 v[104:107], v[142:145], v[186:189], v[104:107]
	v_mfma_f32_16x16x32_bf16 v[92:95], v[134:137], v[194:197], v[92:95]
	v_mfma_f32_16x16x32_bf16 v[88:91], v[142:145], v[194:197], v[88:91]
	v_mfma_f32_16x16x32_bf16 v[76:79], v[134:137], v[202:205], v[76:79]
	v_mfma_f32_16x16x32_bf16 v[72:75], v[142:145], v[202:205], v[72:75]
	v_mfma_f32_16x16x32_bf16 v[124:127], v[138:141], v[182:185], v[124:127]
	v_mfma_f32_16x16x32_bf16 v[120:123], v[146:149], v[182:185], v[120:123]
	v_mfma_f32_16x16x32_bf16 v[108:111], v[138:141], v[190:193], v[108:111]
	v_mfma_f32_16x16x32_bf16 v[104:107], v[146:149], v[190:193], v[104:107]
	v_mfma_f32_16x16x32_bf16 v[92:95], v[138:141], v[198:201], v[92:95]
	v_mfma_f32_16x16x32_bf16 v[88:91], v[146:149], v[198:201], v[88:91]
	v_mfma_f32_16x16x32_bf16 v[76:79], v[138:141], v[206:209], v[76:79]
	v_mfma_f32_16x16x32_bf16 v[72:75], v[146:149], v[206:209], v[72:75]
	v_mfma_f32_16x16x32_bf16 v[116:119], v[150:153], v[178:181], v[116:119]
	v_mfma_f32_16x16x32_bf16 v[112:115], v[170:173], v[178:181], v[112:115]
	v_mfma_f32_16x16x32_bf16 v[100:103], v[150:153], v[186:189], v[100:103]
	v_mfma_f32_16x16x32_bf16 v[96:99], v[170:173], v[186:189], v[96:99]
	v_mfma_f32_16x16x32_bf16 v[84:87], v[150:153], v[194:197], v[84:87]
	v_mfma_f32_16x16x32_bf16 v[80:83], v[170:173], v[194:197], v[80:83]
	v_mfma_f32_16x16x32_bf16 v[68:71], v[150:153], v[202:205], v[68:71]
	v_mfma_f32_16x16x32_bf16 v[64:67], v[170:173], v[202:205], v[64:67]
	v_mfma_f32_16x16x32_bf16 v[116:119], v[166:169], v[182:185], v[116:119]
	v_mfma_f32_16x16x32_bf16 v[112:115], v[174:177], v[182:185], v[112:115]
	v_mfma_f32_16x16x32_bf16 v[100:103], v[166:169], v[190:193], v[100:103]
	v_mfma_f32_16x16x32_bf16 v[96:99], v[174:177], v[190:193], v[96:99]
	v_mfma_f32_16x16x32_bf16 v[84:87], v[166:169], v[198:201], v[84:87]
	v_mfma_f32_16x16x32_bf16 v[80:83], v[174:177], v[198:201], v[80:83]
	v_mfma_f32_16x16x32_bf16 v[68:71], v[166:169], v[206:209], v[68:71]
	v_mfma_f32_16x16x32_bf16 v[64:67], v[174:177], v[206:209], v[64:67]
	s_setprio 0
	s_barrier
	ds_read_b128 v[178:181], v162 offset:16384
	ds_read_b128 v[182:185], v162 offset:17408
	ds_read_b128 v[186:189], v162 offset:18432
	ds_read_b128 v[190:193], v162 offset:19456
	ds_read_b128 v[194:197], v162 offset:20480
	ds_read_b128 v[198:201], v162 offset:21504
	ds_read_b128 v[202:205], v162 offset:22528
	ds_read_b128 v[206:209], v162 offset:23552
	s_mov_b32 s18, m0
	s_mov_b32 m0, s43
	s_nop 0
	global_load_lds_dwordx4 v156, s[54:55]
	s_mov_b32 m0, s58
	s_nop 0
	global_load_lds_dwordx4 v157, s[54:55]
	s_mov_b32 m0, s18
	s_add_u32 s18, s54, 0x100000
	s_addc_u32 s19, s55, 0
	s_mov_b32 s36, m0
	s_mov_b32 m0, s59
	s_nop 0
	global_load_lds_dwordx4 v156, s[18:19]
	s_mov_b32 m0, s60
	s_nop 0
	global_load_lds_dwordx4 v157, s[18:19]
	s_mov_b32 m0, s36
	s_mov_b32 s18, m0
	s_mov_b32 m0, s41
	s_nop 0
	global_load_lds_dwordx4 v156, s[56:57]
	s_mov_b32 m0, s61
	s_nop 0
	global_load_lds_dwordx4 v157, s[56:57]
	s_mov_b32 m0, s18
	s_waitcnt vmcnt(8)
	s_waitcnt lgkmcnt(0)
	s_barrier
; #define PG8_LDA(dst, b, h) do { _Pragma("unroll") for (int m = 0; m < 4; ++m) _Pragma("unroll") for (int k = 0; k < 2; ++k) dst[m][k] = *(const LAS bf16x8*)(lds + PG8_SA(b, h) + aoff + m * 2048 + k * 1024); } while (0)
; #define PG8_LDB(dst, b, h) do { _Pragma("unroll") for (int n = 0; n < 2; ++n) _Pragma("unroll") for (int k = 0; k < 2; ++k) dst[n][k] = *(const LAS bf16x8*)(lds + PG8_SB(b, h) + boff + n * 2048 + k * 1024); } while (0)
; #define PG8_MMA(ai, bj, At, Bt) do { __builtin_amdgcn_s_setprio(1); _Pragma("unroll") for (int m = 0; m < 4; ++m) _Pragma("unroll") for (int n = 0; n < 2; ++n) _Pragma("unroll") for (int k = 0; k < 2; ++k) \
;         acc[ai][bj][m][n] = __builtin_amdgcn_mfma_f32_16x16x32_bf16(Bt[n][k], At[m][k], acc[ai][bj][m][n], 0, 0, 0); __builtin_amdgcn_s_setprio(0); } while (0)
; #define PG8_WAIT_V(n) asm volatile("s_waitcnt vmcnt(" #n ")" ::: "memory")
; #define PG8_WAIT_L(n) asm volatile("s_waitcnt lgkmcnt(" #n ")" ::: "memory")
; #define PG8_BAR __builtin_amdgcn_s_barrier()
; #define PG8_SCHED __builtin_amdgcn_sched_barrier(0)
; template <class Epi, class Addr, bool ALIGN_EPI = true, class Order = StaticOrder>
; __device__ __forceinline__ void gemm_phase(LAS unsigned char* lds, const Gemm g, const Order& S, const Epi& E, const int wid) {
;     ...
;             PG8_LDB(B0, 0, 0); PG8_LDB(B1, 0, 1); PG8_SCHED; PG8_LDA(At, 0, 0); PG8_STAGE(PG8_SA(1, 1), a1 + hstepA, voffA);
;             PG8_WAIT_V(8); PG8_WAIT_L(0); PG8_BAR; PG8_MMA(0, 0, At, B0); PG8_MMA(0, 1, At, B1); PG8_BAR; PG8_SCHED;
;             PG8_LDA(At, 0, 1); PG8_STAGE(PG8_SB(0, 0), b2, voffB); PG8_STAGE(PG8_SB(0, 1), b2 + hstepB, voffB); PG8_STAGE(PG8_SA(0, 0), a2, voffA);
;             PG8_WAIT_V(8); PG8_WAIT_L(0); PG8_BAR; PG8_MMA(1, 0, At, B0); PG8_MMA(1, 1, At, B1); PG8_BAR; PG8_SCHED;
;             PG8_LDB(B0, 1, 0); PG8_LDB(B1, 1, 1); PG8_SCHED; PG8_LDA(At, 1, 0); PG8_STAGE(PG8_SA(0, 1), a2 + hstepA, voffA);
;             PG8_WAIT_V(8); PG8_WAIT_L(0); PG8_BAR; PG8_MMA(0, 0, At, B0); PG8_MMA(0, 1, At, B1); PG8_BAR; PG8_SCHED;
;             PG8_LDA(At, 1, 1); PG8_STAGE(PG8_SB(1, 0), b3, voffB); PG8_STAGE(PG8_SB(1, 1), b3 + hstepB, voffB); PG8_STAGE(PG8_SA(1, 0), a3, voffA);
;             PG8_WAIT_V(8); PG8_WAIT_L(0); PG8_BAR; PG8_MMA(1, 0, At, B0); PG8_MMA(1, 1, At, B1); PG8_BAR; PG8_SCHED;
	s_setprio 1
	s_waitcnt lgkmcnt(7)
	v_mfma_f32_16x16x32_bf16 v[60:63], v[134:137], v[178:181], v[60:63]
	v_mfma_f32_16x16x32_bf16 v[56:59], v[142:145], v[178:181], v[56:59]
	s_waitcnt lgkmcnt(5)
	v_mfma_f32_16x16x32_bf16 v[44:47], v[134:137], v[186:189], v[44:47]
	v_mfma_f32_16x16x32_bf16 v[40:43], v[142:145], v[186:189], v[40:43]
	s_waitcnt lgkmcnt(3)
	v_mfma_f32_16x16x32_bf16 v[28:31], v[134:137], v[194:197], v[28:31]
	v_mfma_f32_16x16x32_bf16 v[24:27], v[142:145], v[194:197], v[24:27]
	s_waitcnt lgkmcnt(1)
	v_mfma_f32_16x16x32_bf16 v[12:15], v[134:137], v[202:205], v[12:15]
	v_mfma_f32_16x16x32_bf16 v[8:11], v[142:145], v[202:205], v[8:11]
	v_mfma_f32_16x16x32_bf16 v[60:63], v[138:141], v[182:185], v[60:63]
	v_mfma_f32_16x16x32_bf16 v[56:59], v[146:149], v[182:185], v[56:59]
	v_mfma_f32_16x16x32_bf16 v[44:47], v[138:141], v[190:193], v[44:47]
	v_mfma_f32_16x16x32_bf16 v[40:43], v[146:149], v[190:193], v[40:43]
	v_mfma_f32_16x16x32_bf16 v[28:31], v[138:141], v[198:201], v[28:31]
	v_mfma_f32_16x16x32_bf16 v[24:27], v[146:149], v[198:201], v[24:27]
	s_waitcnt lgkmcnt(0)
	v_mfma_f32_16x16x32_bf16 v[12:15], v[138:141], v[206:209], v[12:15]
	v_mfma_f32_16x16x32_bf16 v[8:11], v[146:149], v[206:209], v[8:11]
	v_mfma_f32_16x16x32_bf16 v[52:55], v[150:153], v[178:181], v[52:55]
	v_mfma_f32_16x16x32_bf16 v[48:51], v[170:173], v[178:181], v[48:51]
	v_mfma_f32_16x16x32_bf16 v[36:39], v[150:153], v[186:189], v[36:39]
	v_mfma_f32_16x16x32_bf16 v[32:35], v[170:173], v[186:189], v[32:35]
	v_mfma_f32_16x16x32_bf16 v[20:23], v[150:153], v[194:197], v[20:23]
	v_mfma_f32_16x16x32_bf16 v[16:19], v[170:173], v[194:197], v[16:19]
	v_mfma_f32_16x16x32_bf16 v[4:7], v[150:153], v[202:205], v[4:7]
	v_mfma_f32_16x16x32_bf16 v[0:3], v[170:173], v[202:205], v[0:3]
	v_mfma_f32_16x16x32_bf16 v[52:55], v[166:169], v[182:185], v[52:55]
	v_mfma_f32_16x16x32_bf16 v[48:51], v[174:177], v[182:185], v[48:51]
	v_mfma_f32_16x16x32_bf16 v[36:39], v[166:169], v[190:193], v[36:39]
	v_mfma_f32_16x16x32_bf16 v[32:35], v[174:177], v[190:193], v[32:35]
	v_mfma_f32_16x16x32_bf16 v[20:23], v[166:169], v[198:201], v[20:23]
	v_mfma_f32_16x16x32_bf16 v[16:19], v[174:177], v[198:201], v[16:19]
	v_mfma_f32_16x16x32_bf16 v[4:7], v[166:169], v[206:209], v[4:7]
	v_mfma_f32_16x16x32_bf16 v[0:3], v[174:177], v[206:209], v[0:3]
	s_setprio 0
	s_barrier
	ds_read_b128 v[134:137], v163
	ds_read_b128 v[138:141], v163 offset:1024
	ds_read_b128 v[142:145], v163 offset:2048
	ds_read_b128 v[146:149], v163 offset:3072
	ds_read_b128 v[150:153], v164
	ds_read_b128 v[166:169], v164 offset:1024
	ds_read_b128 v[170:173], v164 offset:2048
	ds_read_b128 v[174:177], v164 offset:3072
	ds_read_b128 v[178:181], v162 offset:32768
	ds_read_b128 v[182:185], v162 offset:33792
	ds_read_b128 v[186:189], v162 offset:34816
	ds_read_b128 v[190:193], v162 offset:35840
	ds_read_b128 v[194:197], v162 offset:36864
	ds_read_b128 v[198:201], v162 offset:37888
	ds_read_b128 v[202:205], v162 offset:38912
	ds_read_b128 v[206:209], v162 offset:39936
	s_add_u32 s18, s56, 0x100000
	s_addc_u32 s19, s57, 0
	s_mov_b32 s36, m0
	s_mov_b32 m0, s62
	s_nop 0
	global_load_lds_dwordx4 v156, s[18:19]
	s_mov_b32 m0, s63
	s_nop 0
	global_load_lds_dwordx4 v157, s[18:19]
	s_mov_b32 m0, s36
	s_waitcnt vmcnt(8)
	s_waitcnt lgkmcnt(0)
	s_barrier
	s_setprio 1
	s_waitcnt lgkmcnt(7)
	v_mfma_f32_16x16x32_bf16 v[124:127], v[134:137], v[178:181], v[124:127]
	v_mfma_f32_16x16x32_bf16 v[120:123], v[142:145], v[178:181], v[120:123]
	s_waitcnt lgkmcnt(5)
	v_mfma_f32_16x16x32_bf16 v[108:111], v[134:137], v[186:189], v[108:111]
	v_mfma_f32_16x16x32_bf16 v[104:107], v[142:145], v[186:189], v[104:107]
	s_waitcnt lgkmcnt(3)
	v_mfma_f32_16x16x32_bf16 v[92:95], v[134:137], v[194:197], v[92:95]
	v_mfma_f32_16x16x32_bf16 v[88:91], v[142:145], v[194:197], v[88:91]
	s_waitcnt lgkmcnt(1)
	v_mfma_f32_16x16x32_bf16 v[76:79], v[134:137], v[202:205], v[76:79]
	v_mfma_f32_16x16x32_bf16 v[72:75], v[142:145], v[202:205], v[72:75]
	v_mfma_f32_16x16x32_bf16 v[124:127], v[138:141], v[182:185], v[124:127]
	v_mfma_f32_16x16x32_bf16 v[120:123], v[146:149], v[182:185], v[120:123]
	v_mfma_f32_16x16x32_bf16 v[108:111], v[138:141], v[190:193], v[108:111]
	v_mfma_f32_16x16x32_bf16 v[104:107], v[146:149], v[190:193], v[104:107]
	v_mfma_f32_16x16x32_bf16 v[92:95], v[138:141], v[198:201], v[92:95]
	v_mfma_f32_16x16x32_bf16 v[88:91], v[146:149], v[198:201], v[88:91]
	s_waitcnt lgkmcnt(0)
	v_mfma_f32_16x16x32_bf16 v[76:79], v[138:141], v[206:209], v[76:79]
	v_mfma_f32_16x16x32_bf16 v[72:75], v[146:149], v[206:209], v[72:75]
	v_mfma_f32_16x16x32_bf16 v[116:119], v[150:153], v[178:181], v[116:119]
	v_mfma_f32_16x16x32_bf16 v[112:115], v[170:173], v[178:181], v[112:115]
	v_mfma_f32_16x16x32_bf16 v[100:103], v[150:153], v[186:189], v[100:103]
	v_mfma_f32_16x16x32_bf16 v[96:99], v[170:173], v[186:189], v[96:99]
	v_mfma_f32_16x16x32_bf16 v[84:87], v[150:153], v[194:197], v[84:87]
	v_mfma_f32_16x16x32_bf16 v[80:83], v[170:173], v[194:197], v[80:83]
	v_mfma_f32_16x16x32_bf16 v[68:71], v[150:153], v[202:205], v[68:71]
	v_mfma_f32_16x16x32_bf16 v[64:67], v[170:173], v[202:205], v[64:67]
	v_mfma_f32_16x16x32_bf16 v[116:119], v[166:169], v[182:185], v[116:119]
	v_mfma_f32_16x16x32_bf16 v[112:115], v[174:177], v[182:185], v[112:115]
	v_mfma_f32_16x16x32_bf16 v[100:103], v[166:169], v[190:193], v[100:103]
	v_mfma_f32_16x16x32_bf16 v[96:99], v[174:177], v[190:193], v[96:99]
	v_mfma_f32_16x16x32_bf16 v[84:87], v[166:169], v[198:201], v[84:87]
	v_mfma_f32_16x16x32_bf16 v[80:83], v[174:177], v[198:201], v[80:83]
	v_mfma_f32_16x16x32_bf16 v[68:71], v[166:169], v[206:209], v[68:71]
	v_mfma_f32_16x16x32_bf16 v[64:67], v[174:177], v[206:209], v[64:67]
	s_setprio 0
	s_barrier
; #define PG8_LDA(dst, b, h) do { _Pragma("unroll") for (int m = 0; m < 4; ++m) _Pragma("unroll") for (int k = 0; k < 2; ++k) dst[m][k] = *(const LAS bf16x8*)(lds + PG8_SA(b, h) + aoff + m * 2048 + k * 1024); } while (0)
; #define PG8_LDB(dst, b, h) do { _Pragma("unroll") for (int n = 0; n < 2; ++n) _Pragma("unroll") for (int k = 0; k < 2; ++k) dst[n][k] = *(const LAS bf16x8*)(lds + PG8_SB(b, h) + boff + n * 2048 + k * 1024); } while (0)
; #define PG8_MMA(ai, bj, At, Bt) do { __builtin_amdgcn_s_setprio(1); _Pragma("unroll") for (int m = 0; m < 4; ++m) _Pragma("unroll") for (int n = 0; n < 2; ++n) _Pragma("unroll") for (int k = 0; k < 2; ++k) \
;         acc[ai][bj][m][n] = __builtin_amdgcn_mfma_f32_16x16x32_bf16(Bt[n][k], At[m][k], acc[ai][bj][m][n], 0, 0, 0); __builtin_amdgcn_s_setprio(0); } while (0)
; #define PG8_WAIT_V(n) asm volatile("s_waitcnt vmcnt(" #n ")" ::: "memory")
; #define PG8_WAIT_L(n) asm volatile("s_waitcnt lgkmcnt(" #n ")" ::: "memory")
; #define PG8_BAR __builtin_amdgcn_s_barrier()
; #define PG8_SCHED __builtin_amdgcn_sched_barrier(0)
; template <class Epi, class Addr, bool ALIGN_EPI = true, class Order = StaticOrder>
; __device__ __forceinline__ void gemm_phase(LAS unsigned char* lds, const Gemm g, const Order& S, const Epi& E, const int wid) {
;     ...
;             PG8_LDB(B0, 1, 0); PG8_LDB(B1, 1, 1); PG8_SCHED; PG8_LDA(At, 1, 0); PG8_STAGE(PG8_SA(0, 1), a2 + hstepA, voffA);
;             PG8_WAIT_V(8); PG8_WAIT_L(0); PG8_BAR; PG8_MMA(0, 0, At, B0); PG8_MMA(0, 1, At, B1); PG8_BAR; PG8_SCHED;
;             PG8_LDA(At, 1, 1); PG8_STAGE(PG8_SB(1, 0), b3, voffB); PG8_STAGE(PG8_SB(1, 1), b3 + hstepB, voffB); PG8_STAGE(PG8_SA(1, 0), a3, voffA);
;             PG8_WAIT_V(8); PG8_WAIT_L(0); PG8_BAR; PG8_MMA(1, 0, At, B0); PG8_MMA(1, 1, At, B1); PG8_BAR; PG8_SCHED;
;         }
;         if constexpr (ALIGN_EPI) { if (wr == 0) PG8_BAR; }
	ds_read_b128 v[178:181], v162 offset:49152
	ds_read_b128 v[182:185], v162 offset:50176
	ds_read_b128 v[186:189], v162 offset:51200
	ds_read_b128 v[190:193], v162 offset:52224
	ds_read_b128 v[194:197], v162 offset:53248
	ds_read_b128 v[198:201], v162 offset:54272
	ds_read_b128 v[202:205], v162 offset:55296
	ds_read_b128 v[206:209], v162 offset:56320
	s_add_u32 s18, s54, 0x80
	s_addc_u32 s19, s55, 0
	s_mov_b32 s36, m0
	s_mov_b32 m0, s66
	s_nop 0
	global_load_lds_dwordx4 v156, s[18:19]
	s_mov_b32 m0, s67
	s_nop 0
	global_load_lds_dwordx4 v157, s[18:19]
	s_mov_b32 m0, s36
	s_add_u32 s18, s54, 0x100080
	s_addc_u32 s19, s55, 0
	s_mov_b32 s36, m0
	s_mov_b32 m0, s70
	s_nop 0
	global_load_lds_dwordx4 v156, s[18:19]
	s_mov_b32 m0, s71
	s_nop 0
	global_load_lds_dwordx4 v157, s[18:19]
	s_mov_b32 m0, s36
	s_mov_b32 s18, m0
	s_mov_b32 m0, s68
	s_nop 0
	global_load_lds_dwordx4 v156, s[52:53]
	s_mov_b32 m0, s69
	s_nop 0
	global_load_lds_dwordx4 v157, s[52:53]
	s_mov_b32 m0, s18
	s_waitcnt vmcnt(8)
	s_waitcnt lgkmcnt(0)
	s_barrier
	s_setprio 1
	s_waitcnt lgkmcnt(7)
	v_mfma_f32_16x16x32_bf16 v[60:63], v[134:137], v[178:181], v[60:63]
	v_mfma_f32_16x16x32_bf16 v[56:59], v[142:145], v[178:181], v[56:59]
	s_waitcnt lgkmcnt(5)
	v_mfma_f32_16x16x32_bf16 v[44:47], v[134:137], v[186:189], v[44:47]
	v_mfma_f32_16x16x32_bf16 v[40:43], v[142:145], v[186:189], v[40:43]
	s_waitcnt lgkmcnt(3)
	v_mfma_f32_16x16x32_bf16 v[28:31], v[134:137], v[194:197], v[28:31]
	v_mfma_f32_16x16x32_bf16 v[24:27], v[142:145], v[194:197], v[24:27]
	s_waitcnt lgkmcnt(1)
	v_mfma_f32_16x16x32_bf16 v[12:15], v[134:137], v[202:205], v[12:15]
	v_mfma_f32_16x16x32_bf16 v[8:11], v[142:145], v[202:205], v[8:11]
	v_mfma_f32_16x16x32_bf16 v[60:63], v[138:141], v[182:185], v[60:63]
	v_mfma_f32_16x16x32_bf16 v[56:59], v[146:149], v[182:185], v[56:59]
	v_mfma_f32_16x16x32_bf16 v[44:47], v[138:141], v[190:193], v[44:47]
	v_mfma_f32_16x16x32_bf16 v[40:43], v[146:149], v[190:193], v[40:43]
	v_mfma_f32_16x16x32_bf16 v[28:31], v[138:141], v[198:201], v[28:31]
	v_mfma_f32_16x16x32_bf16 v[24:27], v[146:149], v[198:201], v[24:27]
	s_waitcnt lgkmcnt(0)
	v_mfma_f32_16x16x32_bf16 v[12:15], v[138:141], v[206:209], v[12:15]
	v_mfma_f32_16x16x32_bf16 v[8:11], v[146:149], v[206:209], v[8:11]
	v_mfma_f32_16x16x32_bf16 v[52:55], v[150:153], v[178:181], v[52:55]
	v_mfma_f32_16x16x32_bf16 v[48:51], v[170:173], v[178:181], v[48:51]
	v_mfma_f32_16x16x32_bf16 v[36:39], v[150:153], v[186:189], v[36:39]
	v_mfma_f32_16x16x32_bf16 v[32:35], v[170:173], v[186:189], v[32:35]
	v_mfma_f32_16x16x32_bf16 v[20:23], v[150:153], v[194:197], v[20:23]
	v_mfma_f32_16x16x32_bf16 v[16:19], v[170:173], v[194:197], v[16:19]
	v_mfma_f32_16x16x32_bf16 v[4:7], v[150:153], v[202:205], v[4:7]
	v_mfma_f32_16x16x32_bf16 v[0:3], v[170:173], v[202:205], v[0:3]
	v_mfma_f32_16x16x32_bf16 v[52:55], v[166:169], v[182:185], v[52:55]
	v_mfma_f32_16x16x32_bf16 v[48:51], v[174:177], v[182:185], v[48:51]
	v_mfma_f32_16x16x32_bf16 v[36:39], v[166:169], v[190:193], v[36:39]
	v_mfma_f32_16x16x32_bf16 v[32:35], v[174:177], v[190:193], v[32:35]
	v_mfma_f32_16x16x32_bf16 v[20:23], v[166:169], v[198:201], v[20:23]
	v_mfma_f32_16x16x32_bf16 v[16:19], v[174:177], v[198:201], v[16:19]
	v_mfma_f32_16x16x32_bf16 v[4:7], v[166:169], v[206:209], v[4:7]
	v_mfma_f32_16x16x32_bf16 v[0:3], v[174:177], v[206:209], v[0:3]
	s_setprio 0
	s_barrier
	s_add_i32 s77, s77, 2
	s_add_u32 s75, s75, 0x100
	s_addc_u32 s76, s76, 0
	s_cmp_gt_u32 s77, 61
	s_mov_b64 s[48:49], s[50:51]
	s_cbranch_scc0 .LBB0_814
	s_and_b64 vcc, exec, s[14:15]
	s_cbranch_vccz .LBB0_817
	s_barrier

; #define PG8_LDA(dst, b, h) do { _Pragma("unroll") for (int m = 0; m < 4; ++m) _Pragma("unroll") for (int k = 0; k < 2; ++k) dst[m][k] = *(const LAS bf16x8*)(lds + PG8_SA(b, h) + aoff + m * 2048 + k * 1024); } while (0)
; #define PG8_LDB(dst, b, h) do { _Pragma("unroll") for (int n = 0; n < 2; ++n) _Pragma("unroll") for (int k = 0; k < 2; ++k) dst[n][k] = *(const LAS bf16x8*)(lds + PG8_SB(b, h) + boff + n * 2048 + k * 1024); } while (0)
; #define PG8_MMA(ai, bj, At, Bt) do { __builtin_amdgcn_s_setprio(1); _Pragma("unroll") for (int m = 0; m < 4; ++m) _Pragma("unroll") for (int n = 0; n < 2; ++n) _Pragma("unroll") for (int k = 0; k < 2; ++k) \
;         acc[ai][bj][m][n] = __builtin_amdgcn_mfma_f32_16x16x32_bf16(Bt[n][k], At[m][k], acc[ai][bj][m][n], 0, 0, 0); __builtin_amdgcn_s_setprio(0); } while (0)
; template <class Epi, class Addr, bool ALIGN_EPI = true, class Order = StaticOrder>
; __device__ __forceinline__ void gemm_phase(LAS unsigned char* lds, const Gemm g, const Order& S, const Epi& E, const int wid) {
;     ...
;             const bool last = (t == nt - 2);
;             const char* a1 = cA + (size_t)(t + 1) * kstep;
;             const char* a2 = last ? nA : cA + (size_t)(t + 2) * kstep; const char* b2 = last ? nB : cB + (size_t)(t + 2) * kstep;
;             const char* a3 = a2 + kstep; const char* b3 = b2 + kstep;
;             PG8_LDB(B0, 0, 0); PG8_LDB(B1, 0, 1); PG8_SCHED; PG8_LDA(At, 0, 0); PG8_STAGE(PG8_SA(1, 1), a1 + hstepA, voffA);
;             PG8_WAIT_V(8); PG8_WAIT_L(0); PG8_BAR; PG8_MMA(0, 0, At, B0); PG8_MMA(0, 1, At, B1); PG8_BAR; PG8_SCHED;
;             PG8_LDA(At, 0, 1); PG8_STAGE(PG8_SB(0, 0), b2, voffB); PG8_STAGE(PG8_SB(0, 1), b2 + hstepB, voffB); PG8_STAGE(PG8_SA(0, 0), a2, voffA);
;             PG8_WAIT_V(8); PG8_WAIT_L(0); PG8_BAR; PG8_MMA(1, 0, At, B0); PG8_MMA(1, 1, At, B1); PG8_BAR; PG8_SCHED;
;             PG8_LDB(B0, 1, 0); PG8_LDB(B1, 1, 1); PG8_SCHED; PG8_LDA(At, 1, 0); PG8_STAGE(PG8_SA(0, 1), a2 + hstepA, voffA);
;             PG8_WAIT_V(8); PG8_WAIT_L(0); PG8_BAR; PG8_MMA(0, 0, At, B0); PG8_MMA(0, 1, At, B1); PG8_BAR; PG8_SCHED;
;             PG8_LDA(At, 1, 1); PG8_STAGE(PG8_SB(1, 0), b3, voffB); PG8_STAGE(PG8_SB(1, 1), b3 + hstepB, voffB); PG8_STAGE(PG8_SA(1, 0), a3, voffA);
;             PG8_WAIT_V(8); PG8_WAIT_L(0); PG8_BAR; PG8_MMA(1, 0, At, B0); PG8_MMA(1, 1, At, B1); PG8_BAR; PG8_SCHED;
.LBB0_951:
	ds_read_b128 v[120:123], v200
	ds_read_b128 v[132:135], v200 offset:1024
	ds_read_b128 v[136:139], v200 offset:2048
	ds_read_b128 v[140:143], v200 offset:3072
	ds_read_b128 v[144:147], v201
	ds_read_b128 v[148:151], v201 offset:1024
	ds_read_b128 v[152:155], v201 offset:2048
	ds_read_b128 v[156:159], v201 offset:3072
	s_add_u32 s14, s12, 0x100
	s_addc_u32 s15, s13, 0
	s_cmp_eq_u32 s18, 60
	s_cselect_b32 s76, s67, s14
	s_cselect_b32 s77, s11, s15
	s_cselect_b32 s74, s73, vcc_lo
	s_cselect_b32 s75, s65, vcc_hi
	s_add_u32 s16, s76, 0x80
	s_addc_u32 s17, s77, 0
	ds_read_b128 v[160:163], v202
	ds_read_b128 v[164:167], v202 offset:1024
	ds_read_b128 v[168:171], v202 offset:2048
	ds_read_b128 v[172:175], v202 offset:3072
	ds_read_b128 v[186:189], v202 offset:4096
	ds_read_b128 v[208:211], v202 offset:5120
	ds_read_b128 v[212:215], v202 offset:6144
	ds_read_b128 v[216:219], v202 offset:7168
	s_add_u32 s12, s12, 0x100080
	s_addc_u32 s13, s13, 0
	s_mov_b32 s19, m0
	s_mov_b32 m0, s96
	s_nop 0
	global_load_lds_dwordx4 v190, s[12:13]
	s_mov_b32 m0, s97
	s_nop 0
	global_load_lds_dwordx4 v192, s[12:13]
	s_mov_b32 m0, s19
	s_waitcnt vmcnt(8)
	s_waitcnt lgkmcnt(0)
	s_barrier
	s_setprio 1
	s_waitcnt lgkmcnt(7)
	v_mfma_f32_16x16x32_bf16 v[128:131], v[120:123], v[160:163], v[128:131]
	v_mfma_f32_16x16x32_bf16 v[56:59], v[136:139], v[160:163], v[56:59]
	s_waitcnt lgkmcnt(5)
	v_mfma_f32_16x16x32_bf16 v[116:119], v[120:123], v[168:171], v[116:119]
	v_mfma_f32_16x16x32_bf16 v[40:43], v[136:139], v[168:171], v[40:43]
	s_waitcnt lgkmcnt(3)
	v_mfma_f32_16x16x32_bf16 v[108:111], v[120:123], v[186:189], v[108:111]
	v_mfma_f32_16x16x32_bf16 v[52:55], v[136:139], v[186:189], v[52:55]
	s_waitcnt lgkmcnt(1)
	v_mfma_f32_16x16x32_bf16 v[104:107], v[120:123], v[212:215], v[104:107]
	v_mfma_f32_16x16x32_bf16 v[32:35], v[136:139], v[212:215], v[32:35]
	v_mfma_f32_16x16x32_bf16 v[128:131], v[132:135], v[164:167], v[128:131]
	v_mfma_f32_16x16x32_bf16 v[56:59], v[140:143], v[164:167], v[56:59]
	v_mfma_f32_16x16x32_bf16 v[116:119], v[132:135], v[172:175], v[116:119]
	v_mfma_f32_16x16x32_bf16 v[40:43], v[140:143], v[172:175], v[40:43]
	v_mfma_f32_16x16x32_bf16 v[108:111], v[132:135], v[208:211], v[108:111]
	v_mfma_f32_16x16x32_bf16 v[52:55], v[140:143], v[208:211], v[52:55]
	s_waitcnt lgkmcnt(0)
	v_mfma_f32_16x16x32_bf16 v[104:107], v[132:135], v[216:219], v[104:107]
	v_mfma_f32_16x16x32_bf16 v[32:35], v[140:143], v[216:219], v[32:35]
	v_mfma_f32_16x16x32_bf16 v[124:127], v[144:147], v[160:163], v[124:127]
	v_mfma_f32_16x16x32_bf16 v[60:63], v[152:155], v[160:163], v[60:63]
	v_mfma_f32_16x16x32_bf16 v[112:115], v[144:147], v[168:171], v[112:115]
	v_mfma_f32_16x16x32_bf16 v[44:47], v[152:155], v[168:171], v[44:47]
	v_mfma_f32_16x16x32_bf16 v[100:103], v[144:147], v[186:189], v[100:103]
	v_mfma_f32_16x16x32_bf16 v[48:51], v[152:155], v[186:189], v[48:51]
	v_mfma_f32_16x16x32_bf16 v[96:99], v[144:147], v[212:215], v[96:99]
	v_mfma_f32_16x16x32_bf16 v[36:39], v[152:155], v[212:215], v[36:39]
	v_mfma_f32_16x16x32_bf16 v[124:127], v[148:151], v[164:167], v[124:127]
	v_mfma_f32_16x16x32_bf16 v[60:63], v[156:159], v[164:167], v[60:63]
	v_mfma_f32_16x16x32_bf16 v[112:115], v[148:151], v[172:175], v[112:115]
	v_mfma_f32_16x16x32_bf16 v[44:47], v[156:159], v[172:175], v[44:47]
	v_mfma_f32_16x16x32_bf16 v[100:103], v[148:151], v[208:211], v[100:103]
	v_mfma_f32_16x16x32_bf16 v[48:51], v[156:159], v[208:211], v[48:51]
	v_mfma_f32_16x16x32_bf16 v[96:99], v[148:151], v[216:219], v[96:99]
	v_mfma_f32_16x16x32_bf16 v[36:39], v[156:159], v[216:219], v[36:39]
	s_setprio 0
	s_barrier
	ds_read_b128 v[160:163], v202 offset:16384
	ds_read_b128 v[164:167], v202 offset:17408
	ds_read_b128 v[168:171], v202 offset:18432
	ds_read_b128 v[172:175], v202 offset:19456
	ds_read_b128 v[186:189], v202 offset:20480
	ds_read_b128 v[208:211], v202 offset:21504
	ds_read_b128 v[212:215], v202 offset:22528
	ds_read_b128 v[216:219], v202 offset:23552
	s_mov_b32 s12, m0
	s_mov_b32 m0, s80
	s_nop 0
	global_load_lds_dwordx4 v191, s[74:75]
	s_mov_b32 m0, s81
	s_nop 0
	global_load_lds_dwordx4 v193, s[74:75]
	s_mov_b32 m0, s12
	s_add_u32 s12, s74, 0x100000
	s_addc_u32 s13, s75, 0
	s_mov_b32 s19, m0
	s_mov_b32 m0, s82
	s_nop 0
	global_load_lds_dwordx4 v191, s[12:13]
	s_mov_b32 m0, s83
	s_nop 0
	global_load_lds_dwordx4 v193, s[12:13]
	s_mov_b32 m0, s19
	s_mov_b32 s12, m0
	s_mov_b32 m0, s79
	s_nop 0
	global_load_lds_dwordx4 v190, s[76:77]
	s_mov_b32 m0, s84
	s_nop 0
	global_load_lds_dwordx4 v192, s[76:77]
	s_mov_b32 m0, s12
	s_waitcnt vmcnt(8)
	s_waitcnt lgkmcnt(0)
	s_barrier
; #define PG8_LDA(dst, b, h) do { _Pragma("unroll") for (int m = 0; m < 4; ++m) _Pragma("unroll") for (int k = 0; k < 2; ++k) dst[m][k] = *(const LAS bf16x8*)(lds + PG8_SA(b, h) + aoff + m * 2048 + k * 1024); } while (0)
; #define PG8_LDB(dst, b, h) do { _Pragma("unroll") for (int n = 0; n < 2; ++n) _Pragma("unroll") for (int k = 0; k < 2; ++k) dst[n][k] = *(const LAS bf16x8*)(lds + PG8_SB(b, h) + boff + n * 2048 + k * 1024); } while (0)
; #define PG8_MMA(ai, bj, At, Bt) do { __builtin_amdgcn_s_setprio(1); _Pragma("unroll") for (int m = 0; m < 4; ++m) _Pragma("unroll") for (int n = 0; n < 2; ++n) _Pragma("unroll") for (int k = 0; k < 2; ++k) \
;         acc[ai][bj][m][n] = __builtin_amdgcn_mfma_f32_16x16x32_bf16(Bt[n][k], At[m][k], acc[ai][bj][m][n], 0, 0, 0); __builtin_amdgcn_s_setprio(0); } while (0)
; #define PG8_WAIT_V(n) asm volatile("s_waitcnt vmcnt(" #n ")" ::: "memory")
; #define PG8_WAIT_L(n) asm volatile("s_waitcnt lgkmcnt(" #n ")" ::: "memory")
; #define PG8_BAR __builtin_amdgcn_s_barrier()
; #define PG8_SCHED __builtin_amdgcn_sched_barrier(0)
; template <class Epi, class Addr, bool ALIGN_EPI = true, class Order = StaticOrder>
; __device__ __forceinline__ void gemm_phase(LAS unsigned char* lds, const Gemm g, const Order& S, const Epi& E, const int wid) {
;     ...
;             PG8_LDB(B0, 0, 0); PG8_LDB(B1, 0, 1); PG8_SCHED; PG8_LDA(At, 0, 0); PG8_STAGE(PG8_SA(1, 1), a1 + hstepA, voffA);
;             PG8_WAIT_V(8); PG8_WAIT_L(0); PG8_BAR; PG8_MMA(0, 0, At, B0); PG8_MMA(0, 1, At, B1); PG8_BAR; PG8_SCHED;
;             PG8_LDA(At, 0, 1); PG8_STAGE(PG8_SB(0, 0), b2, voffB); PG8_STAGE(PG8_SB(0, 1), b2 + hstepB, voffB); PG8_STAGE(PG8_SA(0, 0), a2, voffA);
;             PG8_WAIT_V(8); PG8_WAIT_L(0); PG8_BAR; PG8_MMA(1, 0, At, B0); PG8_MMA(1, 1, At, B1); PG8_BAR; PG8_SCHED;
;             PG8_LDB(B0, 1, 0); PG8_LDB(B1, 1, 1); PG8_SCHED; PG8_LDA(At, 1, 0); PG8_STAGE(PG8_SA(0, 1), a2 + hstepA, voffA);
;             PG8_WAIT_V(8); PG8_WAIT_L(0); PG8_BAR; PG8_MMA(0, 0, At, B0); PG8_MMA(0, 1, At, B1); PG8_BAR; PG8_SCHED;
;             PG8_LDA(At, 1, 1); PG8_STAGE(PG8_SB(1, 0), b3, voffB); PG8_STAGE(PG8_SB(1, 1), b3 + hstepB, voffB); PG8_STAGE(PG8_SA(1, 0), a3, voffA);
;             PG8_WAIT_V(8); PG8_WAIT_L(0); PG8_BAR; PG8_MMA(1, 0, At, B0); PG8_MMA(1, 1, At, B1); PG8_BAR; PG8_SCHED;
	s_setprio 1
	s_waitcnt lgkmcnt(7)
	v_mfma_f32_16x16x32_bf16 v[92:95], v[120:123], v[160:163], v[92:95]
	v_mfma_f32_16x16x32_bf16 v[24:27], v[136:139], v[160:163], v[24:27]
	s_waitcnt lgkmcnt(5)
	v_mfma_f32_16x16x32_bf16 v[84:87], v[120:123], v[168:171], v[84:87]
	v_mfma_f32_16x16x32_bf16 v[20:23], v[136:139], v[168:171], v[20:23]
	s_waitcnt lgkmcnt(3)
	v_mfma_f32_16x16x32_bf16 v[76:79], v[120:123], v[186:189], v[76:79]
	v_mfma_f32_16x16x32_bf16 v[0:3], v[136:139], v[186:189], v[0:3]
	s_waitcnt lgkmcnt(1)
	v_mfma_f32_16x16x32_bf16 v[72:75], v[120:123], v[212:215], v[72:75]
	v_mfma_f32_16x16x32_bf16 v[8:11], v[136:139], v[212:215], v[8:11]
	v_mfma_f32_16x16x32_bf16 v[92:95], v[132:135], v[164:167], v[92:95]
	v_mfma_f32_16x16x32_bf16 v[24:27], v[140:143], v[164:167], v[24:27]
	v_mfma_f32_16x16x32_bf16 v[84:87], v[132:135], v[172:175], v[84:87]
	v_mfma_f32_16x16x32_bf16 v[20:23], v[140:143], v[172:175], v[20:23]
	v_mfma_f32_16x16x32_bf16 v[76:79], v[132:135], v[208:211], v[76:79]
	v_mfma_f32_16x16x32_bf16 v[0:3], v[140:143], v[208:211], v[0:3]
	s_waitcnt lgkmcnt(0)
	v_mfma_f32_16x16x32_bf16 v[72:75], v[132:135], v[216:219], v[72:75]
	v_mfma_f32_16x16x32_bf16 v[8:11], v[140:143], v[216:219], v[8:11]
	v_mfma_f32_16x16x32_bf16 v[88:91], v[144:147], v[160:163], v[88:91]
	v_mfma_f32_16x16x32_bf16 v[28:31], v[152:155], v[160:163], v[28:31]
	v_mfma_f32_16x16x32_bf16 v[80:83], v[144:147], v[168:171], v[80:83]
	v_mfma_f32_16x16x32_bf16 v[16:19], v[152:155], v[168:171], v[16:19]
	v_mfma_f32_16x16x32_bf16 v[68:71], v[144:147], v[186:189], v[68:71]
	v_mfma_f32_16x16x32_bf16 v[4:7], v[152:155], v[186:189], v[4:7]
	v_mfma_f32_16x16x32_bf16 v[64:67], v[144:147], v[212:215], v[64:67]
	v_mfma_f32_16x16x32_bf16 v[12:15], v[152:155], v[212:215], v[12:15]
	v_mfma_f32_16x16x32_bf16 v[88:91], v[148:151], v[164:167], v[88:91]
	v_mfma_f32_16x16x32_bf16 v[28:31], v[156:159], v[164:167], v[28:31]
	v_mfma_f32_16x16x32_bf16 v[80:83], v[148:151], v[172:175], v[80:83]
	v_mfma_f32_16x16x32_bf16 v[16:19], v[156:159], v[172:175], v[16:19]
	v_mfma_f32_16x16x32_bf16 v[68:71], v[148:151], v[208:211], v[68:71]
	v_mfma_f32_16x16x32_bf16 v[4:7], v[156:159], v[208:211], v[4:7]
	v_mfma_f32_16x16x32_bf16 v[64:67], v[148:151], v[216:219], v[64:67]
	v_mfma_f32_16x16x32_bf16 v[12:15], v[156:159], v[216:219], v[12:15]
	s_setprio 0
	s_barrier
	ds_read_b128 v[120:123], v203
	ds_read_b128 v[132:135], v203 offset:1024
	ds_read_b128 v[136:139], v203 offset:2048
	ds_read_b128 v[140:143], v203 offset:3072
	ds_read_b128 v[144:147], v204
	ds_read_b128 v[148:151], v204 offset:1024
	ds_read_b128 v[152:155], v204 offset:2048
	ds_read_b128 v[156:159], v204 offset:3072
	ds_read_b128 v[160:163], v202 offset:32768
	ds_read_b128 v[164:167], v202 offset:33792
	ds_read_b128 v[168:171], v202 offset:34816
	ds_read_b128 v[172:175], v202 offset:35840
	ds_read_b128 v[186:189], v202 offset:36864
	ds_read_b128 v[208:211], v202 offset:37888
	ds_read_b128 v[212:215], v202 offset:38912
	ds_read_b128 v[216:219], v202 offset:39936
	s_add_u32 s12, s76, 0x100000
	s_addc_u32 s13, s77, 0
	s_mov_b32 s19, m0
	s_mov_b32 m0, s85
	s_nop 0
	global_load_lds_dwordx4 v190, s[12:13]
	s_mov_b32 m0, s86
	s_nop 0
	global_load_lds_dwordx4 v192, s[12:13]
	s_mov_b32 m0, s19
	s_waitcnt vmcnt(8)
	s_waitcnt lgkmcnt(0)
	s_barrier
	s_setprio 1
	s_waitcnt lgkmcnt(7)
	v_mfma_f32_16x16x32_bf16 v[128:131], v[120:123], v[160:163], v[128:131]
	v_mfma_f32_16x16x32_bf16 v[56:59], v[136:139], v[160:163], v[56:59]
	s_waitcnt lgkmcnt(5)
	v_mfma_f32_16x16x32_bf16 v[116:119], v[120:123], v[168:171], v[116:119]
	v_mfma_f32_16x16x32_bf16 v[40:43], v[136:139], v[168:171], v[40:43]
	s_waitcnt lgkmcnt(3)
	v_mfma_f32_16x16x32_bf16 v[108:111], v[120:123], v[186:189], v[108:111]
	v_mfma_f32_16x16x32_bf16 v[52:55], v[136:139], v[186:189], v[52:55]
	s_waitcnt lgkmcnt(1)
	v_mfma_f32_16x16x32_bf16 v[104:107], v[120:123], v[212:215], v[104:107]
	v_mfma_f32_16x16x32_bf16 v[32:35], v[136:139], v[212:215], v[32:35]
	v_mfma_f32_16x16x32_bf16 v[128:131], v[132:135], v[164:167], v[128:131]
	v_mfma_f32_16x16x32_bf16 v[56:59], v[140:143], v[164:167], v[56:59]
	v_mfma_f32_16x16x32_bf16 v[116:119], v[132:135], v[172:175], v[116:119]
	v_mfma_f32_16x16x32_bf16 v[40:43], v[140:143], v[172:175], v[40:43]
	v_mfma_f32_16x16x32_bf16 v[108:111], v[132:135], v[208:211], v[108:111]
	v_mfma_f32_16x16x32_bf16 v[52:55], v[140:143], v[208:211], v[52:55]
	s_waitcnt lgkmcnt(0)
	v_mfma_f32_16x16x32_bf16 v[104:107], v[132:135], v[216:219], v[104:107]
	v_mfma_f32_16x16x32_bf16 v[32:35], v[140:143], v[216:219], v[32:35]
	v_mfma_f32_16x16x32_bf16 v[124:127], v[144:147], v[160:163], v[124:127]
	v_mfma_f32_16x16x32_bf16 v[60:63], v[152:155], v[160:163], v[60:63]
	v_mfma_f32_16x16x32_bf16 v[112:115], v[144:147], v[168:171], v[112:115]
	v_mfma_f32_16x16x32_bf16 v[44:47], v[152:155], v[168:171], v[44:47]
	v_mfma_f32_16x16x32_bf16 v[100:103], v[144:147], v[186:189], v[100:103]
	v_mfma_f32_16x16x32_bf16 v[48:51], v[152:155], v[186:189], v[48:51]
	v_mfma_f32_16x16x32_bf16 v[96:99], v[144:147], v[212:215], v[96:99]
	v_mfma_f32_16x16x32_bf16 v[36:39], v[152:155], v[212:215], v[36:39]
	v_mfma_f32_16x16x32_bf16 v[124:127], v[148:151], v[164:167], v[124:127]
	v_mfma_f32_16x16x32_bf16 v[60:63], v[156:159], v[164:167], v[60:63]
	v_mfma_f32_16x16x32_bf16 v[112:115], v[148:151], v[172:175], v[112:115]
	v_mfma_f32_16x16x32_bf16 v[44:47], v[156:159], v[172:175], v[44:47]
	v_mfma_f32_16x16x32_bf16 v[100:103], v[148:151], v[208:211], v[100:103]
	v_mfma_f32_16x16x32_bf16 v[48:51], v[156:159], v[208:211], v[48:51]
	v_mfma_f32_16x16x32_bf16 v[96:99], v[148:151], v[216:219], v[96:99]
	v_mfma_f32_16x16x32_bf16 v[36:39], v[156:159], v[216:219], v[36:39]
	s_setprio 0
	s_barrier
; #define PG8_LDA(dst, b, h) do { _Pragma("unroll") for (int m = 0; m < 4; ++m) _Pragma("unroll") for (int k = 0; k < 2; ++k) dst[m][k] = *(const LAS bf16x8*)(lds + PG8_SA(b, h) + aoff + m * 2048 + k * 1024); } while (0)
; #define PG8_LDB(dst, b, h) do { _Pragma("unroll") for (int n = 0; n < 2; ++n) _Pragma("unroll") for (int k = 0; k < 2; ++k) dst[n][k] = *(const LAS bf16x8*)(lds + PG8_SB(b, h) + boff + n * 2048 + k * 1024); } while (0)
; #define PG8_MMA(ai, bj, At, Bt) do { __builtin_amdgcn_s_setprio(1); _Pragma("unroll") for (int m = 0; m < 4; ++m) _Pragma("unroll") for (int n = 0; n < 2; ++n) _Pragma("unroll") for (int k = 0; k < 2; ++k) \
;         acc[ai][bj][m][n] = __builtin_amdgcn_mfma_f32_16x16x32_bf16(Bt[n][k], At[m][k], acc[ai][bj][m][n], 0, 0, 0); __builtin_amdgcn_s_setprio(0); } while (0)
; #define PG8_WAIT_V(n) asm volatile("s_waitcnt vmcnt(" #n ")" ::: "memory")
; #define PG8_WAIT_L(n) asm volatile("s_waitcnt lgkmcnt(" #n ")" ::: "memory")
; #define PG8_BAR __builtin_amdgcn_s_barrier()
; #define PG8_SCHED __builtin_amdgcn_sched_barrier(0)
; template <class Epi, class Addr, bool ALIGN_EPI = true, class Order = StaticOrder>
; __device__ __forceinline__ void gemm_phase(LAS unsigned char* lds, const Gemm g, const Order& S, const Epi& E, const int wid) {
;     ...
;             PG8_LDB(B0, 1, 0); PG8_LDB(B1, 1, 1); PG8_SCHED; PG8_LDA(At, 1, 0); PG8_STAGE(PG8_SA(0, 1), a2 + hstepA, voffA);
;             PG8_WAIT_V(8); PG8_WAIT_L(0); PG8_BAR; PG8_MMA(0, 0, At, B0); PG8_MMA(0, 1, At, B1); PG8_BAR; PG8_SCHED;
;             PG8_LDA(At, 1, 1); PG8_STAGE(PG8_SB(1, 0), b3, voffB); PG8_STAGE(PG8_SB(1, 1), b3 + hstepB, voffB); PG8_STAGE(PG8_SA(1, 0), a3, voffA);
;             PG8_WAIT_V(8); PG8_WAIT_L(0); PG8_BAR; PG8_MMA(1, 0, At, B0); PG8_MMA(1, 1, At, B1); PG8_BAR; PG8_SCHED;
;         }
;         if constexpr (ALIGN_EPI) { if (wr == 0) PG8_BAR; }
;         E(acc, cur, wr, wc, fr, fq);
	ds_read_b128 v[160:163], v202 offset:49152
	ds_read_b128 v[164:167], v202 offset:50176
	ds_read_b128 v[168:171], v202 offset:51200
	ds_read_b128 v[172:175], v202 offset:52224
	ds_read_b128 v[186:189], v202 offset:53248
	ds_read_b128 v[208:211], v202 offset:54272
	ds_read_b128 v[212:215], v202 offset:55296
	ds_read_b128 v[216:219], v202 offset:56320
	s_add_u32 s12, s74, 0x80
	s_addc_u32 s13, s75, 0
	s_mov_b32 s19, m0
	s_mov_b32 m0, s89
	s_nop 0
	global_load_lds_dwordx4 v191, s[12:13]
	s_mov_b32 m0, s90
	s_nop 0
	global_load_lds_dwordx4 v193, s[12:13]
	s_mov_b32 m0, s19
	s_add_u32 s12, s74, 0x100080
	s_addc_u32 s13, s75, 0
	s_mov_b32 s19, m0
	s_mov_b32 m0, s94
	s_nop 0
	global_load_lds_dwordx4 v191, s[12:13]
	s_mov_b32 m0, s95
	s_nop 0
	global_load_lds_dwordx4 v193, s[12:13]
	s_mov_b32 m0, s19
	s_mov_b32 s12, m0
	s_mov_b32 m0, s91
	s_nop 0
	global_load_lds_dwordx4 v190, s[16:17]
	s_mov_b32 m0, s93
	s_nop 0
	global_load_lds_dwordx4 v192, s[16:17]
	s_mov_b32 m0, s12
	s_waitcnt vmcnt(8)
	s_waitcnt lgkmcnt(0)
	s_barrier
	s_setprio 1
	s_waitcnt lgkmcnt(7)
	v_mfma_f32_16x16x32_bf16 v[92:95], v[120:123], v[160:163], v[92:95]
	v_mfma_f32_16x16x32_bf16 v[24:27], v[136:139], v[160:163], v[24:27]
	s_waitcnt lgkmcnt(5)
	v_mfma_f32_16x16x32_bf16 v[84:87], v[120:123], v[168:171], v[84:87]
	v_mfma_f32_16x16x32_bf16 v[20:23], v[136:139], v[168:171], v[20:23]
	s_waitcnt lgkmcnt(3)
	v_mfma_f32_16x16x32_bf16 v[76:79], v[120:123], v[186:189], v[76:79]
	v_mfma_f32_16x16x32_bf16 v[0:3], v[136:139], v[186:189], v[0:3]
	s_waitcnt lgkmcnt(1)
	v_mfma_f32_16x16x32_bf16 v[72:75], v[120:123], v[212:215], v[72:75]
	v_mfma_f32_16x16x32_bf16 v[8:11], v[136:139], v[212:215], v[8:11]
	v_mfma_f32_16x16x32_bf16 v[92:95], v[132:135], v[164:167], v[92:95]
	v_mfma_f32_16x16x32_bf16 v[24:27], v[140:143], v[164:167], v[24:27]
	v_mfma_f32_16x16x32_bf16 v[84:87], v[132:135], v[172:175], v[84:87]
	v_mfma_f32_16x16x32_bf16 v[20:23], v[140:143], v[172:175], v[20:23]
	v_mfma_f32_16x16x32_bf16 v[76:79], v[132:135], v[208:211], v[76:79]
	v_mfma_f32_16x16x32_bf16 v[0:3], v[140:143], v[208:211], v[0:3]
	s_waitcnt lgkmcnt(0)
	v_mfma_f32_16x16x32_bf16 v[72:75], v[132:135], v[216:219], v[72:75]
	v_mfma_f32_16x16x32_bf16 v[8:11], v[140:143], v[216:219], v[8:11]
	v_mfma_f32_16x16x32_bf16 v[88:91], v[144:147], v[160:163], v[88:91]
	v_mfma_f32_16x16x32_bf16 v[28:31], v[152:155], v[160:163], v[28:31]
	v_mfma_f32_16x16x32_bf16 v[80:83], v[144:147], v[168:171], v[80:83]
	v_mfma_f32_16x16x32_bf16 v[16:19], v[152:155], v[168:171], v[16:19]
	v_mfma_f32_16x16x32_bf16 v[68:71], v[144:147], v[186:189], v[68:71]
	v_mfma_f32_16x16x32_bf16 v[4:7], v[152:155], v[186:189], v[4:7]
	v_mfma_f32_16x16x32_bf16 v[64:67], v[144:147], v[212:215], v[64:67]
	v_mfma_f32_16x16x32_bf16 v[12:15], v[152:155], v[212:215], v[12:15]
	v_mfma_f32_16x16x32_bf16 v[88:91], v[148:151], v[164:167], v[88:91]
	v_mfma_f32_16x16x32_bf16 v[28:31], v[156:159], v[164:167], v[28:31]
	v_mfma_f32_16x16x32_bf16 v[80:83], v[148:151], v[172:175], v[80:83]
	v_mfma_f32_16x16x32_bf16 v[16:19], v[156:159], v[172:175], v[16:19]
	v_mfma_f32_16x16x32_bf16 v[68:71], v[148:151], v[208:211], v[68:71]
	v_mfma_f32_16x16x32_bf16 v[4:7], v[156:159], v[208:211], v[4:7]
	v_mfma_f32_16x16x32_bf16 v[64:67], v[148:151], v[216:219], v[64:67]
	v_mfma_f32_16x16x32_bf16 v[12:15], v[156:159], v[216:219], v[12:15]
	s_setprio 0
	s_barrier
	s_add_i32 s18, s18, 2
	s_add_u32 vcc_lo, vcc_lo, 0x100
	s_addc_u32 vcc_hi, vcc_hi, 0
	s_cmp_gt_u32 s18, 61
	s_mov_b64 s[12:13], s[14:15]
	s_cbranch_scc0 .LBB0_951
	s_and_b64 vcc, exec, s[4:5]
	s_cbranch_vccz .LBB0_995
	s_barrier
	v_cmp_gt_i32_e32 vcc, 15, v194
	s_mov_b64 s[14:15], -1
	s_and_saveexec_b64 s[12:13], vcc
	s_cbranch_execnz .LBB0_996

; #define PG8_LDA(dst, b, h) do { _Pragma("unroll") for (int m = 0; m < 4; ++m) _Pragma("unroll") for (int k = 0; k < 2; ++k) dst[m][k] = *(const LAS bf16x8*)(lds + PG8_SA(b, h) + aoff + m * 2048 + k * 1024); } while (0)
; #define PG8_LDB(dst, b, h) do { _Pragma("unroll") for (int n = 0; n < 2; ++n) _Pragma("unroll") for (int k = 0; k < 2; ++k) dst[n][k] = *(const LAS bf16x8*)(lds + PG8_SB(b, h) + boff + n * 2048 + k * 1024); } while (0)
; #define PG8_MMA(ai, bj, At, Bt) do { __builtin_amdgcn_s_setprio(1); _Pragma("unroll") for (int m = 0; m < 4; ++m) _Pragma("unroll") for (int n = 0; n < 2; ++n) _Pragma("unroll") for (int k = 0; k < 2; ++k) \
;         acc[ai][bj][m][n] = __builtin_amdgcn_mfma_f32_16x16x32_bf16(Bt[n][k], At[m][k], acc[ai][bj][m][n], 0, 0, 0); __builtin_amdgcn_s_setprio(0); } while (0)
; template <class Epi, class Addr, bool ALIGN_EPI = true, class Order = StaticOrder>
; __device__ __forceinline__ void gemm_phase(LAS unsigned char* lds, const Gemm g, const Order& S, const Epi& E, const int wid) {
;     ...
;             const bool last = (t == nt - 2);
;             const char* a1 = cA + (size_t)(t + 1) * kstep;
;             const char* a2 = last ? nA : cA + (size_t)(t + 2) * kstep; const char* b2 = last ? nB : cB + (size_t)(t + 2) * kstep;
;             const char* a3 = a2 + kstep; const char* b3 = b2 + kstep;
;             PG8_LDB(B0, 0, 0); PG8_LDB(B1, 0, 1); PG8_SCHED; PG8_LDA(At, 0, 0); PG8_STAGE(PG8_SA(1, 1), a1 + hstepA, voffA);
;             PG8_WAIT_V(8); PG8_WAIT_L(0); PG8_BAR; PG8_MMA(0, 0, At, B0); PG8_MMA(0, 1, At, B1); PG8_BAR; PG8_SCHED;
;             PG8_LDA(At, 0, 1); PG8_STAGE(PG8_SB(0, 0), b2, voffB); PG8_STAGE(PG8_SB(0, 1), b2 + hstepB, voffB); PG8_STAGE(PG8_SA(0, 0), a2, voffA);
;             PG8_WAIT_V(8); PG8_WAIT_L(0); PG8_BAR; PG8_MMA(1, 0, At, B0); PG8_MMA(1, 1, At, B1); PG8_BAR; PG8_SCHED;
;             PG8_LDB(B0, 1, 0); PG8_LDB(B1, 1, 1); PG8_SCHED; PG8_LDA(At, 1, 0); PG8_STAGE(PG8_SA(0, 1), a2 + hstepA, voffA);
;             PG8_WAIT_V(8); PG8_WAIT_L(0); PG8_BAR; PG8_MMA(0, 0, At, B0); PG8_MMA(0, 1, At, B1); PG8_BAR; PG8_SCHED;
;             PG8_LDA(At, 1, 1); PG8_STAGE(PG8_SB(1, 0), b3, voffB); PG8_STAGE(PG8_SB(1, 1), b3 + hstepB, voffB); PG8_STAGE(PG8_SA(1, 0), a3, voffA);
;             PG8_WAIT_V(8); PG8_WAIT_L(0); PG8_BAR; PG8_MMA(1, 0, At, B0); PG8_MMA(1, 1, At, B1); PG8_BAR; PG8_SCHED;
.LBB0_1144:
	ds_read_b128 v[134:137], v160
	ds_read_b128 v[138:141], v160 offset:1024
	ds_read_b128 v[142:145], v160 offset:2048
	ds_read_b128 v[146:149], v160 offset:3072
	ds_read_b128 v[150:153], v161
	ds_read_b128 v[166:169], v161 offset:1024
	ds_read_b128 v[170:173], v161 offset:2048
	ds_read_b128 v[174:177], v161 offset:3072
	s_add_u32 s42, s24, 0x100
	s_addc_u32 s43, s25, 0
	s_cmpk_eq_i32 s18, 0xa8
	s_cselect_b32 s48, s6, s42
	s_cselect_b32 s49, s7, s43
	s_cselect_b32 s46, s20, s23
	s_cselect_b32 s47, s21, s27
	s_add_u32 s44, s48, 0x80
	s_addc_u32 s45, s49, 0
	ds_read_b128 v[178:181], v162
	ds_read_b128 v[182:185], v162 offset:1024
	ds_read_b128 v[186:189], v162 offset:2048
	ds_read_b128 v[190:193], v162 offset:3072
	ds_read_b128 v[194:197], v162 offset:4096
	ds_read_b128 v[198:201], v162 offset:5120
	ds_read_b128 v[202:205], v162 offset:6144
	ds_read_b128 v[206:209], v162 offset:7168
	s_add_u32 s24, s24, 0x2b0080
	s_addc_u32 s25, s25, 0
	s_mov_b32 s19, m0
	s_mov_b32 m0, s67
	s_nop 0
	global_load_lds_dwordx4 v156, s[24:25]
	s_mov_b32 m0, s68
	s_nop 0
	global_load_lds_dwordx4 v157, s[24:25]
	s_mov_b32 m0, s19
	s_waitcnt vmcnt(8)
	s_waitcnt lgkmcnt(0)
	s_barrier
	s_setprio 1
	s_waitcnt lgkmcnt(0)
	v_mfma_f32_16x16x32_bf16 v[124:127], v[134:137], v[178:181], v[124:127]
	v_mfma_f32_16x16x32_bf16 v[120:123], v[142:145], v[178:181], v[120:123]
	v_mfma_f32_16x16x32_bf16 v[108:111], v[134:137], v[186:189], v[108:111]
	v_mfma_f32_16x16x32_bf16 v[104:107], v[142:145], v[186:189], v[104:107]
	v_mfma_f32_16x16x32_bf16 v[92:95], v[134:137], v[194:197], v[92:95]
	v_mfma_f32_16x16x32_bf16 v[88:91], v[142:145], v[194:197], v[88:91]
	v_mfma_f32_16x16x32_bf16 v[76:79], v[134:137], v[202:205], v[76:79]
	v_mfma_f32_16x16x32_bf16 v[72:75], v[142:145], v[202:205], v[72:75]
	v_mfma_f32_16x16x32_bf16 v[124:127], v[138:141], v[182:185], v[124:127]
	v_mfma_f32_16x16x32_bf16 v[120:123], v[146:149], v[182:185], v[120:123]
	v_mfma_f32_16x16x32_bf16 v[108:111], v[138:141], v[190:193], v[108:111]
	v_mfma_f32_16x16x32_bf16 v[104:107], v[146:149], v[190:193], v[104:107]
	v_mfma_f32_16x16x32_bf16 v[92:95], v[138:141], v[198:201], v[92:95]
	v_mfma_f32_16x16x32_bf16 v[88:91], v[146:149], v[198:201], v[88:91]
	v_mfma_f32_16x16x32_bf16 v[76:79], v[138:141], v[206:209], v[76:79]
	v_mfma_f32_16x16x32_bf16 v[72:75], v[146:149], v[206:209], v[72:75]
	v_mfma_f32_16x16x32_bf16 v[116:119], v[150:153], v[178:181], v[116:119]
	v_mfma_f32_16x16x32_bf16 v[112:115], v[170:173], v[178:181], v[112:115]
	v_mfma_f32_16x16x32_bf16 v[100:103], v[150:153], v[186:189], v[100:103]
	v_mfma_f32_16x16x32_bf16 v[96:99], v[170:173], v[186:189], v[96:99]
	v_mfma_f32_16x16x32_bf16 v[84:87], v[150:153], v[194:197], v[84:87]
	v_mfma_f32_16x16x32_bf16 v[80:83], v[170:173], v[194:197], v[80:83]
	v_mfma_f32_16x16x32_bf16 v[68:71], v[150:153], v[202:205], v[68:71]
	v_mfma_f32_16x16x32_bf16 v[64:67], v[170:173], v[202:205], v[64:67]
	v_mfma_f32_16x16x32_bf16 v[116:119], v[166:169], v[182:185], v[116:119]
	v_mfma_f32_16x16x32_bf16 v[112:115], v[174:177], v[182:185], v[112:115]
	v_mfma_f32_16x16x32_bf16 v[100:103], v[166:169], v[190:193], v[100:103]
	v_mfma_f32_16x16x32_bf16 v[96:99], v[174:177], v[190:193], v[96:99]
	v_mfma_f32_16x16x32_bf16 v[84:87], v[166:169], v[198:201], v[84:87]
	v_mfma_f32_16x16x32_bf16 v[80:83], v[174:177], v[198:201], v[80:83]
	v_mfma_f32_16x16x32_bf16 v[68:71], v[166:169], v[206:209], v[68:71]
	v_mfma_f32_16x16x32_bf16 v[64:67], v[174:177], v[206:209], v[64:67]
	s_setprio 0
	s_barrier
	ds_read_b128 v[178:181], v162 offset:16384
	ds_read_b128 v[182:185], v162 offset:17408
	ds_read_b128 v[186:189], v162 offset:18432
	ds_read_b128 v[190:193], v162 offset:19456
	ds_read_b128 v[194:197], v162 offset:20480
	ds_read_b128 v[198:201], v162 offset:21504
	ds_read_b128 v[202:205], v162 offset:22528
	ds_read_b128 v[206:209], v162 offset:23552
	s_mov_b32 s19, m0
	s_mov_b32 m0, s40
	s_nop 0
	global_load_lds_dwordx4 v156, s[46:47]
	s_mov_b32 m0, s41
	s_nop 0
	global_load_lds_dwordx4 v157, s[46:47]
	s_mov_b32 m0, s19
	s_add_u32 s24, s46, 0x2b0000
	s_addc_u32 s25, s47, 0
	s_mov_b32 s19, m0
	s_mov_b32 m0, s50
	s_nop 0
	global_load_lds_dwordx4 v156, s[24:25]
	s_mov_b32 m0, s51
	s_nop 0
	global_load_lds_dwordx4 v157, s[24:25]
	s_mov_b32 m0, s19
	s_nop 0
	s_mov_b32 s19, m0
	s_mov_b32 m0, s39
	s_nop 0
	global_load_lds_dwordx4 v156, s[48:49]
	s_mov_b32 m0, s52
	s_nop 0
	global_load_lds_dwordx4 v157, s[48:49]
	s_mov_b32 m0, s19
	s_waitcnt vmcnt(8)
	s_waitcnt lgkmcnt(0)
	s_barrier
; #define PG8_LDA(dst, b, h) do { _Pragma("unroll") for (int m = 0; m < 4; ++m) _Pragma("unroll") for (int k = 0; k < 2; ++k) dst[m][k] = *(const LAS bf16x8*)(lds + PG8_SA(b, h) + aoff + m * 2048 + k * 1024); } while (0)
; #define PG8_LDB(dst, b, h) do { _Pragma("unroll") for (int n = 0; n < 2; ++n) _Pragma("unroll") for (int k = 0; k < 2; ++k) dst[n][k] = *(const LAS bf16x8*)(lds + PG8_SB(b, h) + boff + n * 2048 + k * 1024); } while (0)
; #define PG8_MMA(ai, bj, At, Bt) do { __builtin_amdgcn_s_setprio(1); _Pragma("unroll") for (int m = 0; m < 4; ++m) _Pragma("unroll") for (int n = 0; n < 2; ++n) _Pragma("unroll") for (int k = 0; k < 2; ++k) \
;         acc[ai][bj][m][n] = __builtin_amdgcn_mfma_f32_16x16x32_bf16(Bt[n][k], At[m][k], acc[ai][bj][m][n], 0, 0, 0); __builtin_amdgcn_s_setprio(0); } while (0)
; #define PG8_WAIT_V(n) asm volatile("s_waitcnt vmcnt(" #n ")" ::: "memory")
; #define PG8_WAIT_L(n) asm volatile("s_waitcnt lgkmcnt(" #n ")" ::: "memory")
; #define PG8_BAR __builtin_amdgcn_s_barrier()
; #define PG8_SCHED __builtin_amdgcn_sched_barrier(0)
; template <class Epi, class Addr, bool ALIGN_EPI = true, class Order = StaticOrder>
; __device__ __forceinline__ void gemm_phase(LAS unsigned char* lds, const Gemm g, const Order& S, const Epi& E, const int wid) {
;     ...
;             PG8_LDB(B0, 0, 0); PG8_LDB(B1, 0, 1); PG8_SCHED; PG8_LDA(At, 0, 0); PG8_STAGE(PG8_SA(1, 1), a1 + hstepA, voffA);
;             PG8_WAIT_V(8); PG8_WAIT_L(0); PG8_BAR; PG8_MMA(0, 0, At, B0); PG8_MMA(0, 1, At, B1); PG8_BAR; PG8_SCHED;
;             PG8_LDA(At, 0, 1); PG8_STAGE(PG8_SB(0, 0), b2, voffB); PG8_STAGE(PG8_SB(0, 1), b2 + hstepB, voffB); PG8_STAGE(PG8_SA(0, 0), a2, voffA);
;             PG8_WAIT_V(8); PG8_WAIT_L(0); PG8_BAR; PG8_MMA(1, 0, At, B0); PG8_MMA(1, 1, At, B1); PG8_BAR; PG8_SCHED;
;             PG8_LDB(B0, 1, 0); PG8_LDB(B1, 1, 1); PG8_SCHED; PG8_LDA(At, 1, 0); PG8_STAGE(PG8_SA(0, 1), a2 + hstepA, voffA);
;             PG8_WAIT_V(8); PG8_WAIT_L(0); PG8_BAR; PG8_MMA(0, 0, At, B0); PG8_MMA(0, 1, At, B1); PG8_BAR; PG8_SCHED;
;             PG8_LDA(At, 1, 1); PG8_STAGE(PG8_SB(1, 0), b3, voffB); PG8_STAGE(PG8_SB(1, 1), b3 + hstepB, voffB); PG8_STAGE(PG8_SA(1, 0), a3, voffA);
;             PG8_WAIT_V(8); PG8_WAIT_L(0); PG8_BAR; PG8_MMA(1, 0, At, B0); PG8_MMA(1, 1, At, B1); PG8_BAR; PG8_SCHED;
	s_setprio 1
	s_waitcnt lgkmcnt(7)
	v_mfma_f32_16x16x32_bf16 v[60:63], v[134:137], v[178:181], v[60:63]
	v_mfma_f32_16x16x32_bf16 v[56:59], v[142:145], v[178:181], v[56:59]
	s_waitcnt lgkmcnt(5)
	v_mfma_f32_16x16x32_bf16 v[44:47], v[134:137], v[186:189], v[44:47]
	v_mfma_f32_16x16x32_bf16 v[40:43], v[142:145], v[186:189], v[40:43]
	s_waitcnt lgkmcnt(3)
	v_mfma_f32_16x16x32_bf16 v[28:31], v[134:137], v[194:197], v[28:31]
	v_mfma_f32_16x16x32_bf16 v[24:27], v[142:145], v[194:197], v[24:27]
	s_waitcnt lgkmcnt(1)
	v_mfma_f32_16x16x32_bf16 v[12:15], v[134:137], v[202:205], v[12:15]
	v_mfma_f32_16x16x32_bf16 v[8:11], v[142:145], v[202:205], v[8:11]
	v_mfma_f32_16x16x32_bf16 v[60:63], v[138:141], v[182:185], v[60:63]
	v_mfma_f32_16x16x32_bf16 v[56:59], v[146:149], v[182:185], v[56:59]
	v_mfma_f32_16x16x32_bf16 v[44:47], v[138:141], v[190:193], v[44:47]
	v_mfma_f32_16x16x32_bf16 v[40:43], v[146:149], v[190:193], v[40:43]
	v_mfma_f32_16x16x32_bf16 v[28:31], v[138:141], v[198:201], v[28:31]
	v_mfma_f32_16x16x32_bf16 v[24:27], v[146:149], v[198:201], v[24:27]
	s_waitcnt lgkmcnt(0)
	v_mfma_f32_16x16x32_bf16 v[12:15], v[138:141], v[206:209], v[12:15]
	v_mfma_f32_16x16x32_bf16 v[8:11], v[146:149], v[206:209], v[8:11]
	v_mfma_f32_16x16x32_bf16 v[52:55], v[150:153], v[178:181], v[52:55]
	v_mfma_f32_16x16x32_bf16 v[48:51], v[170:173], v[178:181], v[48:51]
	v_mfma_f32_16x16x32_bf16 v[36:39], v[150:153], v[186:189], v[36:39]
	v_mfma_f32_16x16x32_bf16 v[32:35], v[170:173], v[186:189], v[32:35]
	v_mfma_f32_16x16x32_bf16 v[20:23], v[150:153], v[194:197], v[20:23]
	v_mfma_f32_16x16x32_bf16 v[16:19], v[170:173], v[194:197], v[16:19]
	v_mfma_f32_16x16x32_bf16 v[4:7], v[150:153], v[202:205], v[4:7]
	v_mfma_f32_16x16x32_bf16 v[0:3], v[170:173], v[202:205], v[0:3]
	v_mfma_f32_16x16x32_bf16 v[52:55], v[166:169], v[182:185], v[52:55]
	v_mfma_f32_16x16x32_bf16 v[48:51], v[174:177], v[182:185], v[48:51]
	v_mfma_f32_16x16x32_bf16 v[36:39], v[166:169], v[190:193], v[36:39]
	v_mfma_f32_16x16x32_bf16 v[32:35], v[174:177], v[190:193], v[32:35]
	v_mfma_f32_16x16x32_bf16 v[20:23], v[166:169], v[198:201], v[20:23]
	v_mfma_f32_16x16x32_bf16 v[16:19], v[174:177], v[198:201], v[16:19]
	v_mfma_f32_16x16x32_bf16 v[4:7], v[166:169], v[206:209], v[4:7]
	v_mfma_f32_16x16x32_bf16 v[0:3], v[174:177], v[206:209], v[0:3]
	s_setprio 0
	s_barrier
	ds_read_b128 v[134:137], v163
	ds_read_b128 v[138:141], v163 offset:1024
	ds_read_b128 v[142:145], v163 offset:2048
	ds_read_b128 v[146:149], v163 offset:3072
	ds_read_b128 v[150:153], v164
	ds_read_b128 v[166:169], v164 offset:1024
	ds_read_b128 v[170:173], v164 offset:2048
	ds_read_b128 v[174:177], v164 offset:3072
	ds_read_b128 v[178:181], v162 offset:32768
	ds_read_b128 v[182:185], v162 offset:33792
	ds_read_b128 v[186:189], v162 offset:34816
	ds_read_b128 v[190:193], v162 offset:35840
	ds_read_b128 v[194:197], v162 offset:36864
	ds_read_b128 v[198:201], v162 offset:37888
	ds_read_b128 v[202:205], v162 offset:38912
	ds_read_b128 v[206:209], v162 offset:39936
	s_add_u32 s24, s48, 0x2b0000
	s_addc_u32 s25, s49, 0
	s_mov_b32 s19, m0
	s_mov_b32 m0, s53
	s_nop 0
	global_load_lds_dwordx4 v156, s[24:25]
	s_mov_b32 m0, s54
	s_nop 0
	global_load_lds_dwordx4 v157, s[24:25]
	s_mov_b32 m0, s19
	s_waitcnt vmcnt(8)
	s_waitcnt lgkmcnt(0)
	s_barrier
	s_setprio 1
	s_waitcnt lgkmcnt(7)
	v_mfma_f32_16x16x32_bf16 v[124:127], v[134:137], v[178:181], v[124:127]
	v_mfma_f32_16x16x32_bf16 v[120:123], v[142:145], v[178:181], v[120:123]
	s_waitcnt lgkmcnt(5)
	v_mfma_f32_16x16x32_bf16 v[108:111], v[134:137], v[186:189], v[108:111]
	v_mfma_f32_16x16x32_bf16 v[104:107], v[142:145], v[186:189], v[104:107]
	s_waitcnt lgkmcnt(3)
	v_mfma_f32_16x16x32_bf16 v[92:95], v[134:137], v[194:197], v[92:95]
	v_mfma_f32_16x16x32_bf16 v[88:91], v[142:145], v[194:197], v[88:91]
	s_waitcnt lgkmcnt(1)
	v_mfma_f32_16x16x32_bf16 v[76:79], v[134:137], v[202:205], v[76:79]
	v_mfma_f32_16x16x32_bf16 v[72:75], v[142:145], v[202:205], v[72:75]
	v_mfma_f32_16x16x32_bf16 v[124:127], v[138:141], v[182:185], v[124:127]
	v_mfma_f32_16x16x32_bf16 v[120:123], v[146:149], v[182:185], v[120:123]
	v_mfma_f32_16x16x32_bf16 v[108:111], v[138:141], v[190:193], v[108:111]
	v_mfma_f32_16x16x32_bf16 v[104:107], v[146:149], v[190:193], v[104:107]
	v_mfma_f32_16x16x32_bf16 v[92:95], v[138:141], v[198:201], v[92:95]
	v_mfma_f32_16x16x32_bf16 v[88:91], v[146:149], v[198:201], v[88:91]
	s_waitcnt lgkmcnt(0)
	v_mfma_f32_16x16x32_bf16 v[76:79], v[138:141], v[206:209], v[76:79]
	v_mfma_f32_16x16x32_bf16 v[72:75], v[146:149], v[206:209], v[72:75]
	v_mfma_f32_16x16x32_bf16 v[116:119], v[150:153], v[178:181], v[116:119]
	v_mfma_f32_16x16x32_bf16 v[112:115], v[170:173], v[178:181], v[112:115]
	v_mfma_f32_16x16x32_bf16 v[100:103], v[150:153], v[186:189], v[100:103]
	v_mfma_f32_16x16x32_bf16 v[96:99], v[170:173], v[186:189], v[96:99]
	v_mfma_f32_16x16x32_bf16 v[84:87], v[150:153], v[194:197], v[84:87]
	v_mfma_f32_16x16x32_bf16 v[80:83], v[170:173], v[194:197], v[80:83]
	v_mfma_f32_16x16x32_bf16 v[68:71], v[150:153], v[202:205], v[68:71]
	v_mfma_f32_16x16x32_bf16 v[64:67], v[170:173], v[202:205], v[64:67]
	v_mfma_f32_16x16x32_bf16 v[116:119], v[166:169], v[182:185], v[116:119]
	v_mfma_f32_16x16x32_bf16 v[112:115], v[174:177], v[182:185], v[112:115]
	v_mfma_f32_16x16x32_bf16 v[100:103], v[166:169], v[190:193], v[100:103]
	v_mfma_f32_16x16x32_bf16 v[96:99], v[174:177], v[190:193], v[96:99]
	v_mfma_f32_16x16x32_bf16 v[84:87], v[166:169], v[198:201], v[84:87]
	v_mfma_f32_16x16x32_bf16 v[80:83], v[174:177], v[198:201], v[80:83]
	v_mfma_f32_16x16x32_bf16 v[68:71], v[166:169], v[206:209], v[68:71]
	v_mfma_f32_16x16x32_bf16 v[64:67], v[174:177], v[206:209], v[64:67]
	s_setprio 0
	s_barrier
; #define PG8_LDA(dst, b, h) do { _Pragma("unroll") for (int m = 0; m < 4; ++m) _Pragma("unroll") for (int k = 0; k < 2; ++k) dst[m][k] = *(const LAS bf16x8*)(lds + PG8_SA(b, h) + aoff + m * 2048 + k * 1024); } while (0)
; #define PG8_LDB(dst, b, h) do { _Pragma("unroll") for (int n = 0; n < 2; ++n) _Pragma("unroll") for (int k = 0; k < 2; ++k) dst[n][k] = *(const LAS bf16x8*)(lds + PG8_SB(b, h) + boff + n * 2048 + k * 1024); } while (0)
; #define PG8_MMA(ai, bj, At, Bt) do { __builtin_amdgcn_s_setprio(1); _Pragma("unroll") for (int m = 0; m < 4; ++m) _Pragma("unroll") for (int n = 0; n < 2; ++n) _Pragma("unroll") for (int k = 0; k < 2; ++k) \
;         acc[ai][bj][m][n] = __builtin_amdgcn_mfma_f32_16x16x32_bf16(Bt[n][k], At[m][k], acc[ai][bj][m][n], 0, 0, 0); __builtin_amdgcn_s_setprio(0); } while (0)
; #define PG8_WAIT_V(n) asm volatile("s_waitcnt vmcnt(" #n ")" ::: "memory")
; #define PG8_WAIT_L(n) asm volatile("s_waitcnt lgkmcnt(" #n ")" ::: "memory")
; #define PG8_BAR __builtin_amdgcn_s_barrier()
; #define PG8_SCHED __builtin_amdgcn_sched_barrier(0)
; template <class Epi, class Addr, bool ALIGN_EPI = true, class Order = StaticOrder>
; __device__ __forceinline__ void gemm_phase(LAS unsigned char* lds, const Gemm g, const Order& S, const Epi& E, const int wid) {
;     ...
;             PG8_LDB(B0, 1, 0); PG8_LDB(B1, 1, 1); PG8_SCHED; PG8_LDA(At, 1, 0); PG8_STAGE(PG8_SA(0, 1), a2 + hstepA, voffA);
;             PG8_WAIT_V(8); PG8_WAIT_L(0); PG8_BAR; PG8_MMA(0, 0, At, B0); PG8_MMA(0, 1, At, B1); PG8_BAR; PG8_SCHED;
;             PG8_LDA(At, 1, 1); PG8_STAGE(PG8_SB(1, 0), b3, voffB); PG8_STAGE(PG8_SB(1, 1), b3 + hstepB, voffB); PG8_STAGE(PG8_SA(1, 0), a3, voffA);
;             PG8_WAIT_V(8); PG8_WAIT_L(0); PG8_BAR; PG8_MMA(1, 0, At, B0); PG8_MMA(1, 1, At, B1); PG8_BAR; PG8_SCHED;
;         }
;         if constexpr (ALIGN_EPI) { if (wr == 0) PG8_BAR; }
	ds_read_b128 v[178:181], v162 offset:49152
	ds_read_b128 v[182:185], v162 offset:50176
	ds_read_b128 v[186:189], v162 offset:51200
	ds_read_b128 v[190:193], v162 offset:52224
	ds_read_b128 v[194:197], v162 offset:53248
	ds_read_b128 v[198:201], v162 offset:54272
	ds_read_b128 v[202:205], v162 offset:55296
	ds_read_b128 v[206:209], v162 offset:56320
	s_add_u32 s24, s46, 0x80
	s_addc_u32 s25, s47, 0
	s_mov_b32 s19, m0
	s_mov_b32 m0, s59
	s_nop 0
	global_load_lds_dwordx4 v156, s[24:25]
	s_mov_b32 m0, s62
	s_nop 0
	global_load_lds_dwordx4 v157, s[24:25]
	s_mov_b32 m0, s19
	s_add_u32 s24, s46, 0x2b0080
	s_addc_u32 s25, s47, 0
	s_mov_b32 s19, m0
	s_mov_b32 m0, s65
	s_nop 0
	global_load_lds_dwordx4 v156, s[24:25]
	s_mov_b32 m0, s66
	s_nop 0
	global_load_lds_dwordx4 v157, s[24:25]
	s_mov_b32 m0, s19
	s_nop 0
	s_mov_b32 s19, m0
	s_mov_b32 m0, s63
	s_nop 0
	global_load_lds_dwordx4 v156, s[44:45]
	s_mov_b32 m0, s64
	s_nop 0
	global_load_lds_dwordx4 v157, s[44:45]
	s_mov_b32 m0, s19
	s_waitcnt vmcnt(8)
	s_waitcnt lgkmcnt(0)
	s_barrier
	s_setprio 1
	s_waitcnt lgkmcnt(7)
	v_mfma_f32_16x16x32_bf16 v[60:63], v[134:137], v[178:181], v[60:63]
	v_mfma_f32_16x16x32_bf16 v[56:59], v[142:145], v[178:181], v[56:59]
	s_waitcnt lgkmcnt(5)
	v_mfma_f32_16x16x32_bf16 v[44:47], v[134:137], v[186:189], v[44:47]
	v_mfma_f32_16x16x32_bf16 v[40:43], v[142:145], v[186:189], v[40:43]
	s_waitcnt lgkmcnt(3)
	v_mfma_f32_16x16x32_bf16 v[28:31], v[134:137], v[194:197], v[28:31]
	v_mfma_f32_16x16x32_bf16 v[24:27], v[142:145], v[194:197], v[24:27]
	s_waitcnt lgkmcnt(1)
	v_mfma_f32_16x16x32_bf16 v[12:15], v[134:137], v[202:205], v[12:15]
	v_mfma_f32_16x16x32_bf16 v[8:11], v[142:145], v[202:205], v[8:11]
	v_mfma_f32_16x16x32_bf16 v[60:63], v[138:141], v[182:185], v[60:63]
	v_mfma_f32_16x16x32_bf16 v[56:59], v[146:149], v[182:185], v[56:59]
	v_mfma_f32_16x16x32_bf16 v[44:47], v[138:141], v[190:193], v[44:47]
	v_mfma_f32_16x16x32_bf16 v[40:43], v[146:149], v[190:193], v[40:43]
	v_mfma_f32_16x16x32_bf16 v[28:31], v[138:141], v[198:201], v[28:31]
	v_mfma_f32_16x16x32_bf16 v[24:27], v[146:149], v[198:201], v[24:27]
	s_waitcnt lgkmcnt(0)
	v_mfma_f32_16x16x32_bf16 v[12:15], v[138:141], v[206:209], v[12:15]
	v_mfma_f32_16x16x32_bf16 v[8:11], v[146:149], v[206:209], v[8:11]
	v_mfma_f32_16x16x32_bf16 v[52:55], v[150:153], v[178:181], v[52:55]
	v_mfma_f32_16x16x32_bf16 v[48:51], v[170:173], v[178:181], v[48:51]
	v_mfma_f32_16x16x32_bf16 v[36:39], v[150:153], v[186:189], v[36:39]
	v_mfma_f32_16x16x32_bf16 v[32:35], v[170:173], v[186:189], v[32:35]
	v_mfma_f32_16x16x32_bf16 v[20:23], v[150:153], v[194:197], v[20:23]
	v_mfma_f32_16x16x32_bf16 v[16:19], v[170:173], v[194:197], v[16:19]
	v_mfma_f32_16x16x32_bf16 v[4:7], v[150:153], v[202:205], v[4:7]
	v_mfma_f32_16x16x32_bf16 v[0:3], v[170:173], v[202:205], v[0:3]
	v_mfma_f32_16x16x32_bf16 v[52:55], v[166:169], v[182:185], v[52:55]
	v_mfma_f32_16x16x32_bf16 v[48:51], v[174:177], v[182:185], v[48:51]
	v_mfma_f32_16x16x32_bf16 v[36:39], v[166:169], v[190:193], v[36:39]
	v_mfma_f32_16x16x32_bf16 v[32:35], v[174:177], v[190:193], v[32:35]
	v_mfma_f32_16x16x32_bf16 v[20:23], v[166:169], v[198:201], v[20:23]
	v_mfma_f32_16x16x32_bf16 v[16:19], v[174:177], v[198:201], v[16:19]
	v_mfma_f32_16x16x32_bf16 v[4:7], v[166:169], v[206:209], v[4:7]
	v_mfma_f32_16x16x32_bf16 v[0:3], v[174:177], v[206:209], v[0:3]
	s_setprio 0
	s_barrier
	s_add_i32 s18, s18, 2
	s_add_u32 s23, s23, 0x100
	s_addc_u32 s27, s27, 0
	s_cmpk_gt_u32 s18, 0xa9
	s_mov_b64 s[24:25], s[42:43]
	s_cbranch_scc0 .LBB0_1144
	s_and_b64 vcc, exec, s[14:15]
	s_cbranch_vccz .LBB0_1147
	s_barrier

; #define PG8_LDA(dst, b, h) do { _Pragma("unroll") for (int m = 0; m < 4; ++m) _Pragma("unroll") for (int k = 0; k < 2; ++k) dst[m][k] = *(const LAS bf16x8*)(lds + PG8_SA(b, h) + aoff + m * 2048 + k * 1024); } while (0)
; #define PG8_LDB(dst, b, h) do { _Pragma("unroll") for (int n = 0; n < 2; ++n) _Pragma("unroll") for (int k = 0; k < 2; ++k) dst[n][k] = *(const LAS bf16x8*)(lds + PG8_SB(b, h) + boff + n * 2048 + k * 1024); } while (0)
; #define PG8_MMA(ai, bj, At, Bt) do { __builtin_amdgcn_s_setprio(1); _Pragma("unroll") for (int m = 0; m < 4; ++m) _Pragma("unroll") for (int n = 0; n < 2; ++n) _Pragma("unroll") for (int k = 0; k < 2; ++k) \
;         acc[ai][bj][m][n] = __builtin_amdgcn_mfma_f32_16x16x32_bf16(Bt[n][k], At[m][k], acc[ai][bj][m][n], 0, 0, 0); __builtin_amdgcn_s_setprio(0); } while (0)
; template <class Epi, class Addr, bool ALIGN_EPI = true, class Order = StaticOrder>
; __device__ __forceinline__ void gemm_phase(LAS unsigned char* lds, const Gemm g, const Order& S, const Epi& E, const int wid) {
;     ...
;             const bool last = (t == nt - 2);
;             const char* a1 = cA + (size_t)(t + 1) * kstep;
;             const char* a2 = last ? nA : cA + (size_t)(t + 2) * kstep; const char* b2 = last ? nB : cB + (size_t)(t + 2) * kstep;
;             const char* a3 = a2 + kstep; const char* b3 = b2 + kstep;
;             PG8_LDB(B0, 0, 0); PG8_LDB(B1, 0, 1); PG8_SCHED; PG8_LDA(At, 0, 0); PG8_STAGE(PG8_SA(1, 1), a1 + hstepA, voffA);
;             PG8_WAIT_V(8); PG8_WAIT_L(0); PG8_BAR; PG8_MMA(0, 0, At, B0); PG8_MMA(0, 1, At, B1); PG8_BAR; PG8_SCHED;
;             PG8_LDA(At, 0, 1); PG8_STAGE(PG8_SB(0, 0), b2, voffB); PG8_STAGE(PG8_SB(0, 1), b2 + hstepB, voffB); PG8_STAGE(PG8_SA(0, 0), a2, voffA);
;             PG8_WAIT_V(8); PG8_WAIT_L(0); PG8_BAR; PG8_MMA(1, 0, At, B0); PG8_MMA(1, 1, At, B1); PG8_BAR; PG8_SCHED;
;             PG8_LDB(B0, 1, 0); PG8_LDB(B1, 1, 1); PG8_SCHED; PG8_LDA(At, 1, 0); PG8_STAGE(PG8_SA(0, 1), a2 + hstepA, voffA);
;             PG8_WAIT_V(8); PG8_WAIT_L(0); PG8_BAR; PG8_MMA(0, 0, At, B0); PG8_MMA(0, 1, At, B1); PG8_BAR; PG8_SCHED;
;             PG8_LDA(At, 1, 1); PG8_STAGE(PG8_SB(1, 0), b3, voffB); PG8_STAGE(PG8_SB(1, 1), b3 + hstepB, voffB); PG8_STAGE(PG8_SA(1, 0), a3, voffA);
;             PG8_WAIT_V(8); PG8_WAIT_L(0); PG8_BAR; PG8_MMA(1, 0, At, B0); PG8_MMA(1, 1, At, B1); PG8_BAR; PG8_SCHED;
.LBB0_1232:
	ds_read_b128 v[132:135], v236
	ds_read_b128 v[136:139], v236 offset:1024
	ds_read_b128 v[140:143], v236 offset:2048
	ds_read_b128 v[144:147], v236 offset:3072
	ds_read_b128 v[148:151], v237
	ds_read_b128 v[152:155], v237 offset:1024
	ds_read_b128 v[156:159], v237 offset:2048
	ds_read_b128 v[160:163], v237 offset:3072
	s_add_u32 s6, s40, 0x100
	s_addc_u32 s7, s41, 0
	s_cmpk_eq_i32 s18, 0xa8
	s_cselect_b32 s46, s24, s6
	s_cselect_b32 s47, s25, s7
	s_cselect_b32 s44, s26, s9
	s_cselect_b32 s45, s27, s39
	s_add_u32 s42, s46, 0x80
	s_addc_u32 s43, s47, 0
	ds_read_b128 v[164:167], v238
	ds_read_b128 v[168:171], v238 offset:1024
	ds_read_b128 v[172:175], v238 offset:2048
	ds_read_b128 v[176:179], v238 offset:3072
	ds_read_b128 v[180:183], v238 offset:4096
	ds_read_b128 v[184:187], v238 offset:5120
	ds_read_b128 v[188:191], v238 offset:6144
	ds_read_b128 v[192:195], v238 offset:7168
	s_add_u32 s36, s40, 0x2b0080
	s_addc_u32 s37, s41, 0
	s_mov_b32 s19, m0
	s_mov_b32 m0, s64
	s_nop 0
	global_load_lds_dwordx4 v234, s[36:37]
	s_mov_b32 m0, s65
	s_nop 0
	global_load_lds_dwordx4 v235, s[36:37]
	s_mov_b32 m0, s19
	s_waitcnt vmcnt(8)
	s_waitcnt lgkmcnt(0)
	s_barrier
	s_setprio 1
	s_waitcnt lgkmcnt(7)
	v_mfma_f32_16x16x32_bf16 v[124:127], v[132:135], v[164:167], v[124:127]
	v_mfma_f32_16x16x32_bf16 v[120:123], v[140:143], v[164:167], v[120:123]
	s_waitcnt lgkmcnt(5)
	v_mfma_f32_16x16x32_bf16 v[108:111], v[132:135], v[172:175], v[108:111]
	v_mfma_f32_16x16x32_bf16 v[104:107], v[140:143], v[172:175], v[104:107]
	s_waitcnt lgkmcnt(3)
	v_mfma_f32_16x16x32_bf16 v[92:95], v[132:135], v[180:183], v[92:95]
	v_mfma_f32_16x16x32_bf16 v[88:91], v[140:143], v[180:183], v[88:91]
	s_waitcnt lgkmcnt(1)
	v_mfma_f32_16x16x32_bf16 v[76:79], v[132:135], v[188:191], v[76:79]
	v_mfma_f32_16x16x32_bf16 v[72:75], v[140:143], v[188:191], v[72:75]
	v_mfma_f32_16x16x32_bf16 v[124:127], v[136:139], v[168:171], v[124:127]
	v_mfma_f32_16x16x32_bf16 v[120:123], v[144:147], v[168:171], v[120:123]
	v_mfma_f32_16x16x32_bf16 v[108:111], v[136:139], v[176:179], v[108:111]
	v_mfma_f32_16x16x32_bf16 v[104:107], v[144:147], v[176:179], v[104:107]
	v_mfma_f32_16x16x32_bf16 v[92:95], v[136:139], v[184:187], v[92:95]
	v_mfma_f32_16x16x32_bf16 v[88:91], v[144:147], v[184:187], v[88:91]
	s_waitcnt lgkmcnt(0)
	v_mfma_f32_16x16x32_bf16 v[76:79], v[136:139], v[192:195], v[76:79]
	v_mfma_f32_16x16x32_bf16 v[72:75], v[144:147], v[192:195], v[72:75]
	v_mfma_f32_16x16x32_bf16 v[116:119], v[148:151], v[164:167], v[116:119]
	v_mfma_f32_16x16x32_bf16 v[112:115], v[156:159], v[164:167], v[112:115]
	v_mfma_f32_16x16x32_bf16 v[100:103], v[148:151], v[172:175], v[100:103]
	v_mfma_f32_16x16x32_bf16 v[96:99], v[156:159], v[172:175], v[96:99]
	v_mfma_f32_16x16x32_bf16 v[84:87], v[148:151], v[180:183], v[84:87]
	v_mfma_f32_16x16x32_bf16 v[80:83], v[156:159], v[180:183], v[80:83]
	v_mfma_f32_16x16x32_bf16 v[68:71], v[148:151], v[188:191], v[68:71]
	v_mfma_f32_16x16x32_bf16 v[64:67], v[156:159], v[188:191], v[64:67]
	v_mfma_f32_16x16x32_bf16 v[116:119], v[152:155], v[168:171], v[116:119]
	v_mfma_f32_16x16x32_bf16 v[112:115], v[160:163], v[168:171], v[112:115]
	v_mfma_f32_16x16x32_bf16 v[100:103], v[152:155], v[176:179], v[100:103]
	v_mfma_f32_16x16x32_bf16 v[96:99], v[160:163], v[176:179], v[96:99]
	v_mfma_f32_16x16x32_bf16 v[84:87], v[152:155], v[184:187], v[84:87]
	v_mfma_f32_16x16x32_bf16 v[80:83], v[160:163], v[184:187], v[80:83]
	v_mfma_f32_16x16x32_bf16 v[68:71], v[152:155], v[192:195], v[68:71]
	v_mfma_f32_16x16x32_bf16 v[64:67], v[160:163], v[192:195], v[64:67]
	s_setprio 0
	s_barrier
	ds_read_b128 v[164:167], v238 offset:16384
	ds_read_b128 v[168:171], v238 offset:17408
	ds_read_b128 v[172:175], v238 offset:18432
	ds_read_b128 v[176:179], v238 offset:19456
	ds_read_b128 v[180:183], v238 offset:20480
	ds_read_b128 v[184:187], v238 offset:21504
	ds_read_b128 v[188:191], v238 offset:22528
	ds_read_b128 v[192:195], v238 offset:23552
	s_mov_b32 s19, m0
	s_mov_b32 m0, s48
	s_nop 0
	global_load_lds_dwordx4 v234, s[44:45]
	s_mov_b32 m0, s49
	s_nop 0
	global_load_lds_dwordx4 v235, s[44:45]
	s_mov_b32 m0, s19
	s_add_u32 s36, s44, 0x2b0000
	s_addc_u32 s37, s45, 0
	s_mov_b32 s19, m0
	s_mov_b32 m0, s50
	s_nop 0
	global_load_lds_dwordx4 v234, s[36:37]
	s_mov_b32 m0, s51
	s_nop 0
	global_load_lds_dwordx4 v235, s[36:37]
	s_mov_b32 m0, s19
	s_nop 0
	s_mov_b32 s19, m0
	s_mov_b32 m0, s23
	s_nop 0
	global_load_lds_dwordx4 v234, s[46:47]
	s_mov_b32 m0, s52
	s_nop 0
	global_load_lds_dwordx4 v235, s[46:47]
	s_mov_b32 m0, s19
	s_waitcnt vmcnt(8)
	s_waitcnt lgkmcnt(0)
	s_barrier
; #define PG8_LDA(dst, b, h) do { _Pragma("unroll") for (int m = 0; m < 4; ++m) _Pragma("unroll") for (int k = 0; k < 2; ++k) dst[m][k] = *(const LAS bf16x8*)(lds + PG8_SA(b, h) + aoff + m * 2048 + k * 1024); } while (0)
; #define PG8_LDB(dst, b, h) do { _Pragma("unroll") for (int n = 0; n < 2; ++n) _Pragma("unroll") for (int k = 0; k < 2; ++k) dst[n][k] = *(const LAS bf16x8*)(lds + PG8_SB(b, h) + boff + n * 2048 + k * 1024); } while (0)
; #define PG8_MMA(ai, bj, At, Bt) do { __builtin_amdgcn_s_setprio(1); _Pragma("unroll") for (int m = 0; m < 4; ++m) _Pragma("unroll") for (int n = 0; n < 2; ++n) _Pragma("unroll") for (int k = 0; k < 2; ++k) \
;         acc[ai][bj][m][n] = __builtin_amdgcn_mfma_f32_16x16x32_bf16(Bt[n][k], At[m][k], acc[ai][bj][m][n], 0, 0, 0); __builtin_amdgcn_s_setprio(0); } while (0)
; #define PG8_WAIT_V(n) asm volatile("s_waitcnt vmcnt(" #n ")" ::: "memory")
; #define PG8_WAIT_L(n) asm volatile("s_waitcnt lgkmcnt(" #n ")" ::: "memory")
; #define PG8_BAR __builtin_amdgcn_s_barrier()
; #define PG8_SCHED __builtin_amdgcn_sched_barrier(0)
; template <class Epi, class Addr, bool ALIGN_EPI = true, class Order = StaticOrder>
; __device__ __forceinline__ void gemm_phase(LAS unsigned char* lds, const Gemm g, const Order& S, const Epi& E, const int wid) {
;     ...
;             PG8_LDB(B0, 0, 0); PG8_LDB(B1, 0, 1); PG8_SCHED; PG8_LDA(At, 0, 0); PG8_STAGE(PG8_SA(1, 1), a1 + hstepA, voffA);
;             PG8_WAIT_V(8); PG8_WAIT_L(0); PG8_BAR; PG8_MMA(0, 0, At, B0); PG8_MMA(0, 1, At, B1); PG8_BAR; PG8_SCHED;
;             PG8_LDA(At, 0, 1); PG8_STAGE(PG8_SB(0, 0), b2, voffB); PG8_STAGE(PG8_SB(0, 1), b2 + hstepB, voffB); PG8_STAGE(PG8_SA(0, 0), a2, voffA);
;             PG8_WAIT_V(8); PG8_WAIT_L(0); PG8_BAR; PG8_MMA(1, 0, At, B0); PG8_MMA(1, 1, At, B1); PG8_BAR; PG8_SCHED;
;             PG8_LDB(B0, 1, 0); PG8_LDB(B1, 1, 1); PG8_SCHED; PG8_LDA(At, 1, 0); PG8_STAGE(PG8_SA(0, 1), a2 + hstepA, voffA);
;             PG8_WAIT_V(8); PG8_WAIT_L(0); PG8_BAR; PG8_MMA(0, 0, At, B0); PG8_MMA(0, 1, At, B1); PG8_BAR; PG8_SCHED;
;             PG8_LDA(At, 1, 1); PG8_STAGE(PG8_SB(1, 0), b3, voffB); PG8_STAGE(PG8_SB(1, 1), b3 + hstepB, voffB); PG8_STAGE(PG8_SA(1, 0), a3, voffA);
;             PG8_WAIT_V(8); PG8_WAIT_L(0); PG8_BAR; PG8_MMA(1, 0, At, B0); PG8_MMA(1, 1, At, B1); PG8_BAR; PG8_SCHED;
	s_setprio 1
	s_waitcnt lgkmcnt(7)
	v_mfma_f32_16x16x32_bf16 v[60:63], v[132:135], v[164:167], v[60:63]
	v_mfma_f32_16x16x32_bf16 v[56:59], v[140:143], v[164:167], v[56:59]
	s_waitcnt lgkmcnt(5)
	v_mfma_f32_16x16x32_bf16 v[44:47], v[132:135], v[172:175], v[44:47]
	v_mfma_f32_16x16x32_bf16 v[40:43], v[140:143], v[172:175], v[40:43]
	s_waitcnt lgkmcnt(3)
	v_mfma_f32_16x16x32_bf16 v[28:31], v[132:135], v[180:183], v[28:31]
	v_mfma_f32_16x16x32_bf16 v[24:27], v[140:143], v[180:183], v[24:27]
	s_waitcnt lgkmcnt(1)
	v_mfma_f32_16x16x32_bf16 v[12:15], v[132:135], v[188:191], v[12:15]
	v_mfma_f32_16x16x32_bf16 v[8:11], v[140:143], v[188:191], v[8:11]
	v_mfma_f32_16x16x32_bf16 v[60:63], v[136:139], v[168:171], v[60:63]
	v_mfma_f32_16x16x32_bf16 v[56:59], v[144:147], v[168:171], v[56:59]
	v_mfma_f32_16x16x32_bf16 v[44:47], v[136:139], v[176:179], v[44:47]
	v_mfma_f32_16x16x32_bf16 v[40:43], v[144:147], v[176:179], v[40:43]
	v_mfma_f32_16x16x32_bf16 v[28:31], v[136:139], v[184:187], v[28:31]
	v_mfma_f32_16x16x32_bf16 v[24:27], v[144:147], v[184:187], v[24:27]
	s_waitcnt lgkmcnt(0)
	v_mfma_f32_16x16x32_bf16 v[12:15], v[136:139], v[192:195], v[12:15]
	v_mfma_f32_16x16x32_bf16 v[8:11], v[144:147], v[192:195], v[8:11]
	v_mfma_f32_16x16x32_bf16 v[52:55], v[148:151], v[164:167], v[52:55]
	v_mfma_f32_16x16x32_bf16 v[48:51], v[156:159], v[164:167], v[48:51]
	v_mfma_f32_16x16x32_bf16 v[36:39], v[148:151], v[172:175], v[36:39]
	v_mfma_f32_16x16x32_bf16 v[32:35], v[156:159], v[172:175], v[32:35]
	v_mfma_f32_16x16x32_bf16 v[20:23], v[148:151], v[180:183], v[20:23]
	v_mfma_f32_16x16x32_bf16 v[16:19], v[156:159], v[180:183], v[16:19]
	v_mfma_f32_16x16x32_bf16 v[4:7], v[148:151], v[188:191], v[4:7]
	v_mfma_f32_16x16x32_bf16 v[0:3], v[156:159], v[188:191], v[0:3]
	v_mfma_f32_16x16x32_bf16 v[52:55], v[152:155], v[168:171], v[52:55]
	v_mfma_f32_16x16x32_bf16 v[48:51], v[160:163], v[168:171], v[48:51]
	v_mfma_f32_16x16x32_bf16 v[36:39], v[152:155], v[176:179], v[36:39]
	v_mfma_f32_16x16x32_bf16 v[32:35], v[160:163], v[176:179], v[32:35]
	v_mfma_f32_16x16x32_bf16 v[20:23], v[152:155], v[184:187], v[20:23]
	v_mfma_f32_16x16x32_bf16 v[16:19], v[160:163], v[184:187], v[16:19]
	v_mfma_f32_16x16x32_bf16 v[4:7], v[152:155], v[192:195], v[4:7]
	v_mfma_f32_16x16x32_bf16 v[0:3], v[160:163], v[192:195], v[0:3]
	s_setprio 0
	s_barrier
	ds_read_b128 v[132:135], v239
	ds_read_b128 v[136:139], v239 offset:1024
	ds_read_b128 v[140:143], v239 offset:2048
	ds_read_b128 v[144:147], v239 offset:3072
	ds_read_b128 v[148:151], v240
	ds_read_b128 v[152:155], v240 offset:1024
	ds_read_b128 v[156:159], v240 offset:2048
	ds_read_b128 v[160:163], v240 offset:3072
	ds_read_b128 v[164:167], v238 offset:32768
	ds_read_b128 v[168:171], v238 offset:33792
	ds_read_b128 v[172:175], v238 offset:34816
	ds_read_b128 v[176:179], v238 offset:35840
	ds_read_b128 v[180:183], v238 offset:36864
	ds_read_b128 v[184:187], v238 offset:37888
	ds_read_b128 v[188:191], v238 offset:38912
	ds_read_b128 v[192:195], v238 offset:39936
	s_add_u32 s36, s46, 0x2b0000
	s_addc_u32 s37, s47, 0
	s_mov_b32 s19, m0
	s_mov_b32 m0, s53
	s_nop 0
	global_load_lds_dwordx4 v234, s[36:37]
	s_mov_b32 m0, s54
	s_nop 0
	global_load_lds_dwordx4 v235, s[36:37]
	s_mov_b32 m0, s19
	s_waitcnt vmcnt(8)
	s_waitcnt lgkmcnt(0)
	s_barrier
	s_setprio 1
	s_waitcnt lgkmcnt(7)
	v_mfma_f32_16x16x32_bf16 v[124:127], v[132:135], v[164:167], v[124:127]
	v_mfma_f32_16x16x32_bf16 v[120:123], v[140:143], v[164:167], v[120:123]
	s_waitcnt lgkmcnt(5)
	v_mfma_f32_16x16x32_bf16 v[108:111], v[132:135], v[172:175], v[108:111]
	v_mfma_f32_16x16x32_bf16 v[104:107], v[140:143], v[172:175], v[104:107]
	s_waitcnt lgkmcnt(3)
	v_mfma_f32_16x16x32_bf16 v[92:95], v[132:135], v[180:183], v[92:95]
	v_mfma_f32_16x16x32_bf16 v[88:91], v[140:143], v[180:183], v[88:91]
	s_waitcnt lgkmcnt(1)
	v_mfma_f32_16x16x32_bf16 v[76:79], v[132:135], v[188:191], v[76:79]
	v_mfma_f32_16x16x32_bf16 v[72:75], v[140:143], v[188:191], v[72:75]
	v_mfma_f32_16x16x32_bf16 v[124:127], v[136:139], v[168:171], v[124:127]
	v_mfma_f32_16x16x32_bf16 v[120:123], v[144:147], v[168:171], v[120:123]
	v_mfma_f32_16x16x32_bf16 v[108:111], v[136:139], v[176:179], v[108:111]
	v_mfma_f32_16x16x32_bf16 v[104:107], v[144:147], v[176:179], v[104:107]
	v_mfma_f32_16x16x32_bf16 v[92:95], v[136:139], v[184:187], v[92:95]
	v_mfma_f32_16x16x32_bf16 v[88:91], v[144:147], v[184:187], v[88:91]
	s_waitcnt lgkmcnt(0)
	v_mfma_f32_16x16x32_bf16 v[76:79], v[136:139], v[192:195], v[76:79]
	v_mfma_f32_16x16x32_bf16 v[72:75], v[144:147], v[192:195], v[72:75]
	v_mfma_f32_16x16x32_bf16 v[116:119], v[148:151], v[164:167], v[116:119]
	v_mfma_f32_16x16x32_bf16 v[112:115], v[156:159], v[164:167], v[112:115]
	v_mfma_f32_16x16x32_bf16 v[100:103], v[148:151], v[172:175], v[100:103]
	v_mfma_f32_16x16x32_bf16 v[96:99], v[156:159], v[172:175], v[96:99]
	v_mfma_f32_16x16x32_bf16 v[84:87], v[148:151], v[180:183], v[84:87]
	v_mfma_f32_16x16x32_bf16 v[80:83], v[156:159], v[180:183], v[80:83]
	v_mfma_f32_16x16x32_bf16 v[68:71], v[148:151], v[188:191], v[68:71]
	v_mfma_f32_16x16x32_bf16 v[64:67], v[156:159], v[188:191], v[64:67]
	v_mfma_f32_16x16x32_bf16 v[116:119], v[152:155], v[168:171], v[116:119]
	v_mfma_f32_16x16x32_bf16 v[112:115], v[160:163], v[168:171], v[112:115]
	v_mfma_f32_16x16x32_bf16 v[100:103], v[152:155], v[176:179], v[100:103]
	v_mfma_f32_16x16x32_bf16 v[96:99], v[160:163], v[176:179], v[96:99]
	v_mfma_f32_16x16x32_bf16 v[84:87], v[152:155], v[184:187], v[84:87]
	v_mfma_f32_16x16x32_bf16 v[80:83], v[160:163], v[184:187], v[80:83]
	v_mfma_f32_16x16x32_bf16 v[68:71], v[152:155], v[192:195], v[68:71]
	v_mfma_f32_16x16x32_bf16 v[64:67], v[160:163], v[192:195], v[64:67]
	s_setprio 0
	s_barrier
; #define PG8_LDA(dst, b, h) do { _Pragma("unroll") for (int m = 0; m < 4; ++m) _Pragma("unroll") for (int k = 0; k < 2; ++k) dst[m][k] = *(const LAS bf16x8*)(lds + PG8_SA(b, h) + aoff + m * 2048 + k * 1024); } while (0)
; #define PG8_LDB(dst, b, h) do { _Pragma("unroll") for (int n = 0; n < 2; ++n) _Pragma("unroll") for (int k = 0; k < 2; ++k) dst[n][k] = *(const LAS bf16x8*)(lds + PG8_SB(b, h) + boff + n * 2048 + k * 1024); } while (0)
; #define PG8_MMA(ai, bj, At, Bt) do { __builtin_amdgcn_s_setprio(1); _Pragma("unroll") for (int m = 0; m < 4; ++m) _Pragma("unroll") for (int n = 0; n < 2; ++n) _Pragma("unroll") for (int k = 0; k < 2; ++k) \
;         acc[ai][bj][m][n] = __builtin_amdgcn_mfma_f32_16x16x32_bf16(Bt[n][k], At[m][k], acc[ai][bj][m][n], 0, 0, 0); __builtin_amdgcn_s_setprio(0); } while (0)
; #define PG8_WAIT_V(n) asm volatile("s_waitcnt vmcnt(" #n ")" ::: "memory")
; #define PG8_WAIT_L(n) asm volatile("s_waitcnt lgkmcnt(" #n ")" ::: "memory")
; #define PG8_BAR __builtin_amdgcn_s_barrier()
; #define PG8_SCHED __builtin_amdgcn_sched_barrier(0)
; template <class Epi, class Addr, bool ALIGN_EPI = true, class Order = StaticOrder>
; __device__ __forceinline__ void gemm_phase(LAS unsigned char* lds, const Gemm g, const Order& S, const Epi& E, const int wid) {
;     ...
;             PG8_LDB(B0, 1, 0); PG8_LDB(B1, 1, 1); PG8_SCHED; PG8_LDA(At, 1, 0); PG8_STAGE(PG8_SA(0, 1), a2 + hstepA, voffA);
;             PG8_WAIT_V(8); PG8_WAIT_L(0); PG8_BAR; PG8_MMA(0, 0, At, B0); PG8_MMA(0, 1, At, B1); PG8_BAR; PG8_SCHED;
;             PG8_LDA(At, 1, 1); PG8_STAGE(PG8_SB(1, 0), b3, voffB); PG8_STAGE(PG8_SB(1, 1), b3 + hstepB, voffB); PG8_STAGE(PG8_SA(1, 0), a3, voffA);
;             PG8_WAIT_V(8); PG8_WAIT_L(0); PG8_BAR; PG8_MMA(1, 0, At, B0); PG8_MMA(1, 1, At, B1); PG8_BAR; PG8_SCHED;
;         }
;         if constexpr (ALIGN_EPI) { if (wr == 0) PG8_BAR; }
	ds_read_b128 v[164:167], v238 offset:49152
	ds_read_b128 v[168:171], v238 offset:50176
	ds_read_b128 v[172:175], v238 offset:51200
	ds_read_b128 v[176:179], v238 offset:52224
	ds_read_b128 v[180:183], v238 offset:53248
	ds_read_b128 v[184:187], v238 offset:54272
	ds_read_b128 v[188:191], v238 offset:55296
	ds_read_b128 v[192:195], v238 offset:56320
	s_add_u32 s36, s44, 0x80
	s_addc_u32 s37, s45, 0
	s_mov_b32 s19, m0
	s_mov_b32 m0, s56
	s_nop 0
	global_load_lds_dwordx4 v234, s[36:37]
	s_mov_b32 m0, s57
	s_nop 0
	global_load_lds_dwordx4 v235, s[36:37]
	s_mov_b32 m0, s19
	s_add_u32 s36, s44, 0x2b0080
	s_addc_u32 s37, s45, 0
	s_mov_b32 s19, m0
	s_mov_b32 m0, s62
	s_nop 0
	global_load_lds_dwordx4 v234, s[36:37]
	s_mov_b32 m0, s63
	s_nop 0
	global_load_lds_dwordx4 v235, s[36:37]
	s_mov_b32 m0, s19
	s_nop 0
	s_mov_b32 s19, m0
	s_mov_b32 m0, s58
	s_nop 0
	global_load_lds_dwordx4 v234, s[42:43]
	s_mov_b32 m0, s59
	s_nop 0
	global_load_lds_dwordx4 v235, s[42:43]
	s_mov_b32 m0, s19
	s_waitcnt vmcnt(8)
	s_waitcnt lgkmcnt(0)
	s_barrier
	s_setprio 1
	s_waitcnt lgkmcnt(7)
	v_mfma_f32_16x16x32_bf16 v[60:63], v[132:135], v[164:167], v[60:63]
	v_mfma_f32_16x16x32_bf16 v[56:59], v[140:143], v[164:167], v[56:59]
	s_waitcnt lgkmcnt(5)
	v_mfma_f32_16x16x32_bf16 v[44:47], v[132:135], v[172:175], v[44:47]
	v_mfma_f32_16x16x32_bf16 v[40:43], v[140:143], v[172:175], v[40:43]
	s_waitcnt lgkmcnt(3)
	v_mfma_f32_16x16x32_bf16 v[28:31], v[132:135], v[180:183], v[28:31]
	v_mfma_f32_16x16x32_bf16 v[24:27], v[140:143], v[180:183], v[24:27]
	s_waitcnt lgkmcnt(1)
	v_mfma_f32_16x16x32_bf16 v[12:15], v[132:135], v[188:191], v[12:15]
	v_mfma_f32_16x16x32_bf16 v[8:11], v[140:143], v[188:191], v[8:11]
	v_mfma_f32_16x16x32_bf16 v[60:63], v[136:139], v[168:171], v[60:63]
	v_mfma_f32_16x16x32_bf16 v[56:59], v[144:147], v[168:171], v[56:59]
	v_mfma_f32_16x16x32_bf16 v[44:47], v[136:139], v[176:179], v[44:47]
	v_mfma_f32_16x16x32_bf16 v[40:43], v[144:147], v[176:179], v[40:43]
	v_mfma_f32_16x16x32_bf16 v[28:31], v[136:139], v[184:187], v[28:31]
	v_mfma_f32_16x16x32_bf16 v[24:27], v[144:147], v[184:187], v[24:27]
	s_waitcnt lgkmcnt(0)
	v_mfma_f32_16x16x32_bf16 v[12:15], v[136:139], v[192:195], v[12:15]
	v_mfma_f32_16x16x32_bf16 v[8:11], v[144:147], v[192:195], v[8:11]
	v_mfma_f32_16x16x32_bf16 v[52:55], v[148:151], v[164:167], v[52:55]
	v_mfma_f32_16x16x32_bf16 v[48:51], v[156:159], v[164:167], v[48:51]
	v_mfma_f32_16x16x32_bf16 v[36:39], v[148:151], v[172:175], v[36:39]
	v_mfma_f32_16x16x32_bf16 v[32:35], v[156:159], v[172:175], v[32:35]
	v_mfma_f32_16x16x32_bf16 v[20:23], v[148:151], v[180:183], v[20:23]
	v_mfma_f32_16x16x32_bf16 v[16:19], v[156:159], v[180:183], v[16:19]
	v_mfma_f32_16x16x32_bf16 v[4:7], v[148:151], v[188:191], v[4:7]
	v_mfma_f32_16x16x32_bf16 v[0:3], v[156:159], v[188:191], v[0:3]
	v_mfma_f32_16x16x32_bf16 v[52:55], v[152:155], v[168:171], v[52:55]
	v_mfma_f32_16x16x32_bf16 v[48:51], v[160:163], v[168:171], v[48:51]
	v_mfma_f32_16x16x32_bf16 v[36:39], v[152:155], v[176:179], v[36:39]
	v_mfma_f32_16x16x32_bf16 v[32:35], v[160:163], v[176:179], v[32:35]
	v_mfma_f32_16x16x32_bf16 v[20:23], v[152:155], v[184:187], v[20:23]
	v_mfma_f32_16x16x32_bf16 v[16:19], v[160:163], v[184:187], v[16:19]
	v_mfma_f32_16x16x32_bf16 v[4:7], v[152:155], v[192:195], v[4:7]
	v_mfma_f32_16x16x32_bf16 v[0:3], v[160:163], v[192:195], v[0:3]
	s_setprio 0
	s_barrier
	s_add_i32 s18, s18, 2
	s_add_u32 s9, s9, 0x100
	s_addc_u32 s39, s39, 0
	s_cmpk_gt_u32 s18, 0xa9
	s_mov_b64 s[40:41], s[6:7]
	s_cbranch_scc0 .LBB0_1232
	s_and_b64 vcc, exec, s[16:17]
	s_cbranch_vccz .LBB0_1235
	s_barrier
